# attention P.V blocks: row-sum init mov merged into the first add (v_add ps, a, b), one VALU less per step in all three 8-step loops
# baseline (speedup 1.0000x reference)
.LBB0_641:
	v_lshl_add_u64 v[178:179], v[174:175], 0, v[170:171]
	s_mov_b32 s24, 0x1894a000
	v_add_co_u32_e32 v52, vcc, s24, v178
	v_lshl_add_u64 v[56:57], v[172:173], 0, v[170:171]
	s_nop 0
	v_addc_co_u32_e32 v53, vcc, 0, v179, vcc
	s_mov_b32 s24, 0x19980000
	v_add_co_u32_e32 v176, vcc, s24, v56
	s_nop 0
	v_addc_co_u32_e32 v177, vcc, 0, v57, vcc
	global_load_dwordx4 v[52:55], v[52:53], off
	s_mul_i32 s26, s25, 0x2400
	global_load_dwordx4 v[56:59], v[176:177], off offset:512
	s_add_i32 s24, s23, -7
	s_add_i32 s27, s26, 0xffffdc00
	s_cmp_lg_u32 s25, 0
	s_cselect_b32 s27, s27, 0x9000
	v_add_u32_e32 v1, s27, v163
	ds_read_b128 v[60:63], v1 offset:36864
	ds_read_b128 v[114:117], v1 offset:36896
	ds_read_b128 v[118:121], v1 offset:41472
	ds_read_b128 v[134:137], v1 offset:41504
	ds_read_b128 v[146:149], v1 offset:36928
	ds_read_b128 v[150:153], v1 offset:36960
	ds_read_b128 v[196:199], v1 offset:41536
	ds_read_b128 v[200:203], v1 offset:41568
	s_setprio 3
	v_cvt_pk_bf16_f32 v204, v102, v103
	v_cvt_pk_bf16_f32 v205, v104, v105
	v_cvt_pk_bf16_f32 v206, v98, v99
	v_cvt_pk_bf16_f32 v207, v100, v101
	s_waitcnt lgkmcnt(7)
	s_nop 0
	v_mfma_f32_32x32x16_bf16 v[18:33], v[60:63], v[204:207], v[18:33]
	v_add_f32_e32 v1, v102, v103
	v_add_f32_e32 v1, v1, v104
	v_add_f32_e32 v1, v1, v105
	s_waitcnt lgkmcnt(5)
	v_mfma_f32_32x32x16_bf16 v[2:17], v[118:121], v[204:207], v[2:17]
	v_cvt_pk_bf16_f32 v60, v194, v187
	v_cvt_pk_bf16_f32 v61, v186, v185
	v_cvt_pk_bf16_f32 v62, v133, v132
	v_cvt_pk_bf16_f32 v63, v131, v130
	v_add_f32_e32 v1, v1, v98
	v_add_f32_e32 v1, v1, v99
	v_add_f32_e32 v1, v1, v100
	v_add_f32_e32 v1, v1, v101
	s_nop 0
	v_mfma_f32_32x32x16_bf16 v[18:33], v[114:117], v[60:63], v[18:33]
	v_add_f32_e32 v1, v1, v194
	v_add_f32_e32 v1, v1, v187
	v_add_f32_e32 v1, v1, v186
	v_add_f32_e32 v1, v1, v185
	s_waitcnt lgkmcnt(4)
	v_mfma_f32_32x32x16_bf16 v[2:17], v[134:137], v[60:63], v[2:17]
	v_cvt_pk_bf16_f32 v98, v129, v128
	v_cvt_pk_bf16_f32 v99, v127, v126
	v_cvt_pk_bf16_f32 v100, v125, v124
	v_cvt_pk_bf16_f32 v101, v123, v122
	v_add_f32_e32 v1, v1, v133
	v_add_f32_e32 v1, v1, v132
	v_add_f32_e32 v1, v1, v131
	v_add_f32_e32 v1, v1, v130
	s_waitcnt lgkmcnt(3)
	v_mfma_f32_32x32x16_bf16 v[18:33], v[146:149], v[98:101], v[18:33]
	v_add_f32_e32 v1, v1, v129
	v_add_f32_e32 v1, v1, v128
	v_add_f32_e32 v1, v1, v127
	v_add_f32_e32 v1, v1, v126
	s_waitcnt lgkmcnt(1)
	v_mfma_f32_32x32x16_bf16 v[2:17], v[196:199], v[98:101], v[2:17]
	v_cvt_pk_bf16_f32 v60, v109, v108
	v_cvt_pk_bf16_f32 v61, v107, v106
	v_cvt_pk_bf16_f32 v62, v113, v112
	v_cvt_pk_bf16_f32 v63, v111, v110
	v_add_f32_e32 v1, v1, v125
	v_add_f32_e32 v1, v1, v124
	v_add_f32_e32 v1, v1, v123
	v_add_f32_e32 v1, v1, v122
	s_nop 0
	v_mfma_f32_32x32x16_bf16 v[18:33], v[150:153], v[60:63], v[18:33]
	v_add_f32_e32 v1, v1, v109
	v_add_f32_e32 v1, v1, v108
	v_add_f32_e32 v1, v1, v107
	v_add_f32_e32 v1, v1, v106
	s_waitcnt lgkmcnt(0)
	v_mfma_f32_32x32x16_bf16 v[2:17], v[200:203], v[60:63], v[2:17]
	v_add_f32_e32 v1, v1, v113
	v_add_f32_e32 v1, v1, v112
	v_add_f32_e32 v1, v1, v111
	v_add_f32_e32 v1, v1, v110
	s_setprio 2
	s_waitcnt lgkmcnt(0)
	s_barrier
	ds_read_b128 v[240:243], v165 offset:18432
	ds_read_b128 v[244:247], v165 offset:23040
	ds_read_b128 v[130:133], v165 offset:18464
	ds_read_b128 v[146:149], v165 offset:23072
	s_waitcnt lgkmcnt(2)
	v_mfma_f32_32x32x16_bf16 v[114:129], v[240:243], v[158:161], v[34:49]
	v_exp_f32_e32 v185, v82
	v_exp_f32_e32 v186, v83
	v_exp_f32_e32 v187, v84
	v_exp_f32_e32 v194, v85
	v_exp_f32_e32 v195, v86
	v_exp_f32_e32 v196, v87
	v_exp_f32_e32 v197, v88
	v_exp_f32_e32 v198, v89
	s_waitcnt lgkmcnt(1)
	v_mfma_f32_32x32x16_bf16 v[98:113], v[244:247], v[158:161], v[34:49]
	v_exp_f32_e32 v199, v90
	v_exp_f32_e32 v200, v91
	v_exp_f32_e32 v201, v92
	v_exp_f32_e32 v202, v93
	v_exp_f32_e32 v134, v94
	v_exp_f32_e32 v135, v95
	v_exp_f32_e32 v136, v96
	v_exp_f32_e32 v137, v97
	v_mfma_f32_32x32x16_bf16 v[114:129], v[130:133], v[154:157], v[114:129]
	v_exp_f32_e32 v96, v66
	v_exp_f32_e32 v97, v67
	v_exp_f32_e32 v203, v68
	v_exp_f32_e32 v204, v69
	v_exp_f32_e32 v130, v70
	v_exp_f32_e32 v131, v71
	v_exp_f32_e32 v132, v72
	v_exp_f32_e32 v133, v73
	s_waitcnt lgkmcnt(0)
	v_mfma_f32_32x32x16_bf16 v[98:113], v[146:149], v[154:157], v[98:113]
	v_exp_f32_e32 v205, v74
	v_exp_f32_e32 v206, v75
	v_exp_f32_e32 v207, v76
	v_exp_f32_e32 v208, v77
	v_exp_f32_e32 v209, v78
	v_exp_f32_e32 v210, v79
	v_exp_f32_e32 v211, v80
	v_exp_f32_e32 v212, v81
	s_cmp_gt_i32 s25, 2
	s_cselect_b32 s27, -3, 2
	s_add_i32 s27, s27, s25
	v_add_u32_e32 v88, s26, v163
	s_add_i32 s26, s23, -6
	s_mulk_i32 s27, 0x2400
	s_min_u32 s26, s26, s13
	v_add_u32_e32 v51, s27, v182
	s_min_u32 s24, s24, s13
	s_lshl_b32 s92, s26, 13
	s_waitcnt vmcnt(3)
	ds_write_b128 v182, v[138:141]
	s_waitcnt vmcnt(2)
	ds_write_b128 v51, v[142:145] offset:36864
	v_add_f32_e32 v1, v50, v1
	s_add_u32 vcc_lo, s100, s92
	s_addc_u32 vcc_hi, s101, 0
	global_load_dwordx4 v[146:149], v248, vcc
	s_lshl_b32 s92, s24, 7
	s_add_u32 vcc_lo, s98, s92
	s_addc_u32 vcc_hi, s99, 0
	global_load_dwordx4 v[150:153], v249, vcc
	ds_read_b128 v[240:243], v165 offset:27648
	ds_read_b128 v[244:247], v165 offset:32256
	ds_read_b128 v[60:63], v88 offset:41472
	ds_read_b128 v[64:67], v88 offset:36864
	ds_read_b128 v[68:71], v88 offset:36896
	ds_read_b128 v[72:75], v88 offset:41504
	ds_read_b128 v[76:79], v88 offset:36928
	ds_read_b128 v[80:83], v88 offset:41536
	ds_read_b128 v[84:87], v88 offset:36960
	ds_read_b128 v[88:91], v88 offset:41568
	s_add_i32 s27, s25, 1
	s_setprio 1
	v_cvt_pk_bf16_f32 v92, v185, v186
	v_cvt_pk_bf16_f32 v93, v187, v194
	v_cvt_pk_bf16_f32 v94, v195, v196
	v_cvt_pk_bf16_f32 v95, v197, v198
	s_waitcnt lgkmcnt(6)
	s_nop 0
	v_mfma_f32_32x32x16_bf16 v[18:33], v[64:67], v[92:95], v[18:33]
	v_add_f32_e32 v213, v185, v186
	v_add_f32_e32 v213, v213, v187
	v_add_f32_e32 v213, v213, v194
	s_nop 0
	v_mfma_f32_32x32x16_bf16 v[2:17], v[60:63], v[92:95], v[2:17]
	v_cvt_pk_bf16_f32 v64, v199, v200
	v_cvt_pk_bf16_f32 v65, v201, v202
	v_cvt_pk_bf16_f32 v66, v134, v135
	v_cvt_pk_bf16_f32 v67, v136, v137
	v_add_f32_e32 v213, v213, v195
	v_add_f32_e32 v213, v213, v196
	v_add_f32_e32 v213, v213, v197
	v_add_f32_e32 v213, v213, v198
	s_waitcnt lgkmcnt(5)
	v_mfma_f32_32x32x16_bf16 v[18:33], v[68:71], v[64:67], v[18:33]
	v_add_f32_e32 v213, v213, v199
	v_add_f32_e32 v213, v213, v200
	v_add_f32_e32 v213, v213, v201
	v_add_f32_e32 v213, v213, v202
	s_waitcnt lgkmcnt(4)
	v_mfma_f32_32x32x16_bf16 v[2:17], v[72:75], v[64:67], v[2:17]
	v_cvt_pk_bf16_f32 v60, v96, v97
	v_cvt_pk_bf16_f32 v61, v203, v204
	v_cvt_pk_bf16_f32 v62, v130, v131
	v_cvt_pk_bf16_f32 v63, v132, v133
	v_add_f32_e32 v213, v213, v134
	v_add_f32_e32 v213, v213, v135
	v_add_f32_e32 v213, v213, v136
	v_add_f32_e32 v213, v213, v137
	s_waitcnt lgkmcnt(3)
	v_mfma_f32_32x32x16_bf16 v[18:33], v[76:79], v[60:63], v[18:33]
	v_add_f32_e32 v213, v213, v96
	v_add_f32_e32 v213, v213, v97
	v_add_f32_e32 v213, v213, v203
	v_add_f32_e32 v213, v213, v204
	s_waitcnt lgkmcnt(2)
	v_mfma_f32_32x32x16_bf16 v[2:17], v[80:83], v[60:63], v[2:17]
	v_cvt_pk_bf16_f32 v64, v205, v206
	v_cvt_pk_bf16_f32 v65, v207, v208
	v_cvt_pk_bf16_f32 v66, v209, v210
	v_cvt_pk_bf16_f32 v67, v211, v212
	v_add_f32_e32 v213, v213, v130
	v_add_f32_e32 v213, v213, v131
	v_add_f32_e32 v213, v213, v132
	v_add_f32_e32 v213, v213, v133
	s_waitcnt lgkmcnt(1)
	v_mfma_f32_32x32x16_bf16 v[18:33], v[84:87], v[64:67], v[18:33]
	v_add_f32_e32 v213, v213, v205
	v_add_f32_e32 v213, v213, v206
	v_add_f32_e32 v213, v213, v207
	v_add_f32_e32 v213, v213, v208
	s_waitcnt lgkmcnt(0)
	v_mfma_f32_32x32x16_bf16 v[2:17], v[88:91], v[64:67], v[2:17]
	v_add_f32_e32 v213, v213, v209
	v_add_f32_e32 v213, v213, v210
	v_add_f32_e32 v213, v213, v211
	v_add_f32_e32 v213, v213, v212
	s_setprio 0
	ds_read_b128 v[64:67], v165 offset:27680
	ds_read_b128 v[72:75], v165 offset:32288
	s_cmp_lg_u32 s25, 4
	s_cselect_b32 s24, s27, 0
	s_waitcnt lgkmcnt(2)
	v_mfma_f32_32x32x16_bf16 v[130:145], v[240:243], v[158:161], v[34:49]
	v_exp_f32_e32 v185, v114
	v_exp_f32_e32 v186, v115
	v_exp_f32_e32 v187, v116
	v_exp_f32_e32 v194, v117
	v_exp_f32_e32 v195, v118
	v_exp_f32_e32 v196, v119
	v_exp_f32_e32 v197, v120
	v_exp_f32_e32 v198, v121
	s_waitcnt lgkmcnt(1)
	v_mfma_f32_32x32x16_bf16 v[82:97], v[244:247], v[158:161], v[34:49]
	v_exp_f32_e32 v199, v122
	v_exp_f32_e32 v200, v123
	v_exp_f32_e32 v201, v124
	v_exp_f32_e32 v202, v125
	v_exp_f32_e32 v122, v126
	v_exp_f32_e32 v123, v127
	v_exp_f32_e32 v124, v128
	v_exp_f32_e32 v125, v129
	v_mfma_f32_32x32x16_bf16 v[130:145], v[64:67], v[154:157], v[130:145]
	v_exp_f32_e32 v126, v98
	v_exp_f32_e32 v127, v99
	v_exp_f32_e32 v128, v100
	v_exp_f32_e32 v129, v101
	v_exp_f32_e32 v203, v102
	v_exp_f32_e32 v204, v103
	v_exp_f32_e32 v205, v104
	v_exp_f32_e32 v206, v105
	s_waitcnt lgkmcnt(0)
	v_mfma_f32_32x32x16_bf16 v[82:97], v[72:75], v[154:157], v[82:97]
	v_exp_f32_e32 v102, v106
	v_exp_f32_e32 v103, v107
	v_exp_f32_e32 v104, v108
	v_exp_f32_e32 v105, v109
	v_exp_f32_e32 v106, v110
	v_exp_f32_e32 v107, v111
	v_exp_f32_e32 v108, v112
	v_exp_f32_e32 v109, v113
	s_cmp_gt_i32 s24, 2
	s_cselect_b32 s25, -3, 2
	s_add_i32 s25, s25, s24
	s_mulk_i32 s25, 0x2400
	v_add_u32_e32 v50, s25, v182
	s_add_i32 s25, s24, 1
	s_cmp_lg_u32 s24, 4
	s_cselect_b32 s24, s25, 0
	s_add_i32 s25, s23, -5
	s_min_u32 s25, s25, s13
	s_lshl_b32 s92, s25, 13
	s_waitcnt vmcnt(3)
	ds_write_b128 v182, v[52:55] offset:9216
	s_waitcnt vmcnt(2)
	ds_write_b128 v50, v[56:59] offset:36864
	s_add_u32 vcc_lo, s100, s92
	s_addc_u32 vcc_hi, s101, 0
	global_load_dwordx4 v[118:121], v248, vcc
	s_lshl_b32 s92, s26, 7
	s_add_u32 vcc_lo, s98, s92
	s_addc_u32 vcc_hi, s99, 0
	global_load_dwordx4 v[114:117], v249, vcc
	s_mul_i32 s26, s24, 0x2400
	s_add_i32 s27, s26, 0xffffdc00
	s_cmp_lg_u32 s24, 0
	s_cselect_b32 s27, s27, 0x9000
	v_add_u32_e32 v78, s27, v163
	ds_read_b128 v[50:53], v78 offset:36864
	ds_read_b128 v[54:57], v78 offset:36896
	ds_read_b128 v[58:61], v78 offset:41472
	ds_read_b128 v[62:65], v78 offset:41504
	ds_read_b128 v[66:69], v78 offset:36928
	ds_read_b128 v[70:73], v78 offset:36960
	ds_read_b128 v[74:77], v78 offset:41536
	ds_read_b128 v[78:81], v78 offset:41568
	s_setprio 3
	v_cvt_pk_bf16_f32 v98, v185, v186
	v_cvt_pk_bf16_f32 v99, v187, v194
	v_cvt_pk_bf16_f32 v100, v195, v196
	v_cvt_pk_bf16_f32 v101, v197, v198
	s_waitcnt lgkmcnt(7)
	s_nop 0
	v_mfma_f32_32x32x16_bf16 v[18:33], v[50:53], v[98:101], v[18:33]
	v_add_f32_e32 v110, v185, v186
	v_add_f32_e32 v110, v110, v187
	v_add_f32_e32 v110, v110, v194
	s_waitcnt lgkmcnt(5)
	v_mfma_f32_32x32x16_bf16 v[2:17], v[58:61], v[98:101], v[2:17]
	v_cvt_pk_bf16_f32 v50, v199, v200
	v_cvt_pk_bf16_f32 v51, v201, v202
	v_cvt_pk_bf16_f32 v52, v122, v123
	v_cvt_pk_bf16_f32 v53, v124, v125
	v_add_f32_e32 v110, v110, v195
	v_add_f32_e32 v110, v110, v196
	v_add_f32_e32 v110, v110, v197
	v_add_f32_e32 v110, v110, v198
	s_nop 0
	v_mfma_f32_32x32x16_bf16 v[18:33], v[54:57], v[50:53], v[18:33]
	v_add_f32_e32 v110, v110, v199
	v_add_f32_e32 v110, v110, v200
	v_add_f32_e32 v110, v110, v201
	v_add_f32_e32 v110, v110, v202
	s_waitcnt lgkmcnt(4)
	v_mfma_f32_32x32x16_bf16 v[2:17], v[62:65], v[50:53], v[2:17]
	v_cvt_pk_bf16_f32 v54, v126, v127
	v_cvt_pk_bf16_f32 v55, v128, v129
	v_cvt_pk_bf16_f32 v56, v203, v204
	v_cvt_pk_bf16_f32 v57, v205, v206
	v_add_f32_e32 v110, v110, v122
	v_add_f32_e32 v110, v110, v123
	v_add_f32_e32 v110, v110, v124
	v_add_f32_e32 v110, v110, v125
	s_waitcnt lgkmcnt(3)
	v_mfma_f32_32x32x16_bf16 v[18:33], v[66:69], v[54:57], v[18:33]
	v_add_f32_e32 v110, v110, v126
	v_add_f32_e32 v110, v110, v127
	v_add_f32_e32 v110, v110, v128
	v_add_f32_e32 v110, v110, v129
	s_waitcnt lgkmcnt(1)
	v_mfma_f32_32x32x16_bf16 v[2:17], v[74:77], v[54:57], v[2:17]
	v_cvt_pk_bf16_f32 v50, v102, v103
	v_cvt_pk_bf16_f32 v51, v104, v105
	v_cvt_pk_bf16_f32 v52, v106, v107
	v_cvt_pk_bf16_f32 v53, v108, v109
	v_add_f32_e32 v110, v110, v203
	v_add_f32_e32 v110, v110, v204
	v_add_f32_e32 v110, v110, v205
	v_add_f32_e32 v110, v110, v206
	s_nop 0
	v_mfma_f32_32x32x16_bf16 v[18:33], v[70:73], v[50:53], v[18:33]
	v_add_f32_e32 v110, v110, v102
	v_add_f32_e32 v110, v110, v103
	v_add_f32_e32 v110, v110, v104
	v_add_f32_e32 v110, v110, v105
	s_waitcnt lgkmcnt(0)
	v_mfma_f32_32x32x16_bf16 v[2:17], v[78:81], v[50:53], v[2:17]
	v_add_f32_e32 v110, v110, v106
	v_add_f32_e32 v110, v110, v107
	v_add_f32_e32 v110, v110, v108
	v_add_f32_e32 v110, v110, v109
	s_setprio 2
	s_waitcnt lgkmcnt(0)
	s_barrier
	ds_read_b128 v[240:243], v165
	ds_read_b128 v[244:247], v165 offset:4608
	ds_read_b128 v[102:105], v165 offset:32
	ds_read_b128 v[106:109], v165 offset:4640
	v_add_f32_e32 v1, v1, v213
	s_waitcnt lgkmcnt(2)
	v_mfma_f32_32x32x16_bf16 v[66:81], v[240:243], v[158:161], v[34:49]
	v_exp_f32_e32 v185, v130
	v_exp_f32_e32 v186, v131
	v_exp_f32_e32 v187, v132
	v_exp_f32_e32 v194, v133
	v_exp_f32_e32 v195, v134
	v_exp_f32_e32 v196, v135
	v_exp_f32_e32 v197, v136
	v_exp_f32_e32 v198, v137
	v_mfma_f32_32x32x16_bf16 v[50:65], v[244:247], v[158:161], v[34:49]
	v_exp_f32_e32 v134, v138
	v_exp_f32_e32 v135, v139
	v_exp_f32_e32 v136, v140
	v_exp_f32_e32 v137, v141
	v_exp_f32_e32 v138, v142
	v_exp_f32_e32 v139, v143
	v_exp_f32_e32 v140, v144
	v_exp_f32_e32 v141, v145
	s_waitcnt lgkmcnt(1)
	v_mfma_f32_32x32x16_bf16 v[66:81], v[102:105], v[154:157], v[66:81]
	v_exp_f32_e32 v142, v82
	v_exp_f32_e32 v143, v83
	v_exp_f32_e32 v144, v84
	v_exp_f32_e32 v145, v85
	v_exp_f32_e32 v199, v86
	v_exp_f32_e32 v200, v87
	v_exp_f32_e32 v201, v88
	v_exp_f32_e32 v202, v89
	s_waitcnt lgkmcnt(0)
	v_mfma_f32_32x32x16_bf16 v[50:65], v[106:109], v[154:157], v[50:65]
	v_exp_f32_e32 v203, v90
	v_exp_f32_e32 v204, v91
	v_exp_f32_e32 v205, v92
	v_exp_f32_e32 v206, v93
	v_exp_f32_e32 v207, v94
	v_exp_f32_e32 v208, v95
	v_exp_f32_e32 v209, v96
	v_exp_f32_e32 v210, v97
	s_cmp_gt_i32 s24, 2
	s_cselect_b32 s27, -3, 2
	s_add_i32 s27, s27, s24
	s_mulk_i32 s27, 0x2400
	v_add_u32_e32 v82, s27, v182
	s_mov_b32 s27, 0x18950000
	s_waitcnt vmcnt(3)
	ds_write_b128 v182, v[146:149] offset:18432
	s_waitcnt vmcnt(2)
	ds_write_b128 v82, v[150:153] offset:36864
	v_add_co_u32_e32 v82, vcc, s27, v178
	s_lshl_b32 s92, s25, 7
	s_nop 0
	v_addc_co_u32_e32 v83, vcc, 0, v179, vcc
	global_load_dwordx4 v[126:129], v[82:83], off
	s_add_u32 vcc_lo, s98, s92
	s_addc_u32 vcc_hi, s99, 0
	global_load_dwordx4 v[122:125], v249, vcc
	v_add_u32_e32 v111, s26, v163
	v_add_f32_e32 v1, v1, v110
	ds_read_b128 v[240:243], v165 offset:9216
	ds_read_b128 v[244:247], v165 offset:13824
	ds_read_b128 v[82:85], v111 offset:41472
	ds_read_b128 v[86:89], v111 offset:36864
	ds_read_b128 v[90:93], v111 offset:36896
	ds_read_b128 v[94:97], v111 offset:41504
	ds_read_b128 v[98:101], v111 offset:36928
	ds_read_b128 v[102:105], v111 offset:41536
	ds_read_b128 v[106:109], v111 offset:36960
	ds_read_b128 v[110:113], v111 offset:41568
	s_add_i32 s26, s24, 1
	s_setprio 1
	v_cvt_pk_bf16_f32 v130, v185, v186
	v_cvt_pk_bf16_f32 v131, v187, v194
	v_cvt_pk_bf16_f32 v132, v195, v196
	v_cvt_pk_bf16_f32 v133, v197, v198
	s_waitcnt lgkmcnt(6)
	s_nop 0
	v_mfma_f32_32x32x16_bf16 v[18:33], v[86:89], v[130:133], v[18:33]
	v_add_f32_e32 v146, v185, v186
	v_add_f32_e32 v146, v146, v187
	v_add_f32_e32 v146, v146, v194
	s_nop 0
	v_mfma_f32_32x32x16_bf16 v[2:17], v[82:85], v[130:133], v[2:17]
	v_cvt_pk_bf16_f32 v86, v134, v135
	v_cvt_pk_bf16_f32 v87, v136, v137
	v_cvt_pk_bf16_f32 v88, v138, v139
	v_cvt_pk_bf16_f32 v89, v140, v141
	v_add_f32_e32 v146, v146, v195
	v_add_f32_e32 v146, v146, v196
	v_add_f32_e32 v146, v146, v197
	v_add_f32_e32 v146, v146, v198
	s_waitcnt lgkmcnt(5)
	v_mfma_f32_32x32x16_bf16 v[18:33], v[90:93], v[86:89], v[18:33]
	v_add_f32_e32 v146, v146, v134
	v_add_f32_e32 v146, v146, v135
	v_add_f32_e32 v146, v146, v136
	v_add_f32_e32 v146, v146, v137
	s_waitcnt lgkmcnt(4)
	v_mfma_f32_32x32x16_bf16 v[2:17], v[94:97], v[86:89], v[2:17]
	v_cvt_pk_bf16_f32 v82, v142, v143
	v_cvt_pk_bf16_f32 v83, v144, v145
	v_cvt_pk_bf16_f32 v84, v199, v200
	v_cvt_pk_bf16_f32 v85, v201, v202
	v_add_f32_e32 v146, v146, v138
	v_add_f32_e32 v146, v146, v139
	v_add_f32_e32 v146, v146, v140
	v_add_f32_e32 v146, v146, v141
	s_waitcnt lgkmcnt(3)
	v_mfma_f32_32x32x16_bf16 v[18:33], v[98:101], v[82:85], v[18:33]
	v_add_f32_e32 v146, v146, v142
	v_add_f32_e32 v146, v146, v143
	v_add_f32_e32 v146, v146, v144
	v_add_f32_e32 v146, v146, v145
	s_waitcnt lgkmcnt(2)
	v_mfma_f32_32x32x16_bf16 v[2:17], v[102:105], v[82:85], v[2:17]
	v_cvt_pk_bf16_f32 v86, v203, v204
	v_cvt_pk_bf16_f32 v87, v205, v206
	v_cvt_pk_bf16_f32 v88, v207, v208
	v_cvt_pk_bf16_f32 v89, v209, v210
	v_add_f32_e32 v146, v146, v199
	v_add_f32_e32 v146, v146, v200
	v_add_f32_e32 v146, v146, v201
	v_add_f32_e32 v146, v146, v202
	s_waitcnt lgkmcnt(1)
	v_mfma_f32_32x32x16_bf16 v[18:33], v[106:109], v[86:89], v[18:33]
	v_add_f32_e32 v146, v146, v203
	v_add_f32_e32 v146, v146, v204
	v_add_f32_e32 v146, v146, v205
	v_add_f32_e32 v146, v146, v206
	s_waitcnt lgkmcnt(0)
	v_mfma_f32_32x32x16_bf16 v[2:17], v[110:113], v[86:89], v[2:17]
	v_add_f32_e32 v146, v146, v207
	v_add_f32_e32 v146, v146, v208
	v_add_f32_e32 v146, v146, v209
	v_add_f32_e32 v146, v146, v210
	s_setprio 0
	ds_read_b128 v[130:133], v165 offset:9248
	ds_read_b128 v[138:141], v165 offset:13856
	s_cmp_lg_u32 s24, 4
	s_cselect_b32 s24, s26, 0
	s_waitcnt lgkmcnt(2)
	v_mfma_f32_32x32x16_bf16 v[98:113], v[240:243], v[158:161], v[34:49]
	v_exp_f32_e32 v142, v66
	v_exp_f32_e32 v143, v67
	v_exp_f32_e32 v144, v68
	v_exp_f32_e32 v145, v69
	v_exp_f32_e32 v147, v70
	v_exp_f32_e32 v148, v71
	v_exp_f32_e32 v149, v72
	v_exp_f32_e32 v150, v73
	s_waitcnt lgkmcnt(1)
	v_mfma_f32_32x32x16_bf16 v[82:97], v[244:247], v[158:161], v[34:49]
	v_exp_f32_e32 v151, v74
	v_exp_f32_e32 v152, v75
	v_exp_f32_e32 v153, v76
	v_exp_f32_e32 v178, v77
	v_exp_f32_e32 v134, v78
	v_exp_f32_e32 v135, v79
	v_exp_f32_e32 v136, v80
	v_exp_f32_e32 v137, v81
	v_mfma_f32_32x32x16_bf16 v[98:113], v[130:133], v[154:157], v[98:113]
	v_exp_f32_e32 v179, v50
	v_exp_f32_e32 v185, v51
	v_exp_f32_e32 v186, v52
	v_exp_f32_e32 v187, v53
	v_exp_f32_e32 v194, v54
	v_exp_f32_e32 v195, v55
	v_exp_f32_e32 v196, v56
	v_exp_f32_e32 v197, v57
	s_waitcnt lgkmcnt(0)
	v_mfma_f32_32x32x16_bf16 v[82:97], v[138:141], v[154:157], v[82:97]
	v_exp_f32_e32 v198, v58
	v_exp_f32_e32 v199, v59
	v_exp_f32_e32 v200, v60
	v_exp_f32_e32 v201, v61
	v_exp_f32_e32 v138, v62
	v_exp_f32_e32 v139, v63
	v_exp_f32_e32 v140, v64
	v_exp_f32_e32 v141, v65
	s_cmp_gt_i32 s24, 2
	s_cselect_b32 s25, -3, 2
	s_add_i32 s25, s25, s24
	s_mulk_i32 s25, 0x2400
	v_add_u32_e32 v50, s25, v182
	s_add_i32 s25, s24, 1
	s_cmp_lg_u32 s24, 4
	s_cselect_b32 s25, s25, 0
	s_add_i32 s24, s23, -3
	s_min_u32 s26, s24, s13
	s_lshl_b32 s92, s26, 13
	s_waitcnt vmcnt(3)
	ds_write_b128 v182, v[118:121] offset:27648
	s_waitcnt vmcnt(2)
	ds_write_b128 v50, v[114:117] offset:36864
	s_add_u32 vcc_lo, s100, s92
	s_addc_u32 vcc_hi, s101, 0
	global_load_dwordx4 v[118:121], v248, vcc
	global_load_dwordx4 v[114:117], v[176:177], off offset:1024
	s_mul_i32 s27, s25, 0x2400
	s_add_i32 s28, s27, 0xffffdc00
	s_cmp_lg_u32 s25, 0
	s_cselect_b32 s28, s28, 0x9000
	v_add_u32_e32 v78, s28, v163
	ds_read_b128 v[50:53], v78 offset:36864
	ds_read_b128 v[54:57], v78 offset:36896
	ds_read_b128 v[58:61], v78 offset:41472
	ds_read_b128 v[62:65], v78 offset:41504
	ds_read_b128 v[66:69], v78 offset:36928
	ds_read_b128 v[70:73], v78 offset:36960
	ds_read_b128 v[74:77], v78 offset:41536
	ds_read_b128 v[78:81], v78 offset:41568
	s_setprio 3
	v_cvt_pk_bf16_f32 v130, v142, v143
	v_cvt_pk_bf16_f32 v131, v144, v145
	v_cvt_pk_bf16_f32 v132, v147, v148
	v_cvt_pk_bf16_f32 v133, v149, v150
	s_waitcnt lgkmcnt(7)
	s_nop 0
	v_mfma_f32_32x32x16_bf16 v[18:33], v[50:53], v[130:133], v[18:33]
	v_add_f32_e32 v176, v142, v143
	v_add_f32_e32 v176, v176, v144
	v_add_f32_e32 v176, v176, v145
	s_waitcnt lgkmcnt(5)
	v_mfma_f32_32x32x16_bf16 v[2:17], v[58:61], v[130:133], v[2:17]
	v_cvt_pk_bf16_f32 v50, v151, v152
	v_cvt_pk_bf16_f32 v51, v153, v178
	v_cvt_pk_bf16_f32 v52, v134, v135
	v_cvt_pk_bf16_f32 v53, v136, v137
	v_add_f32_e32 v176, v176, v147
	v_add_f32_e32 v176, v176, v148
	v_add_f32_e32 v176, v176, v149
	v_add_f32_e32 v176, v176, v150
	s_nop 0
	v_mfma_f32_32x32x16_bf16 v[18:33], v[54:57], v[50:53], v[18:33]
	v_add_f32_e32 v176, v176, v151
	v_add_f32_e32 v176, v176, v152
	v_add_f32_e32 v176, v176, v153
	v_add_f32_e32 v176, v176, v178
	s_waitcnt lgkmcnt(4)
	v_mfma_f32_32x32x16_bf16 v[2:17], v[62:65], v[50:53], v[2:17]
	v_cvt_pk_bf16_f32 v54, v179, v185
	v_cvt_pk_bf16_f32 v55, v186, v187
	v_cvt_pk_bf16_f32 v56, v194, v195
	v_cvt_pk_bf16_f32 v57, v196, v197
	v_add_f32_e32 v176, v176, v134
	v_add_f32_e32 v176, v176, v135
	v_add_f32_e32 v176, v176, v136
	v_add_f32_e32 v176, v176, v137
	s_waitcnt lgkmcnt(3)
	v_mfma_f32_32x32x16_bf16 v[18:33], v[66:69], v[54:57], v[18:33]
	v_add_f32_e32 v176, v176, v179
	v_add_f32_e32 v176, v176, v185
	v_add_f32_e32 v176, v176, v186
	v_add_f32_e32 v176, v176, v187
	s_waitcnt lgkmcnt(1)
	v_mfma_f32_32x32x16_bf16 v[2:17], v[74:77], v[54:57], v[2:17]
	v_cvt_pk_bf16_f32 v50, v198, v199
	v_cvt_pk_bf16_f32 v51, v200, v201
	v_cvt_pk_bf16_f32 v52, v138, v139
	v_cvt_pk_bf16_f32 v53, v140, v141
	v_add_f32_e32 v176, v176, v194
	v_add_f32_e32 v176, v176, v195
	v_add_f32_e32 v176, v176, v196
	v_add_f32_e32 v176, v176, v197
	s_nop 0
	v_mfma_f32_32x32x16_bf16 v[18:33], v[70:73], v[50:53], v[18:33]
	v_add_f32_e32 v176, v176, v198
	v_add_f32_e32 v176, v176, v199
	v_add_f32_e32 v176, v176, v200
	v_add_f32_e32 v176, v176, v201
	s_waitcnt lgkmcnt(0)
	v_mfma_f32_32x32x16_bf16 v[2:17], v[78:81], v[50:53], v[2:17]
	v_add_f32_e32 v176, v176, v138
	v_add_f32_e32 v176, v176, v139
	v_add_f32_e32 v176, v176, v140
	v_add_f32_e32 v176, v176, v141
	s_setprio 2
	s_waitcnt lgkmcnt(0)
	s_barrier
	ds_read_b128 v[240:243], v165 offset:18432
	ds_read_b128 v[244:247], v165 offset:23040
	ds_read_b128 v[134:137], v165 offset:18464
	ds_read_b128 v[138:141], v165 offset:23072
	v_add_f32_e32 v1, v1, v146
	s_waitcnt lgkmcnt(2)
	v_mfma_f32_32x32x16_bf16 v[66:81], v[240:243], v[158:161], v[34:49]
	v_exp_f32_e32 v142, v98
	v_exp_f32_e32 v143, v99
	v_exp_f32_e32 v144, v100
	v_exp_f32_e32 v145, v101
	v_exp_f32_e32 v146, v102
	v_exp_f32_e32 v147, v103
	v_exp_f32_e32 v148, v104
	v_exp_f32_e32 v149, v105
	v_mfma_f32_32x32x16_bf16 v[50:65], v[244:247], v[158:161], v[34:49]
	v_exp_f32_e32 v150, v106
	v_exp_f32_e32 v151, v107
	v_exp_f32_e32 v152, v108
	v_exp_f32_e32 v153, v109
	v_exp_f32_e32 v177, v110
	v_exp_f32_e32 v178, v111
	v_exp_f32_e32 v179, v112
	v_exp_f32_e32 v185, v113
	s_waitcnt lgkmcnt(1)
	v_mfma_f32_32x32x16_bf16 v[66:81], v[134:137], v[154:157], v[66:81]
	v_exp_f32_e32 v186, v82
	v_exp_f32_e32 v187, v83
	v_exp_f32_e32 v194, v84
	v_exp_f32_e32 v195, v85
	v_exp_f32_e32 v134, v86
	v_exp_f32_e32 v135, v87
	v_exp_f32_e32 v136, v88
	v_exp_f32_e32 v137, v89
	s_waitcnt lgkmcnt(0)
	v_mfma_f32_32x32x16_bf16 v[50:65], v[138:141], v[154:157], v[50:65]
	v_exp_f32_e32 v196, v90
	v_exp_f32_e32 v197, v91
	v_exp_f32_e32 v198, v92
	v_exp_f32_e32 v199, v93
	v_exp_f32_e32 v138, v94
	v_exp_f32_e32 v139, v95
	v_exp_f32_e32 v140, v96
	v_exp_f32_e32 v141, v97
	s_cmp_gt_i32 s25, 2
	s_cselect_b32 s28, -3, 2
	s_waitcnt vmcnt(3)
	ds_write_b128 v182, v[126:129]
	s_add_i32 s28, s28, s25
	v_add_u32_e32 v126, s27, v163
	s_add_i32 s27, s23, -2
	s_mulk_i32 s28, 0x2400
	s_min_u32 s27, s27, s13
	v_add_u32_e32 v82, s28, v182
	s_lshl_b32 s92, s27, 13
	s_waitcnt vmcnt(2)
	ds_write_b128 v82, v[122:125] offset:36864
	s_add_u32 vcc_lo, s100, s92
	s_addc_u32 vcc_hi, s101, 0
	global_load_dwordx4 v[98:101], v248, vcc
	s_lshl_b32 s92, s26, 7
	s_add_u32 vcc_lo, s98, s92
	s_addc_u32 vcc_hi, s99, 0
	global_load_dwordx4 v[102:105], v249, vcc
	ds_read_b128 v[240:243], v165 offset:27648
	ds_read_b128 v[244:247], v165 offset:32256
	ds_read_b128 v[82:85], v126 offset:41472
	ds_read_b128 v[86:89], v126 offset:36864
	ds_read_b128 v[90:93], v126 offset:36896
	ds_read_b128 v[94:97], v126 offset:41504
	ds_read_b128 v[106:109], v126 offset:36928
	ds_read_b128 v[110:113], v126 offset:41536
	ds_read_b128 v[122:125], v126 offset:36960
	ds_read_b128 v[126:129], v126 offset:41568
	v_add_f32_e32 v1, v1, v176
	s_add_i32 s28, s25, 1
	s_setprio 1
	v_cvt_pk_bf16_f32 v130, v142, v143
	v_cvt_pk_bf16_f32 v131, v144, v145
	v_cvt_pk_bf16_f32 v132, v146, v147
	v_cvt_pk_bf16_f32 v133, v148, v149
	s_waitcnt lgkmcnt(6)
	s_nop 0
	v_mfma_f32_32x32x16_bf16 v[18:33], v[86:89], v[130:133], v[18:33]
	v_add_f32_e32 v176, v142, v143
	v_add_f32_e32 v176, v176, v144
	v_add_f32_e32 v176, v176, v145
	s_nop 0
	v_mfma_f32_32x32x16_bf16 v[2:17], v[82:85], v[130:133], v[2:17]
	v_cvt_pk_bf16_f32 v86, v150, v151
	v_cvt_pk_bf16_f32 v87, v152, v153
	v_cvt_pk_bf16_f32 v88, v177, v178
	v_cvt_pk_bf16_f32 v89, v179, v185
	v_add_f32_e32 v176, v176, v146
	v_add_f32_e32 v176, v176, v147
	v_add_f32_e32 v176, v176, v148
	v_add_f32_e32 v176, v176, v149
	s_waitcnt lgkmcnt(5)
	v_mfma_f32_32x32x16_bf16 v[18:33], v[90:93], v[86:89], v[18:33]
	v_add_f32_e32 v176, v176, v150
	v_add_f32_e32 v176, v176, v151
	v_add_f32_e32 v176, v176, v152
	v_add_f32_e32 v176, v176, v153
	s_waitcnt lgkmcnt(4)
	v_mfma_f32_32x32x16_bf16 v[2:17], v[94:97], v[86:89], v[2:17]
	v_cvt_pk_bf16_f32 v82, v186, v187
	v_cvt_pk_bf16_f32 v83, v194, v195
	v_cvt_pk_bf16_f32 v84, v134, v135
	v_cvt_pk_bf16_f32 v85, v136, v137
	v_add_f32_e32 v176, v176, v177
	v_add_f32_e32 v176, v176, v178
	v_add_f32_e32 v176, v176, v179
	v_add_f32_e32 v176, v176, v185
	s_waitcnt lgkmcnt(3)
	v_mfma_f32_32x32x16_bf16 v[18:33], v[106:109], v[82:85], v[18:33]
	v_add_f32_e32 v176, v176, v186
	v_add_f32_e32 v176, v176, v187
	v_add_f32_e32 v176, v176, v194
	v_add_f32_e32 v176, v176, v195
	s_waitcnt lgkmcnt(2)
	v_mfma_f32_32x32x16_bf16 v[2:17], v[110:113], v[82:85], v[2:17]
	v_cvt_pk_bf16_f32 v86, v196, v197
	v_cvt_pk_bf16_f32 v87, v198, v199
	v_cvt_pk_bf16_f32 v88, v138, v139
	v_cvt_pk_bf16_f32 v89, v140, v141
	v_add_f32_e32 v176, v176, v134
	v_add_f32_e32 v176, v176, v135
	v_add_f32_e32 v176, v176, v136
	v_add_f32_e32 v176, v176, v137
	s_waitcnt lgkmcnt(1)
	v_mfma_f32_32x32x16_bf16 v[18:33], v[122:125], v[86:89], v[18:33]
	v_add_f32_e32 v176, v176, v196
	v_add_f32_e32 v176, v176, v197
	v_add_f32_e32 v176, v176, v198
	v_add_f32_e32 v176, v176, v199
	s_waitcnt lgkmcnt(0)
	v_mfma_f32_32x32x16_bf16 v[2:17], v[126:129], v[86:89], v[2:17]
	v_add_f32_e32 v176, v176, v138
	v_add_f32_e32 v176, v176, v139
	v_add_f32_e32 v176, v176, v140
	v_add_f32_e32 v176, v176, v141
	s_setprio 0
	ds_read_b128 v[106:109], v165 offset:27680
	ds_read_b128 v[122:125], v165 offset:32288
	s_cmp_lg_u32 s25, 4
	s_cselect_b32 s25, s28, 0
	s_waitcnt lgkmcnt(2)
	v_mfma_f32_32x32x16_bf16 v[138:153], v[240:243], v[158:161], v[34:49]
	v_exp_f32_e32 v126, v66
	v_exp_f32_e32 v127, v67
	v_exp_f32_e32 v128, v68
	v_exp_f32_e32 v129, v69
	v_exp_f32_e32 v130, v70
	v_exp_f32_e32 v131, v71
	v_exp_f32_e32 v132, v72
	v_exp_f32_e32 v133, v73
	s_waitcnt lgkmcnt(1)
	v_mfma_f32_32x32x16_bf16 v[82:97], v[244:247], v[158:161], v[34:49]
	v_exp_f32_e32 v134, v74
	v_exp_f32_e32 v135, v75
	v_exp_f32_e32 v136, v76
	v_exp_f32_e32 v137, v77
	v_exp_f32_e32 v177, v78
	v_exp_f32_e32 v178, v79
	v_exp_f32_e32 v179, v80
	v_exp_f32_e32 v185, v81
	v_mfma_f32_32x32x16_bf16 v[138:153], v[106:109], v[154:157], v[138:153]
	v_exp_f32_e32 v80, v50
	v_exp_f32_e32 v81, v51
	v_exp_f32_e32 v186, v52
	v_exp_f32_e32 v187, v53
	v_exp_f32_e32 v194, v54
	v_exp_f32_e32 v195, v55
	v_exp_f32_e32 v196, v56
	v_exp_f32_e32 v197, v57
	s_waitcnt lgkmcnt(0)
	v_mfma_f32_32x32x16_bf16 v[82:97], v[122:125], v[154:157], v[82:97]
	v_exp_f32_e32 v198, v58
	v_exp_f32_e32 v199, v59
	v_exp_f32_e32 v200, v60
	v_exp_f32_e32 v201, v61
	v_exp_f32_e32 v122, v62
	v_exp_f32_e32 v123, v63
	v_exp_f32_e32 v124, v64
	v_exp_f32_e32 v125, v65
	s_cmp_gt_i32 s25, 2
	s_cselect_b32 s26, -3, 2
	s_add_i32 s26, s26, s25
	s_mulk_i32 s26, 0x2400
	v_add_u32_e32 v50, s26, v182
	s_add_i32 s26, s25, 1
	s_cmp_lg_u32 s25, 4
	s_cselect_b32 s25, s26, 0
	s_add_i32 s26, s23, -1
	s_min_u32 s26, s26, s13
	s_lshl_b32 s92, s26, 13
	s_waitcnt vmcnt(3)
	ds_write_b128 v182, v[118:121] offset:9216
	s_waitcnt vmcnt(2)
	ds_write_b128 v50, v[114:117] offset:36864
	s_add_u32 vcc_lo, s100, s92
	s_addc_u32 vcc_hi, s101, 0
	global_load_dwordx4 v[56:59], v248, vcc
	s_lshl_b32 s92, s27, 7
	s_add_u32 vcc_lo, s98, s92
	s_addc_u32 vcc_hi, s99, 0
	global_load_dwordx4 v[52:55], v249, vcc
	s_nop 0
	s_mul_i32 s27, s25, 0x2400
	s_add_i32 s28, s27, 0xffffdc00
	s_cmp_lg_u32 s25, 0
	s_cselect_b32 s28, s28, 0x9000
	v_add_u32_e32 v50, s28, v163
	ds_read_b128 v[60:63], v50 offset:36864
	ds_read_b128 v[64:67], v50 offset:36896
	ds_read_b128 v[68:71], v50 offset:41472
	ds_read_b128 v[72:75], v50 offset:41504
	ds_read_b128 v[76:79], v50 offset:36928
	ds_read_b128 v[106:109], v50 offset:36960
	ds_read_b128 v[110:113], v50 offset:41536
	ds_read_b128 v[114:117], v50 offset:41568
	s_setprio 3
	v_cvt_pk_bf16_f32 v118, v126, v127
	v_cvt_pk_bf16_f32 v119, v128, v129
	v_cvt_pk_bf16_f32 v120, v130, v131
	v_cvt_pk_bf16_f32 v121, v132, v133
	s_waitcnt lgkmcnt(7)
	s_nop 0
	v_mfma_f32_32x32x16_bf16 v[18:33], v[60:63], v[118:121], v[18:33]
	v_add_f32_e32 v50, v126, v127
	v_add_f32_e32 v50, v50, v128
	v_add_f32_e32 v50, v50, v129
	s_waitcnt lgkmcnt(5)
	v_mfma_f32_32x32x16_bf16 v[2:17], v[68:71], v[118:121], v[2:17]
	v_cvt_pk_bf16_f32 v60, v134, v135
	v_cvt_pk_bf16_f32 v61, v136, v137
	v_cvt_pk_bf16_f32 v62, v177, v178
	v_cvt_pk_bf16_f32 v63, v179, v185
	v_add_f32_e32 v50, v50, v130
	v_add_f32_e32 v50, v50, v131
	v_add_f32_e32 v50, v50, v132
	v_add_f32_e32 v50, v50, v133
	s_nop 0
	v_mfma_f32_32x32x16_bf16 v[18:33], v[64:67], v[60:63], v[18:33]
	v_add_f32_e32 v50, v50, v134
	v_add_f32_e32 v50, v50, v135
	v_add_f32_e32 v50, v50, v136
	v_add_f32_e32 v50, v50, v137
	s_waitcnt lgkmcnt(4)
	v_mfma_f32_32x32x16_bf16 v[2:17], v[72:75], v[60:63], v[2:17]
	v_cvt_pk_bf16_f32 v64, v80, v81
	v_cvt_pk_bf16_f32 v65, v186, v187
	v_cvt_pk_bf16_f32 v66, v194, v195
	v_cvt_pk_bf16_f32 v67, v196, v197
	v_add_f32_e32 v50, v50, v177
	v_add_f32_e32 v50, v50, v178
	v_add_f32_e32 v50, v50, v179
	v_add_f32_e32 v50, v50, v185
	s_waitcnt lgkmcnt(3)
	v_mfma_f32_32x32x16_bf16 v[18:33], v[76:79], v[64:67], v[18:33]
	v_add_f32_e32 v50, v50, v80
	v_add_f32_e32 v50, v50, v81
	v_add_f32_e32 v50, v50, v186
	v_add_f32_e32 v50, v50, v187
	s_waitcnt lgkmcnt(1)
	v_mfma_f32_32x32x16_bf16 v[2:17], v[110:113], v[64:67], v[2:17]
	v_cvt_pk_bf16_f32 v60, v198, v199
	v_cvt_pk_bf16_f32 v61, v200, v201
	v_cvt_pk_bf16_f32 v62, v122, v123
	v_cvt_pk_bf16_f32 v63, v124, v125
	v_add_f32_e32 v50, v50, v194
	v_add_f32_e32 v50, v50, v195
	v_add_f32_e32 v50, v50, v196
	v_add_f32_e32 v50, v50, v197
	s_nop 0
	v_mfma_f32_32x32x16_bf16 v[18:33], v[106:109], v[60:63], v[18:33]
	v_add_f32_e32 v50, v50, v198
	v_add_f32_e32 v50, v50, v199
	v_add_f32_e32 v50, v50, v200
	v_add_f32_e32 v50, v50, v201
	s_waitcnt lgkmcnt(0)
	v_mfma_f32_32x32x16_bf16 v[2:17], v[114:117], v[60:63], v[2:17]
	v_add_f32_e32 v50, v50, v122
	v_add_f32_e32 v50, v50, v123
	v_add_f32_e32 v50, v50, v124
	v_add_f32_e32 v50, v50, v125
	s_setprio 2
	s_waitcnt lgkmcnt(0)
	s_barrier
	ds_read_b128 v[240:243], v165
	ds_read_b128 v[244:247], v165 offset:4608
	ds_read_b128 v[68:71], v165 offset:32
	ds_read_b128 v[72:75], v165 offset:4640
	v_add_f32_e32 v1, v1, v176
	s_waitcnt lgkmcnt(2)
	v_mfma_f32_32x32x16_bf16 v[122:137], v[240:243], v[158:161], v[34:49]
	v_exp_f32_e32 v176, v138
	v_exp_f32_e32 v177, v139
	v_exp_f32_e32 v178, v140
	v_exp_f32_e32 v179, v141
	v_exp_f32_e32 v185, v142
	v_exp_f32_e32 v186, v143
	v_exp_f32_e32 v187, v144
	v_exp_f32_e32 v194, v145
	v_mfma_f32_32x32x16_bf16 v[106:121], v[244:247], v[158:161], v[34:49]
	v_exp_f32_e32 v195, v146
	v_exp_f32_e32 v196, v147
	v_exp_f32_e32 v197, v148
	v_exp_f32_e32 v198, v149
	v_exp_f32_e32 v146, v150
	v_exp_f32_e32 v147, v151
	v_exp_f32_e32 v148, v152
	v_exp_f32_e32 v149, v153
	s_waitcnt lgkmcnt(1)
	v_mfma_f32_32x32x16_bf16 v[122:137], v[68:71], v[154:157], v[122:137]
	v_exp_f32_e32 v150, v82
	v_exp_f32_e32 v151, v83
	v_exp_f32_e32 v152, v84
	v_exp_f32_e32 v153, v85
	v_exp_f32_e32 v199, v86
	v_exp_f32_e32 v200, v87
	v_exp_f32_e32 v201, v88
	v_exp_f32_e32 v202, v89
	s_waitcnt lgkmcnt(0)
	v_mfma_f32_32x32x16_bf16 v[106:121], v[72:75], v[154:157], v[106:121]
	v_exp_f32_e32 v203, v90
	v_exp_f32_e32 v204, v91
	v_exp_f32_e32 v205, v92
	v_exp_f32_e32 v206, v93
	v_exp_f32_e32 v207, v94
	v_exp_f32_e32 v208, v95
	v_exp_f32_e32 v209, v96
	v_exp_f32_e32 v210, v97
	s_cmp_gt_i32 s25, 2
	s_cselect_b32 s28, -3, 2
	s_add_i32 s28, s28, s25
	s_mulk_i32 s28, 0x2400
	v_add_u32_e32 v88, s27, v163
	s_min_u32 s27, s23, s13
	v_add_u32_e32 v51, s28, v182
	s_lshl_b32 s92, s27, 13
	s_waitcnt vmcnt(3)
	ds_write_b128 v182, v[98:101] offset:18432
	s_waitcnt vmcnt(2)
	ds_write_b128 v51, v[102:105] offset:36864
	v_add_f32_e32 v1, v1, v50
	s_add_u32 vcc_lo, s100, s92
	s_addc_u32 vcc_hi, s101, 0
	global_load_dwordx4 v[138:141], v248, vcc
	s_lshl_b32 s92, s26, 7
	s_add_u32 vcc_lo, s98, s92
	s_addc_u32 vcc_hi, s99, 0
	global_load_dwordx4 v[142:145], v249, vcc
	ds_read_b128 v[240:243], v165 offset:9216
	ds_read_b128 v[244:247], v165 offset:13824
	ds_read_b128 v[60:63], v88 offset:41472
	ds_read_b128 v[64:67], v88 offset:36864
	ds_read_b128 v[68:71], v88 offset:36896
	ds_read_b128 v[72:75], v88 offset:41504
	ds_read_b128 v[76:79], v88 offset:36928
	ds_read_b128 v[80:83], v88 offset:41536
	ds_read_b128 v[84:87], v88 offset:36960
	ds_read_b128 v[88:91], v88 offset:41568
	s_setprio 1
	v_mov_b32_e32 v51, v122
	v_cvt_pk_bf16_f32 v92, v176, v177
	v_cvt_pk_bf16_f32 v93, v178, v179
	v_cvt_pk_bf16_f32 v94, v185, v186
	v_cvt_pk_bf16_f32 v95, v187, v194
	s_waitcnt lgkmcnt(6)
	s_nop 0
	v_mfma_f32_32x32x16_bf16 v[18:33], v[64:67], v[92:95], v[18:33]
	v_max3_f32 v51, v51, v123, v124
	v_max3_f32 v51, v51, v125, v126
	v_add_f32_e32 v50, v176, v177
	v_add_f32_e32 v50, v50, v178
	v_add_f32_e32 v50, v50, v179
	s_nop 0
	v_mfma_f32_32x32x16_bf16 v[2:17], v[60:63], v[92:95], v[2:17]
	v_cvt_pk_bf16_f32 v64, v195, v196
	v_cvt_pk_bf16_f32 v65, v197, v198
	v_cvt_pk_bf16_f32 v66, v146, v147
	v_cvt_pk_bf16_f32 v67, v148, v149
	v_max3_f32 v51, v51, v127, v128
	v_max3_f32 v51, v51, v129, v130
	v_add_f32_e32 v50, v50, v185
	v_add_f32_e32 v50, v50, v186
	v_add_f32_e32 v50, v50, v187
	v_add_f32_e32 v50, v50, v194
	s_waitcnt lgkmcnt(5)
	v_mfma_f32_32x32x16_bf16 v[18:33], v[68:71], v[64:67], v[18:33]
	v_max3_f32 v51, v51, v131, v132
	v_max3_f32 v51, v51, v133, v134
	v_add_f32_e32 v50, v50, v195
	v_add_f32_e32 v50, v50, v196
	v_add_f32_e32 v50, v50, v197
	v_add_f32_e32 v50, v50, v198
	s_waitcnt lgkmcnt(4)
	v_mfma_f32_32x32x16_bf16 v[2:17], v[72:75], v[64:67], v[2:17]
	v_cvt_pk_bf16_f32 v60, v150, v151
	v_cvt_pk_bf16_f32 v61, v152, v153
	v_cvt_pk_bf16_f32 v62, v199, v200
	v_cvt_pk_bf16_f32 v63, v201, v202
	v_max3_f32 v51, v51, v135, v136
	v_max3_f32 v51, v51, v137, v106
	v_add_f32_e32 v50, v50, v146
	v_add_f32_e32 v50, v50, v147
	v_add_f32_e32 v50, v50, v148
	v_add_f32_e32 v50, v50, v149
	s_waitcnt lgkmcnt(3)
	v_mfma_f32_32x32x16_bf16 v[18:33], v[76:79], v[60:63], v[18:33]
	v_max3_f32 v51, v51, v107, v108
	v_max3_f32 v51, v51, v109, v110
	v_add_f32_e32 v50, v50, v150
	v_add_f32_e32 v50, v50, v151
	v_add_f32_e32 v50, v50, v152
	v_add_f32_e32 v50, v50, v153
	s_waitcnt lgkmcnt(2)
	v_mfma_f32_32x32x16_bf16 v[2:17], v[80:83], v[60:63], v[2:17]
	v_cvt_pk_bf16_f32 v64, v203, v204
	v_cvt_pk_bf16_f32 v65, v205, v206
	v_cvt_pk_bf16_f32 v66, v207, v208
	v_cvt_pk_bf16_f32 v67, v209, v210
	v_max3_f32 v51, v51, v111, v112
	v_max3_f32 v51, v51, v113, v114
	v_add_f32_e32 v50, v50, v199
	v_add_f32_e32 v50, v50, v200
	v_add_f32_e32 v50, v50, v201
	v_add_f32_e32 v50, v50, v202
	s_waitcnt lgkmcnt(1)
	v_mfma_f32_32x32x16_bf16 v[18:33], v[84:87], v[64:67], v[18:33]
	v_max3_f32 v51, v51, v115, v116
	v_max3_f32 v51, v51, v117, v118
	v_add_f32_e32 v50, v50, v203
	v_add_f32_e32 v50, v50, v204
	v_add_f32_e32 v50, v50, v205
	v_add_f32_e32 v50, v50, v206
	s_waitcnt lgkmcnt(0)
	v_mfma_f32_32x32x16_bf16 v[2:17], v[88:91], v[64:67], v[2:17]
	v_max3_f32 v51, v51, v119, v120
	v_max3_f32 v51, v51, v121, v121
	v_add_f32_e32 v50, v50, v207
	v_add_f32_e32 v50, v50, v208
	v_add_f32_e32 v50, v50, v209
	v_add_f32_e32 v50, v50, v210
	s_setprio 0
	ds_read_b128 v[146:149], v165 offset:9248
	ds_read_b128 v[60:63], v165 offset:13856
	v_add_f32_e32 v50, v1, v50
	v_mov_b32_e32 v1, v51
	s_nop 1
	v_permlane32_swap_b32_e32 v51, v1
	v_max_f32_e32 v1, v1, v1
	v_max_f32_e32 v51, v51, v51
	v_max_f32_e32 v1, v51, v1
	v_cmp_lt_f32_e32 vcc, s52, v1
	s_cbranch_vccz .LBB0_643
	v_max_f32_e32 v1, v1, v1
	v_max_f32_e32 v68, 0, v1
	v_add_f32_e32 v183, v183, v68
	v_xor_b32_e32 v34, 0x80000000, v183
	v_pk_add_f32 v[122:123], v[122:123], v[68:69] op_sel_hi:[1,0] neg_lo:[0,1] neg_hi:[0,1]
	v_pk_add_f32 v[106:107], v[106:107], v[68:69] op_sel_hi:[1,0] neg_lo:[0,1] neg_hi:[0,1]
	v_pk_add_f32 v[124:125], v[124:125], v[68:69] op_sel_hi:[1,0] neg_lo:[0,1] neg_hi:[0,1]
	v_pk_add_f32 v[108:109], v[108:109], v[68:69] op_sel_hi:[1,0] neg_lo:[0,1] neg_hi:[0,1]
	v_pk_add_f32 v[126:127], v[126:127], v[68:69] op_sel_hi:[1,0] neg_lo:[0,1] neg_hi:[0,1]
	v_pk_add_f32 v[110:111], v[110:111], v[68:69] op_sel_hi:[1,0] neg_lo:[0,1] neg_hi:[0,1]
	v_pk_add_f32 v[128:129], v[128:129], v[68:69] op_sel_hi:[1,0] neg_lo:[0,1] neg_hi:[0,1]
	v_pk_add_f32 v[112:113], v[112:113], v[68:69] op_sel_hi:[1,0] neg_lo:[0,1] neg_hi:[0,1]
	v_pk_add_f32 v[130:131], v[130:131], v[68:69] op_sel_hi:[1,0] neg_lo:[0,1] neg_hi:[0,1]
	v_pk_add_f32 v[114:115], v[114:115], v[68:69] op_sel_hi:[1,0] neg_lo:[0,1] neg_hi:[0,1]
	v_pk_add_f32 v[132:133], v[132:133], v[68:69] op_sel_hi:[1,0] neg_lo:[0,1] neg_hi:[0,1]
	v_pk_add_f32 v[116:117], v[116:117], v[68:69] op_sel_hi:[1,0] neg_lo:[0,1] neg_hi:[0,1]
	v_pk_add_f32 v[134:135], v[134:135], v[68:69] op_sel_hi:[1,0] neg_lo:[0,1] neg_hi:[0,1]
	v_pk_add_f32 v[118:119], v[118:119], v[68:69] op_sel_hi:[1,0] neg_lo:[0,1] neg_hi:[0,1]
	v_pk_add_f32 v[136:137], v[136:137], v[68:69] op_sel_hi:[1,0] neg_lo:[0,1] neg_hi:[0,1]
	v_pk_add_f32 v[120:121], v[120:121], v[68:69] op_sel_hi:[1,0] neg_lo:[0,1] neg_hi:[0,1]
	v_exp_f32_e64 v68, -v68
	v_mov_b32_e32 v35, v34
	v_mov_b32_e32 v36, v34
	v_mov_b32_e32 v37, v34
	v_mov_b32_e32 v38, v34
	v_mov_b32_e32 v39, v34
	v_mov_b32_e32 v40, v34
	v_mov_b32_e32 v41, v34
	v_mov_b32_e32 v42, v34
	v_mov_b32_e32 v43, v34
	v_mov_b32_e32 v44, v34
	v_mov_b32_e32 v45, v34
	v_mov_b32_e32 v46, v34
	v_mov_b32_e32 v47, v34
	v_mov_b32_e32 v48, v34
	v_mov_b32_e32 v49, v34
	s_nop 11
	v_pk_mul_f32 v[32:33], v[32:33], v[68:69] op_sel_hi:[1,0]
	v_pk_mul_f32 v[30:31], v[30:31], v[68:69] op_sel_hi:[1,0]
	v_pk_mul_f32 v[28:29], v[28:29], v[68:69] op_sel_hi:[1,0]
	v_pk_mul_f32 v[26:27], v[26:27], v[68:69] op_sel_hi:[1,0]
	v_pk_mul_f32 v[24:25], v[24:25], v[68:69] op_sel_hi:[1,0]
	v_pk_mul_f32 v[22:23], v[22:23], v[68:69] op_sel_hi:[1,0]
	v_pk_mul_f32 v[20:21], v[20:21], v[68:69] op_sel_hi:[1,0]
	v_pk_mul_f32 v[18:19], v[18:19], v[68:69] op_sel_hi:[1,0]
	v_pk_mul_f32 v[16:17], v[16:17], v[68:69] op_sel_hi:[1,0]
	v_pk_mul_f32 v[14:15], v[14:15], v[68:69] op_sel_hi:[1,0]
	v_pk_mul_f32 v[12:13], v[12:13], v[68:69] op_sel_hi:[1,0]
	v_pk_mul_f32 v[10:11], v[10:11], v[68:69] op_sel_hi:[1,0]
	v_pk_mul_f32 v[8:9], v[8:9], v[68:69] op_sel_hi:[1,0]
	v_pk_mul_f32 v[6:7], v[6:7], v[68:69] op_sel_hi:[1,0]
	v_pk_mul_f32 v[4:5], v[4:5], v[68:69] op_sel_hi:[1,0]
	v_pk_mul_f32 v[2:3], v[2:3], v[68:69] op_sel_hi:[1,0]
	v_mul_f32_e32 v50, v50, v68

.LBB0_661:
	v_lshl_add_u64 v[164:165], v[204:205], 0, v[200:201]
	s_mov_b32 s26, 0x1da8a000
	v_add_co_u32_e32 v2, vcc, s26, v164
	v_lshl_add_u64 v[6:7], v[202:203], 0, v[200:201]
	s_nop 0
	v_addc_co_u32_e32 v3, vcc, 0, v165, vcc
	s_mov_b32 s26, 0x1e2a0000
	v_add_co_u32_e32 v14, vcc, s26, v6
	s_nop 0
	v_addc_co_u32_e32 v15, vcc, 0, v7, vcc
	global_load_dwordx4 v[2:5], v[2:3], off
	s_mul_i32 s28, s27, 0x2400
	global_load_dwordx4 v[6:9], v[14:15], off offset:512
	s_add_i32 s26, s13, -7
	s_add_i32 s29, s28, 0xffffdc00
	s_cmp_lg_u32 s27, 0
	s_cselect_b32 s29, s29, 0x9000
	v_add_u32_e32 v1, s29, v195
	ds_read_b128 v[10:13], v1 offset:36864
	ds_read_b128 v[66:69], v1 offset:36896
	ds_read_b128 v[70:73], v1 offset:41472
	ds_read_b128 v[74:77], v1 offset:41504
	ds_read_b128 v[128:131], v1 offset:36928
	ds_read_b128 v[132:135], v1 offset:36960
	ds_read_b128 v[148:151], v1 offset:41536
	ds_read_b128 v[160:163], v1 offset:41568
	s_setprio 3
	v_cvt_pk_bf16_f32 v210, v116, v117
	v_cvt_pk_bf16_f32 v211, v118, v119
	v_cvt_pk_bf16_f32 v212, v112, v113
	v_cvt_pk_bf16_f32 v213, v114, v115
	s_waitcnt lgkmcnt(7)
	s_nop 0
	v_mfma_f32_32x32x16_bf16 v[16:31], v[10:13], v[210:213], v[16:31]
	v_add_f32_e32 v1, v116, v117
	v_add_f32_e32 v1, v1, v118
	v_add_f32_e32 v1, v1, v119
	s_waitcnt lgkmcnt(5)
	v_mfma_f32_32x32x16_bf16 v[32:47], v[70:73], v[210:213], v[32:47]
	v_cvt_pk_bf16_f32 v10, v187, v186
	v_cvt_pk_bf16_f32 v11, v185, v184
	v_cvt_pk_bf16_f32 v12, v147, v146
	v_cvt_pk_bf16_f32 v13, v145, v144
	v_add_f32_e32 v1, v1, v112
	v_add_f32_e32 v1, v1, v113
	v_add_f32_e32 v1, v1, v114
	v_add_f32_e32 v1, v1, v115
	s_nop 0
	v_mfma_f32_32x32x16_bf16 v[16:31], v[66:69], v[10:13], v[16:31]
	v_add_f32_e32 v1, v1, v187
	v_add_f32_e32 v1, v1, v186
	v_add_f32_e32 v1, v1, v185
	v_add_f32_e32 v1, v1, v184
	s_waitcnt lgkmcnt(4)
	v_mfma_f32_32x32x16_bf16 v[32:47], v[74:77], v[10:13], v[32:47]
	v_cvt_pk_bf16_f32 v66, v143, v142
	v_cvt_pk_bf16_f32 v67, v141, v140
	v_cvt_pk_bf16_f32 v68, v139, v138
	v_cvt_pk_bf16_f32 v69, v137, v136
	v_add_f32_e32 v1, v1, v147
	v_add_f32_e32 v1, v1, v146
	v_add_f32_e32 v1, v1, v145
	v_add_f32_e32 v1, v1, v144
	s_waitcnt lgkmcnt(3)
	v_mfma_f32_32x32x16_bf16 v[16:31], v[128:131], v[66:69], v[16:31]
	v_add_f32_e32 v1, v1, v143
	v_add_f32_e32 v1, v1, v142
	v_add_f32_e32 v1, v1, v141
	v_add_f32_e32 v1, v1, v140
	s_waitcnt lgkmcnt(1)
	v_mfma_f32_32x32x16_bf16 v[32:47], v[148:151], v[66:69], v[32:47]
	v_cvt_pk_bf16_f32 v10, v123, v122
	v_cvt_pk_bf16_f32 v11, v121, v120
	v_cvt_pk_bf16_f32 v12, v127, v126
	v_cvt_pk_bf16_f32 v13, v125, v124
	v_add_f32_e32 v1, v1, v139
	v_add_f32_e32 v1, v1, v138
	v_add_f32_e32 v1, v1, v137
	v_add_f32_e32 v1, v1, v136
	s_nop 0
	v_mfma_f32_32x32x16_bf16 v[16:31], v[132:135], v[10:13], v[16:31]
	v_add_f32_e32 v1, v1, v123
	v_add_f32_e32 v1, v1, v122
	v_add_f32_e32 v1, v1, v121
	v_add_f32_e32 v1, v1, v120
	s_waitcnt lgkmcnt(0)
	v_mfma_f32_32x32x16_bf16 v[32:47], v[160:163], v[10:13], v[32:47]
	v_add_f32_e32 v1, v1, v127
	v_add_f32_e32 v1, v1, v126
	v_add_f32_e32 v1, v1, v125
	v_add_f32_e32 v1, v1, v124
	s_setprio 2
	s_waitcnt lgkmcnt(0)
	s_barrier
	ds_read_b128 v[240:243], v195 offset:18432
	ds_read_b128 v[244:247], v195 offset:23040
	ds_read_b128 v[66:69], v195 offset:18464
	ds_read_b128 v[74:77], v195 offset:23072
	ds_read_b128 v[144:147], v195 offset:18496
	ds_read_b128 v[148:151], v195 offset:18528
	ds_read_b128 v[160:163], v195 offset:23104
	ds_read_b128 v[184:187], v195 offset:23136
	s_waitcnt lgkmcnt(6)
	v_mfma_f32_32x32x16_bf16 v[128:143], v[240:243], v[180:183], v[48:63]
	v_exp_f32_e32 v166, v96
	v_exp_f32_e32 v167, v97
	v_exp_f32_e32 v210, v98
	v_exp_f32_e32 v211, v99
	s_waitcnt lgkmcnt(5)
	v_mfma_f32_32x32x16_bf16 v[112:127], v[244:247], v[180:183], v[48:63]
	v_exp_f32_e32 v212, v100
	v_exp_f32_e32 v213, v101
	v_exp_f32_e32 v214, v102
	v_exp_f32_e32 v215, v103
	v_mfma_f32_32x32x16_bf16 v[128:143], v[66:69], v[176:179], v[128:143]
	v_exp_f32_e32 v100, v104
	v_exp_f32_e32 v101, v105
	v_exp_f32_e32 v102, v106
	v_exp_f32_e32 v103, v107
	s_waitcnt lgkmcnt(4)
	v_mfma_f32_32x32x16_bf16 v[112:127], v[74:77], v[176:179], v[112:127]
	v_exp_f32_e32 v104, v108
	v_exp_f32_e32 v105, v109
	v_exp_f32_e32 v106, v110
	v_exp_f32_e32 v107, v111
	s_waitcnt lgkmcnt(3)
	v_mfma_f32_32x32x16_bf16 v[128:143], v[144:147], v[172:175], v[128:143]
	v_exp_f32_e32 v108, v80
	v_exp_f32_e32 v109, v81
	v_exp_f32_e32 v110, v82
	v_exp_f32_e32 v111, v83
	s_waitcnt lgkmcnt(1)
	v_mfma_f32_32x32x16_bf16 v[112:127], v[160:163], v[172:175], v[112:127]
	v_exp_f32_e32 v144, v84
	v_exp_f32_e32 v145, v85
	v_exp_f32_e32 v146, v86
	v_exp_f32_e32 v147, v87
	v_mfma_f32_32x32x16_bf16 v[128:143], v[148:151], v[168:171], v[128:143]
	v_exp_f32_e32 v216, v88
	v_exp_f32_e32 v217, v89
	v_exp_f32_e32 v218, v90
	v_exp_f32_e32 v219, v91
	s_waitcnt lgkmcnt(0)
	v_mfma_f32_32x32x16_bf16 v[112:127], v[184:187], v[168:171], v[112:127]
	v_exp_f32_e32 v148, v92
	v_exp_f32_e32 v149, v93
	v_exp_f32_e32 v150, v94
	v_exp_f32_e32 v151, v95
	s_cmp_gt_i32 s27, 2
	s_cselect_b32 s29, -3, 2
	s_add_i32 s29, s29, s27
	v_add_u32_e32 v92, s28, v195
	s_add_i32 s28, s13, -6
	s_mulk_i32 s29, 0x2400
	s_min_u32 s28, s28, s12
	v_add_u32_e32 v10, s29, v208
	s_min_u32 s26, s26, s12
	s_lshl_b32 s92, s28, 13
	s_waitcnt vmcnt(3)
	ds_write_b128 v208, v[152:155]
	s_waitcnt vmcnt(2)
	ds_write_b128 v10, v[156:159] offset:36864
	s_add_u32 vcc_lo, s100, s92
	s_addc_u32 vcc_hi, s101, 0
	global_load_dwordx4 v[10:13], v248, vcc
	s_lshl_b32 s92, s26, 7
	v_add_f32_e32 v1, v64, v1
	s_add_u32 vcc_lo, s98, s92
	s_addc_u32 vcc_hi, s99, 0
	global_load_dwordx4 v[160:163], v249, vcc
	s_add_i32 s29, s27, 1
	ds_read_b128 v[240:243], v195 offset:27648
	ds_read_b128 v[244:247], v195 offset:32256
	ds_read_b128 v[64:67], v92 offset:41472
	ds_read_b128 v[68:71], v92 offset:36864
	ds_read_b128 v[72:75], v92 offset:36896
	ds_read_b128 v[76:79], v92 offset:41504
	ds_read_b128 v[80:83], v92 offset:36928
	ds_read_b128 v[84:87], v92 offset:41536
	ds_read_b128 v[88:91], v92 offset:36960
	ds_read_b128 v[92:95], v92 offset:41568
	s_setprio 1
	v_cvt_pk_bf16_f32 v96, v166, v167
	v_cvt_pk_bf16_f32 v97, v210, v211
	v_cvt_pk_bf16_f32 v98, v212, v213
	v_cvt_pk_bf16_f32 v99, v214, v215
	s_waitcnt lgkmcnt(6)
	s_nop 0
	v_mfma_f32_32x32x16_bf16 v[16:31], v[68:71], v[96:99], v[16:31]
	v_add_f32_e32 v184, v166, v167
	v_add_f32_e32 v184, v184, v210
	v_add_f32_e32 v184, v184, v211
	s_nop 0
	v_mfma_f32_32x32x16_bf16 v[32:47], v[64:67], v[96:99], v[32:47]
	v_cvt_pk_bf16_f32 v68, v100, v101
	v_cvt_pk_bf16_f32 v69, v102, v103
	v_cvt_pk_bf16_f32 v70, v104, v105
	v_cvt_pk_bf16_f32 v71, v106, v107
	v_add_f32_e32 v184, v184, v212
	v_add_f32_e32 v184, v184, v213
	v_add_f32_e32 v184, v184, v214
	v_add_f32_e32 v184, v184, v215
	s_waitcnt lgkmcnt(5)
	v_mfma_f32_32x32x16_bf16 v[16:31], v[72:75], v[68:71], v[16:31]
	v_add_f32_e32 v184, v184, v100
	v_add_f32_e32 v184, v184, v101
	v_add_f32_e32 v184, v184, v102
	v_add_f32_e32 v184, v184, v103
	s_waitcnt lgkmcnt(4)
	v_mfma_f32_32x32x16_bf16 v[32:47], v[76:79], v[68:71], v[32:47]
	v_cvt_pk_bf16_f32 v64, v108, v109
	v_cvt_pk_bf16_f32 v65, v110, v111
	v_cvt_pk_bf16_f32 v66, v144, v145
	v_cvt_pk_bf16_f32 v67, v146, v147
	v_add_f32_e32 v184, v184, v104
	v_add_f32_e32 v184, v184, v105
	v_add_f32_e32 v184, v184, v106
	v_add_f32_e32 v184, v184, v107
	s_waitcnt lgkmcnt(3)
	v_mfma_f32_32x32x16_bf16 v[16:31], v[80:83], v[64:67], v[16:31]
	v_add_f32_e32 v184, v184, v108
	v_add_f32_e32 v184, v184, v109
	v_add_f32_e32 v184, v184, v110
	v_add_f32_e32 v184, v184, v111
	s_waitcnt lgkmcnt(2)
	v_mfma_f32_32x32x16_bf16 v[32:47], v[84:87], v[64:67], v[32:47]
	v_cvt_pk_bf16_f32 v68, v216, v217
	v_cvt_pk_bf16_f32 v69, v218, v219
	v_cvt_pk_bf16_f32 v70, v148, v149
	v_cvt_pk_bf16_f32 v71, v150, v151
	v_add_f32_e32 v184, v184, v144
	v_add_f32_e32 v184, v184, v145
	v_add_f32_e32 v184, v184, v146
	v_add_f32_e32 v184, v184, v147
	s_waitcnt lgkmcnt(1)
	v_mfma_f32_32x32x16_bf16 v[16:31], v[88:91], v[68:71], v[16:31]
	v_add_f32_e32 v184, v184, v216
	v_add_f32_e32 v184, v184, v217
	v_add_f32_e32 v184, v184, v218
	v_add_f32_e32 v184, v184, v219
	s_waitcnt lgkmcnt(0)
	v_mfma_f32_32x32x16_bf16 v[32:47], v[92:95], v[68:71], v[32:47]
	v_add_f32_e32 v184, v184, v148
	v_add_f32_e32 v184, v184, v149
	v_add_f32_e32 v184, v184, v150
	v_add_f32_e32 v184, v184, v151
	s_setprio 0
	ds_read_b128 v[68:71], v195 offset:27680
	ds_read_b128 v[76:79], v195 offset:32288
	ds_read_b128 v[80:83], v195 offset:27712
	ds_read_b128 v[84:87], v195 offset:27744
	ds_read_b128 v[88:91], v195 offset:32320
	ds_read_b128 v[92:95], v195 offset:32352
	s_cmp_lg_u32 s27, 4
	s_cselect_b32 s26, s29, 0
	s_waitcnt lgkmcnt(6)
	v_mfma_f32_32x32x16_bf16 v[144:159], v[240:243], v[180:183], v[48:63]
	v_exp_f32_e32 v166, v128
	v_exp_f32_e32 v167, v129
	v_exp_f32_e32 v185, v130
	v_exp_f32_e32 v186, v131
	s_waitcnt lgkmcnt(5)
	v_mfma_f32_32x32x16_bf16 v[96:111], v[244:247], v[180:183], v[48:63]
	v_exp_f32_e32 v128, v132
	v_exp_f32_e32 v129, v133
	v_exp_f32_e32 v130, v134
	v_exp_f32_e32 v131, v135
	v_mfma_f32_32x32x16_bf16 v[144:159], v[68:71], v[176:179], v[144:159]
	v_exp_f32_e32 v132, v136
	v_exp_f32_e32 v133, v137
	v_exp_f32_e32 v134, v138
	v_exp_f32_e32 v135, v139
	s_waitcnt lgkmcnt(4)
	v_mfma_f32_32x32x16_bf16 v[96:111], v[76:79], v[176:179], v[96:111]
	v_exp_f32_e32 v136, v140
	v_exp_f32_e32 v137, v141
	v_exp_f32_e32 v138, v142
	v_exp_f32_e32 v139, v143
	s_waitcnt lgkmcnt(3)
	v_mfma_f32_32x32x16_bf16 v[144:159], v[80:83], v[172:175], v[144:159]
	v_exp_f32_e32 v140, v112
	v_exp_f32_e32 v141, v113
	v_exp_f32_e32 v142, v114
	v_exp_f32_e32 v143, v115
	s_waitcnt lgkmcnt(1)
	v_mfma_f32_32x32x16_bf16 v[96:111], v[88:91], v[172:175], v[96:111]
	v_exp_f32_e32 v187, v116
	v_exp_f32_e32 v210, v117
	v_exp_f32_e32 v211, v118
	v_exp_f32_e32 v212, v119
	v_mfma_f32_32x32x16_bf16 v[144:159], v[84:87], v[168:171], v[144:159]
	v_exp_f32_e32 v116, v120
	v_exp_f32_e32 v117, v121
	v_exp_f32_e32 v118, v122
	v_exp_f32_e32 v119, v123
	s_waitcnt lgkmcnt(0)
	v_mfma_f32_32x32x16_bf16 v[96:111], v[92:95], v[168:171], v[96:111]
	v_exp_f32_e32 v120, v124
	v_exp_f32_e32 v121, v125
	v_exp_f32_e32 v122, v126
	v_exp_f32_e32 v123, v127
	s_cmp_gt_i32 s26, 2
	s_cselect_b32 s27, -3, 2
	s_add_i32 s27, s27, s26
	s_mulk_i32 s27, 0x2400
	s_waitcnt vmcnt(3)
	ds_write_b128 v208, v[2:5] offset:9216
	v_add_u32_e32 v2, s27, v208
	s_add_i32 s27, s26, 1
	s_cmp_lg_u32 s26, 4
	s_cselect_b32 s26, s27, 0
	s_add_i32 s27, s13, -5
	s_min_u32 s27, s27, s12
	s_lshl_b32 s92, s27, 13
	s_waitcnt vmcnt(2)
	ds_write_b128 v2, v[6:9] offset:36864
	s_add_u32 vcc_lo, s100, s92
	s_addc_u32 vcc_hi, s101, 0
	global_load_dwordx4 v[6:9], v248, vcc
	s_lshl_b32 s92, s28, 7
	s_add_u32 vcc_lo, s98, s92
	s_addc_u32 vcc_hi, s99, 0
	global_load_dwordx4 v[2:5], v249, vcc
	s_nop 0
	s_mul_i32 s28, s26, 0x2400
	s_add_i32 s29, s28, 0xffffdc00
	s_cmp_lg_u32 s26, 0
	s_cselect_b32 s29, s29, 0x9000
	v_add_u32_e32 v92, s29, v195
	ds_read_b128 v[64:67], v92 offset:36864
	ds_read_b128 v[68:71], v92 offset:36896
	ds_read_b128 v[72:75], v92 offset:41472
	ds_read_b128 v[76:79], v92 offset:41504
	ds_read_b128 v[80:83], v92 offset:36928
	ds_read_b128 v[84:87], v92 offset:36960
	ds_read_b128 v[88:91], v92 offset:41536
	ds_read_b128 v[92:95], v92 offset:41568
	s_setprio 3
	v_cvt_pk_bf16_f32 v112, v166, v167
	v_cvt_pk_bf16_f32 v113, v185, v186
	v_cvt_pk_bf16_f32 v114, v128, v129
	v_cvt_pk_bf16_f32 v115, v130, v131
	s_waitcnt lgkmcnt(7)
	s_nop 0
	v_mfma_f32_32x32x16_bf16 v[16:31], v[64:67], v[112:115], v[16:31]
	v_add_f32_e32 v213, v166, v167
	v_add_f32_e32 v213, v213, v185
	v_add_f32_e32 v213, v213, v186
	s_waitcnt lgkmcnt(5)
	v_mfma_f32_32x32x16_bf16 v[32:47], v[72:75], v[112:115], v[32:47]
	v_cvt_pk_bf16_f32 v64, v132, v133
	v_cvt_pk_bf16_f32 v65, v134, v135
	v_cvt_pk_bf16_f32 v66, v136, v137
	v_cvt_pk_bf16_f32 v67, v138, v139
	v_add_f32_e32 v213, v213, v128
	v_add_f32_e32 v213, v213, v129
	v_add_f32_e32 v213, v213, v130
	v_add_f32_e32 v213, v213, v131
	s_nop 0
	v_mfma_f32_32x32x16_bf16 v[16:31], v[68:71], v[64:67], v[16:31]
	v_add_f32_e32 v213, v213, v132
	v_add_f32_e32 v213, v213, v133
	v_add_f32_e32 v213, v213, v134
	v_add_f32_e32 v213, v213, v135
	s_waitcnt lgkmcnt(4)
	v_mfma_f32_32x32x16_bf16 v[32:47], v[76:79], v[64:67], v[32:47]
	v_cvt_pk_bf16_f32 v68, v140, v141
	v_cvt_pk_bf16_f32 v69, v142, v143
	v_cvt_pk_bf16_f32 v70, v187, v210
	v_cvt_pk_bf16_f32 v71, v211, v212
	v_add_f32_e32 v213, v213, v136
	v_add_f32_e32 v213, v213, v137
	v_add_f32_e32 v213, v213, v138
	v_add_f32_e32 v213, v213, v139
	s_waitcnt lgkmcnt(3)
	v_mfma_f32_32x32x16_bf16 v[16:31], v[80:83], v[68:71], v[16:31]
	v_add_f32_e32 v213, v213, v140
	v_add_f32_e32 v213, v213, v141
	v_add_f32_e32 v213, v213, v142
	v_add_f32_e32 v213, v213, v143
	s_waitcnt lgkmcnt(1)
	v_mfma_f32_32x32x16_bf16 v[32:47], v[88:91], v[68:71], v[32:47]
	v_cvt_pk_bf16_f32 v64, v116, v117
	v_cvt_pk_bf16_f32 v65, v118, v119
	v_cvt_pk_bf16_f32 v66, v120, v121
	v_cvt_pk_bf16_f32 v67, v122, v123
	v_add_f32_e32 v213, v213, v187
	v_add_f32_e32 v213, v213, v210
	v_add_f32_e32 v213, v213, v211
	v_add_f32_e32 v213, v213, v212
	s_nop 0
	v_mfma_f32_32x32x16_bf16 v[16:31], v[84:87], v[64:67], v[16:31]
	v_add_f32_e32 v213, v213, v116
	v_add_f32_e32 v213, v213, v117
	v_add_f32_e32 v213, v213, v118
	v_add_f32_e32 v213, v213, v119
	s_waitcnt lgkmcnt(0)
	v_mfma_f32_32x32x16_bf16 v[32:47], v[92:95], v[64:67], v[32:47]
	v_add_f32_e32 v213, v213, v120
	v_add_f32_e32 v213, v213, v121
	v_add_f32_e32 v213, v213, v122
	v_add_f32_e32 v213, v213, v123
	s_setprio 2
	s_waitcnt lgkmcnt(0)
	s_barrier
	ds_read_b128 v[240:243], v195
	ds_read_b128 v[244:247], v195 offset:4608
	ds_read_b128 v[116:119], v195 offset:32
	ds_read_b128 v[120:123], v195 offset:4640
	ds_read_b128 v[124:127], v195 offset:64
	ds_read_b128 v[128:131], v195 offset:4672
	ds_read_b128 v[132:135], v195 offset:96
	ds_read_b128 v[136:139], v195 offset:4704
	v_add_f32_e32 v1, v1, v184
	s_waitcnt lgkmcnt(6)
	v_mfma_f32_32x32x16_bf16 v[80:95], v[240:243], v[180:183], v[48:63]
	v_exp_f32_e32 v140, v144
	v_exp_f32_e32 v141, v145
	v_exp_f32_e32 v142, v146
	v_exp_f32_e32 v143, v147
	v_mfma_f32_32x32x16_bf16 v[64:79], v[244:247], v[180:183], v[48:63]
	v_exp_f32_e32 v144, v148
	v_exp_f32_e32 v145, v149
	v_exp_f32_e32 v146, v150
	v_exp_f32_e32 v147, v151
	s_waitcnt lgkmcnt(5)
	v_mfma_f32_32x32x16_bf16 v[80:95], v[116:119], v[176:179], v[80:95]
	v_exp_f32_e32 v148, v152
	v_exp_f32_e32 v149, v153
	v_exp_f32_e32 v150, v154
	v_exp_f32_e32 v151, v155
	s_waitcnt lgkmcnt(4)
	v_mfma_f32_32x32x16_bf16 v[64:79], v[120:123], v[176:179], v[64:79]
	v_exp_f32_e32 v152, v156
	v_exp_f32_e32 v153, v157
	v_exp_f32_e32 v154, v158
	v_exp_f32_e32 v155, v159
	s_waitcnt lgkmcnt(3)
	v_mfma_f32_32x32x16_bf16 v[80:95], v[124:127], v[172:175], v[80:95]
	v_exp_f32_e32 v156, v96
	v_exp_f32_e32 v157, v97
	v_exp_f32_e32 v158, v98
	v_exp_f32_e32 v159, v99
	s_waitcnt lgkmcnt(2)
	v_mfma_f32_32x32x16_bf16 v[64:79], v[128:131], v[172:175], v[64:79]
	v_exp_f32_e32 v166, v100
	v_exp_f32_e32 v167, v101
	v_exp_f32_e32 v184, v102
	v_exp_f32_e32 v185, v103
	s_waitcnt lgkmcnt(1)
	v_mfma_f32_32x32x16_bf16 v[80:95], v[132:135], v[168:171], v[80:95]
	v_exp_f32_e32 v186, v104
	v_exp_f32_e32 v187, v105
	v_exp_f32_e32 v210, v106
	v_exp_f32_e32 v211, v107
	s_waitcnt lgkmcnt(0)
	v_mfma_f32_32x32x16_bf16 v[64:79], v[136:139], v[168:171], v[64:79]
	v_exp_f32_e32 v212, v108
	v_exp_f32_e32 v214, v109
	v_exp_f32_e32 v215, v110
	v_exp_f32_e32 v216, v111
	s_cmp_gt_i32 s26, 2
	s_cselect_b32 s29, -3, 2
	s_add_i32 s29, s29, s26
	s_mulk_i32 s29, 0x2400
	s_waitcnt vmcnt(3)
	ds_write_b128 v208, v[10:13] offset:18432
	v_add_u32_e32 v10, s29, v208
	s_mov_b32 s29, 0x1da90000
	s_waitcnt vmcnt(2)
	ds_write_b128 v10, v[160:163] offset:36864
	v_add_co_u32_e32 v10, vcc, s29, v164
	s_lshl_b32 s92, s27, 7
	s_nop 0
	v_addc_co_u32_e32 v11, vcc, 0, v165, vcc
	global_load_dwordx4 v[128:131], v[10:11], off
	s_add_u32 vcc_lo, s98, s92
	s_addc_u32 vcc_hi, s99, 0
	global_load_dwordx4 v[10:13], v249, vcc
	v_add_u32_e32 v124, s28, v195
	ds_read_b128 v[240:243], v195 offset:9216
	ds_read_b128 v[244:247], v195 offset:13824
	ds_read_b128 v[96:99], v124 offset:41472
	ds_read_b128 v[100:103], v124 offset:36864
	ds_read_b128 v[104:107], v124 offset:36896
	ds_read_b128 v[108:111], v124 offset:41504
	ds_read_b128 v[112:115], v124 offset:36928
	ds_read_b128 v[116:119], v124 offset:41536
	ds_read_b128 v[120:123], v124 offset:36960
	ds_read_b128 v[124:127], v124 offset:41568
	v_add_f32_e32 v1, v1, v213
	s_add_i32 s28, s26, 1
	s_setprio 1
	v_cvt_pk_bf16_f32 v132, v140, v141
	v_cvt_pk_bf16_f32 v133, v142, v143
	v_cvt_pk_bf16_f32 v134, v144, v145
	v_cvt_pk_bf16_f32 v135, v146, v147
	s_waitcnt lgkmcnt(6)
	s_nop 0
	v_mfma_f32_32x32x16_bf16 v[16:31], v[100:103], v[132:135], v[16:31]
	v_add_f32_e32 v160, v140, v141
	v_add_f32_e32 v160, v160, v142
	v_add_f32_e32 v160, v160, v143
	s_nop 0
	v_mfma_f32_32x32x16_bf16 v[32:47], v[96:99], v[132:135], v[32:47]
	v_cvt_pk_bf16_f32 v100, v148, v149
	v_cvt_pk_bf16_f32 v101, v150, v151
	v_cvt_pk_bf16_f32 v102, v152, v153
	v_cvt_pk_bf16_f32 v103, v154, v155
	v_add_f32_e32 v160, v160, v144
	v_add_f32_e32 v160, v160, v145
	v_add_f32_e32 v160, v160, v146
	v_add_f32_e32 v160, v160, v147
	s_waitcnt lgkmcnt(5)
	v_mfma_f32_32x32x16_bf16 v[16:31], v[104:107], v[100:103], v[16:31]
	v_add_f32_e32 v160, v160, v148
	v_add_f32_e32 v160, v160, v149
	v_add_f32_e32 v160, v160, v150
	v_add_f32_e32 v160, v160, v151
	s_waitcnt lgkmcnt(4)
	v_mfma_f32_32x32x16_bf16 v[32:47], v[108:111], v[100:103], v[32:47]
	v_cvt_pk_bf16_f32 v96, v156, v157
	v_cvt_pk_bf16_f32 v97, v158, v159
	v_cvt_pk_bf16_f32 v98, v166, v167
	v_cvt_pk_bf16_f32 v99, v184, v185
	v_add_f32_e32 v160, v160, v152
	v_add_f32_e32 v160, v160, v153
	v_add_f32_e32 v160, v160, v154
	v_add_f32_e32 v160, v160, v155
	s_waitcnt lgkmcnt(3)
	v_mfma_f32_32x32x16_bf16 v[16:31], v[112:115], v[96:99], v[16:31]
	v_add_f32_e32 v160, v160, v156
	v_add_f32_e32 v160, v160, v157
	v_add_f32_e32 v160, v160, v158
	v_add_f32_e32 v160, v160, v159
	s_waitcnt lgkmcnt(2)
	v_mfma_f32_32x32x16_bf16 v[32:47], v[116:119], v[96:99], v[32:47]
	v_cvt_pk_bf16_f32 v100, v186, v187
	v_cvt_pk_bf16_f32 v101, v210, v211
	v_cvt_pk_bf16_f32 v102, v212, v214
	v_cvt_pk_bf16_f32 v103, v215, v216
	v_add_f32_e32 v160, v160, v166
	v_add_f32_e32 v160, v160, v167
	v_add_f32_e32 v160, v160, v184
	v_add_f32_e32 v160, v160, v185
	s_waitcnt lgkmcnt(1)
	v_mfma_f32_32x32x16_bf16 v[16:31], v[120:123], v[100:103], v[16:31]
	v_add_f32_e32 v160, v160, v186
	v_add_f32_e32 v160, v160, v187
	v_add_f32_e32 v160, v160, v210
	v_add_f32_e32 v160, v160, v211
	s_waitcnt lgkmcnt(0)
	v_mfma_f32_32x32x16_bf16 v[32:47], v[124:127], v[100:103], v[32:47]
	v_add_f32_e32 v160, v160, v212
	v_add_f32_e32 v160, v160, v214
	v_add_f32_e32 v160, v160, v215
	v_add_f32_e32 v160, v160, v216
	s_setprio 0
	ds_read_b128 v[132:135], v195 offset:9248
	ds_read_b128 v[140:143], v195 offset:13856
	ds_read_b128 v[144:147], v195 offset:9280
	ds_read_b128 v[148:151], v195 offset:9312
	ds_read_b128 v[152:155], v195 offset:13888
	ds_read_b128 v[156:159], v195 offset:13920
	s_cmp_lg_u32 s26, 4
	s_cselect_b32 s26, s28, 0
	s_waitcnt lgkmcnt(6)
	v_mfma_f32_32x32x16_bf16 v[112:127], v[240:243], v[180:183], v[48:63]
	v_exp_f32_e32 v161, v80
	v_exp_f32_e32 v162, v81
	v_exp_f32_e32 v163, v82
	v_exp_f32_e32 v164, v83
	s_waitcnt lgkmcnt(5)
	v_mfma_f32_32x32x16_bf16 v[96:111], v[244:247], v[180:183], v[48:63]
	v_exp_f32_e32 v165, v84
	v_exp_f32_e32 v166, v85
	v_exp_f32_e32 v167, v86
	v_exp_f32_e32 v184, v87
	v_mfma_f32_32x32x16_bf16 v[112:127], v[132:135], v[176:179], v[112:127]
	v_exp_f32_e32 v136, v88
	v_exp_f32_e32 v137, v89
	v_exp_f32_e32 v138, v90
	v_exp_f32_e32 v139, v91
	s_waitcnt lgkmcnt(4)
	v_mfma_f32_32x32x16_bf16 v[96:111], v[140:143], v[176:179], v[96:111]
	v_exp_f32_e32 v185, v92
	v_exp_f32_e32 v186, v93
	v_exp_f32_e32 v187, v94
	v_exp_f32_e32 v210, v95
	s_waitcnt lgkmcnt(3)
	v_mfma_f32_32x32x16_bf16 v[112:127], v[144:147], v[172:175], v[112:127]
	v_exp_f32_e32 v140, v64
	v_exp_f32_e32 v141, v65
	v_exp_f32_e32 v142, v66
	v_exp_f32_e32 v143, v67
	s_waitcnt lgkmcnt(1)
	v_mfma_f32_32x32x16_bf16 v[96:111], v[152:155], v[172:175], v[96:111]
	v_exp_f32_e32 v144, v68
	v_exp_f32_e32 v145, v69
	v_exp_f32_e32 v146, v70
	v_exp_f32_e32 v147, v71
	v_mfma_f32_32x32x16_bf16 v[112:127], v[148:151], v[168:171], v[112:127]
	v_exp_f32_e32 v152, v72
	v_exp_f32_e32 v153, v73
	v_exp_f32_e32 v154, v74
	v_exp_f32_e32 v155, v75
	s_waitcnt lgkmcnt(0)
	v_mfma_f32_32x32x16_bf16 v[96:111], v[156:159], v[168:171], v[96:111]
	v_exp_f32_e32 v148, v76
	v_exp_f32_e32 v149, v77
	v_exp_f32_e32 v150, v78
	v_exp_f32_e32 v151, v79
	s_cmp_gt_i32 s26, 2
	s_cselect_b32 s27, -3, 2
	s_add_i32 s27, s27, s26
	s_mulk_i32 s27, 0x2400
	s_waitcnt vmcnt(3)
	ds_write_b128 v208, v[6:9] offset:27648
	v_add_u32_e32 v6, s27, v208
	s_add_i32 s27, s26, 1
	s_cmp_lg_u32 s26, 4
	s_cselect_b32 s27, s27, 0
	s_add_i32 s26, s13, -3
	s_min_u32 s28, s26, s12
	s_lshl_b32 s92, s28, 13
	s_waitcnt vmcnt(2)
	ds_write_b128 v6, v[2:5] offset:36864
	s_add_u32 vcc_lo, s100, s92
	s_addc_u32 vcc_hi, s101, 0
	global_load_dwordx4 v[6:9], v248, vcc
	s_nop 0
	global_load_dwordx4 v[2:5], v[14:15], off offset:1024
	s_mul_i32 s29, s27, 0x2400
	s_add_i32 s34, s29, 0xffffdc00
	s_cmp_lg_u32 s27, 0
	s_cselect_b32 s34, s34, 0x9000
	v_add_u32_e32 v14, s34, v195
	ds_read_b128 v[64:67], v14 offset:36864
	ds_read_b128 v[68:71], v14 offset:36896
	ds_read_b128 v[72:75], v14 offset:41472
	ds_read_b128 v[76:79], v14 offset:41504
	ds_read_b128 v[80:83], v14 offset:36928
	ds_read_b128 v[84:87], v14 offset:36960
	ds_read_b128 v[88:91], v14 offset:41536
	ds_read_b128 v[92:95], v14 offset:41568
	s_setprio 3
	v_cvt_pk_bf16_f32 v132, v161, v162
	v_cvt_pk_bf16_f32 v133, v163, v164
	v_cvt_pk_bf16_f32 v134, v165, v166
	v_cvt_pk_bf16_f32 v135, v167, v184
	s_waitcnt lgkmcnt(7)
	s_nop 0
	v_mfma_f32_32x32x16_bf16 v[16:31], v[64:67], v[132:135], v[16:31]
	v_add_f32_e32 v14, v161, v162
	v_add_f32_e32 v14, v14, v163
	v_add_f32_e32 v14, v14, v164
	s_waitcnt lgkmcnt(5)
	v_mfma_f32_32x32x16_bf16 v[32:47], v[72:75], v[132:135], v[32:47]
	v_cvt_pk_bf16_f32 v64, v136, v137
	v_cvt_pk_bf16_f32 v65, v138, v139
	v_cvt_pk_bf16_f32 v66, v185, v186
	v_cvt_pk_bf16_f32 v67, v187, v210
	v_add_f32_e32 v14, v14, v165
	v_add_f32_e32 v14, v14, v166
	v_add_f32_e32 v14, v14, v167
	v_add_f32_e32 v14, v14, v184
	s_nop 0
	v_mfma_f32_32x32x16_bf16 v[16:31], v[68:71], v[64:67], v[16:31]
	v_add_f32_e32 v14, v14, v136
	v_add_f32_e32 v14, v14, v137
	v_add_f32_e32 v14, v14, v138
	v_add_f32_e32 v14, v14, v139
	s_waitcnt lgkmcnt(4)
	v_mfma_f32_32x32x16_bf16 v[32:47], v[76:79], v[64:67], v[32:47]
	v_cvt_pk_bf16_f32 v68, v140, v141
	v_cvt_pk_bf16_f32 v69, v142, v143
	v_cvt_pk_bf16_f32 v70, v144, v145
	v_cvt_pk_bf16_f32 v71, v146, v147
	v_add_f32_e32 v14, v14, v185
	v_add_f32_e32 v14, v14, v186
	v_add_f32_e32 v14, v14, v187
	v_add_f32_e32 v14, v14, v210
	s_waitcnt lgkmcnt(3)
	v_mfma_f32_32x32x16_bf16 v[16:31], v[80:83], v[68:71], v[16:31]
	v_add_f32_e32 v14, v14, v140
	v_add_f32_e32 v14, v14, v141
	v_add_f32_e32 v14, v14, v142
	v_add_f32_e32 v14, v14, v143
	s_waitcnt lgkmcnt(1)
	v_mfma_f32_32x32x16_bf16 v[32:47], v[88:91], v[68:71], v[32:47]
	v_cvt_pk_bf16_f32 v64, v152, v153
	v_cvt_pk_bf16_f32 v65, v154, v155
	v_cvt_pk_bf16_f32 v66, v148, v149
	v_cvt_pk_bf16_f32 v67, v150, v151
	v_add_f32_e32 v14, v14, v144
	v_add_f32_e32 v14, v14, v145
	v_add_f32_e32 v14, v14, v146
	v_add_f32_e32 v14, v14, v147
	s_nop 0
	v_mfma_f32_32x32x16_bf16 v[16:31], v[84:87], v[64:67], v[16:31]
	v_add_f32_e32 v14, v14, v152
	v_add_f32_e32 v14, v14, v153
	v_add_f32_e32 v14, v14, v154
	v_add_f32_e32 v14, v14, v155
	s_waitcnt lgkmcnt(0)
	v_mfma_f32_32x32x16_bf16 v[32:47], v[92:95], v[64:67], v[32:47]
	v_add_f32_e32 v14, v14, v148
	v_add_f32_e32 v14, v14, v149
	v_add_f32_e32 v14, v14, v150
	v_add_f32_e32 v14, v14, v151
	s_setprio 2
	s_waitcnt lgkmcnt(0)
	s_barrier
	ds_read_b128 v[240:243], v195 offset:18432
	ds_read_b128 v[244:247], v195 offset:23040
	ds_read_b128 v[136:139], v195 offset:18464
	ds_read_b128 v[140:143], v195 offset:23072
	ds_read_b128 v[144:147], v195 offset:18496
	ds_read_b128 v[148:151], v195 offset:23104
	ds_read_b128 v[152:155], v195 offset:18528
	ds_read_b128 v[156:159], v195 offset:23136
	v_add_f32_e32 v1, v1, v160
	s_waitcnt lgkmcnt(6)
	v_mfma_f32_32x32x16_bf16 v[80:95], v[240:243], v[180:183], v[48:63]
	v_exp_f32_e32 v160, v112
	v_exp_f32_e32 v161, v113
	v_exp_f32_e32 v162, v114
	v_exp_f32_e32 v163, v115
	v_mfma_f32_32x32x16_bf16 v[64:79], v[244:247], v[180:183], v[48:63]
	v_exp_f32_e32 v164, v116
	v_exp_f32_e32 v165, v117
	v_exp_f32_e32 v166, v118
	v_exp_f32_e32 v167, v119
	s_waitcnt lgkmcnt(5)
	v_mfma_f32_32x32x16_bf16 v[80:95], v[136:139], v[176:179], v[80:95]
	v_exp_f32_e32 v184, v120
	v_exp_f32_e32 v185, v121
	v_exp_f32_e32 v186, v122
	v_exp_f32_e32 v187, v123
	s_waitcnt lgkmcnt(4)
	v_mfma_f32_32x32x16_bf16 v[64:79], v[140:143], v[176:179], v[64:79]
	v_exp_f32_e32 v136, v124
	v_exp_f32_e32 v137, v125
	v_exp_f32_e32 v138, v126
	v_exp_f32_e32 v139, v127
	s_waitcnt lgkmcnt(3)
	v_mfma_f32_32x32x16_bf16 v[80:95], v[144:147], v[172:175], v[80:95]
	v_exp_f32_e32 v140, v96
	v_exp_f32_e32 v141, v97
	v_exp_f32_e32 v142, v98
	v_exp_f32_e32 v143, v99
	s_waitcnt lgkmcnt(2)
	v_mfma_f32_32x32x16_bf16 v[64:79], v[148:151], v[172:175], v[64:79]
	v_exp_f32_e32 v144, v100
	v_exp_f32_e32 v145, v101
	v_exp_f32_e32 v146, v102
	v_exp_f32_e32 v147, v103
	s_waitcnt lgkmcnt(1)
	v_mfma_f32_32x32x16_bf16 v[80:95], v[152:155], v[168:171], v[80:95]
	v_exp_f32_e32 v148, v104
	v_exp_f32_e32 v149, v105
	v_exp_f32_e32 v150, v106
	v_exp_f32_e32 v151, v107
	s_waitcnt lgkmcnt(0)
	v_mfma_f32_32x32x16_bf16 v[64:79], v[156:159], v[168:171], v[64:79]
	v_exp_f32_e32 v152, v108
	v_exp_f32_e32 v153, v109
	v_exp_f32_e32 v154, v110
	v_exp_f32_e32 v155, v111
	s_cmp_gt_i32 s27, 2
	s_cselect_b32 s34, -3, 2
	s_waitcnt vmcnt(3)
	ds_write_b128 v208, v[128:131]
	s_add_i32 s34, s34, s27
	v_add_u32_e32 v128, s29, v195
	s_add_i32 s29, s13, -2
	s_mulk_i32 s34, 0x2400
	s_min_u32 s29, s29, s12
	v_add_u32_e32 v15, s34, v208
	s_lshl_b32 s92, s29, 13
	s_waitcnt vmcnt(2)
	ds_write_b128 v15, v[10:13] offset:36864
	s_add_u32 vcc_lo, s100, s92
	s_addc_u32 vcc_hi, s101, 0
	global_load_dwordx4 v[10:13], v248, vcc
	s_lshl_b32 s92, s28, 7
	v_add_f32_e32 v1, v1, v14
	s_add_u32 vcc_lo, s98, s92
	s_addc_u32 vcc_hi, s99, 0
	global_load_dwordx4 v[112:115], v249, vcc
	ds_read_b128 v[240:243], v195 offset:27648
	ds_read_b128 v[244:247], v195 offset:32256
	ds_read_b128 v[96:99], v128 offset:41472
	ds_read_b128 v[100:103], v128 offset:36864
	ds_read_b128 v[104:107], v128 offset:36896
	ds_read_b128 v[108:111], v128 offset:41504
	ds_read_b128 v[116:119], v128 offset:36928
	ds_read_b128 v[120:123], v128 offset:41536
	ds_read_b128 v[124:127], v128 offset:36960
	ds_read_b128 v[128:131], v128 offset:41568
	s_add_i32 s34, s27, 1
	s_setprio 1
	v_cvt_pk_bf16_f32 v132, v160, v161
	v_cvt_pk_bf16_f32 v133, v162, v163
	v_cvt_pk_bf16_f32 v134, v164, v165
	v_cvt_pk_bf16_f32 v135, v166, v167
	s_waitcnt lgkmcnt(6)
	s_nop 0
	v_mfma_f32_32x32x16_bf16 v[16:31], v[100:103], v[132:135], v[16:31]
	v_add_f32_e32 v14, v160, v161
	v_add_f32_e32 v14, v14, v162
	v_add_f32_e32 v14, v14, v163
	s_nop 0
	v_mfma_f32_32x32x16_bf16 v[32:47], v[96:99], v[132:135], v[32:47]
	v_cvt_pk_bf16_f32 v100, v184, v185
	v_cvt_pk_bf16_f32 v101, v186, v187
	v_cvt_pk_bf16_f32 v102, v136, v137
	v_cvt_pk_bf16_f32 v103, v138, v139
	v_add_f32_e32 v14, v14, v164
	v_add_f32_e32 v14, v14, v165
	v_add_f32_e32 v14, v14, v166
	v_add_f32_e32 v14, v14, v167
	s_waitcnt lgkmcnt(5)
	v_mfma_f32_32x32x16_bf16 v[16:31], v[104:107], v[100:103], v[16:31]
	v_add_f32_e32 v14, v14, v184
	v_add_f32_e32 v14, v14, v185
	v_add_f32_e32 v14, v14, v186
	v_add_f32_e32 v14, v14, v187
	s_waitcnt lgkmcnt(4)
	v_mfma_f32_32x32x16_bf16 v[32:47], v[108:111], v[100:103], v[32:47]
	v_cvt_pk_bf16_f32 v96, v140, v141
	v_cvt_pk_bf16_f32 v97, v142, v143
	v_cvt_pk_bf16_f32 v98, v144, v145
	v_cvt_pk_bf16_f32 v99, v146, v147
	v_add_f32_e32 v14, v14, v136
	v_add_f32_e32 v14, v14, v137
	v_add_f32_e32 v14, v14, v138
	v_add_f32_e32 v14, v14, v139
	s_waitcnt lgkmcnt(3)
	v_mfma_f32_32x32x16_bf16 v[16:31], v[116:119], v[96:99], v[16:31]
	v_add_f32_e32 v14, v14, v140
	v_add_f32_e32 v14, v14, v141
	v_add_f32_e32 v14, v14, v142
	v_add_f32_e32 v14, v14, v143
	s_waitcnt lgkmcnt(2)
	v_mfma_f32_32x32x16_bf16 v[32:47], v[120:123], v[96:99], v[32:47]
	v_cvt_pk_bf16_f32 v100, v148, v149
	v_cvt_pk_bf16_f32 v101, v150, v151
	v_cvt_pk_bf16_f32 v102, v152, v153
	v_cvt_pk_bf16_f32 v103, v154, v155
	v_add_f32_e32 v14, v14, v144
	v_add_f32_e32 v14, v14, v145
	v_add_f32_e32 v14, v14, v146
	v_add_f32_e32 v14, v14, v147
	s_waitcnt lgkmcnt(1)
	v_mfma_f32_32x32x16_bf16 v[16:31], v[124:127], v[100:103], v[16:31]
	v_add_f32_e32 v14, v14, v148
	v_add_f32_e32 v14, v14, v149
	v_add_f32_e32 v14, v14, v150
	v_add_f32_e32 v14, v14, v151
	s_waitcnt lgkmcnt(0)
	v_mfma_f32_32x32x16_bf16 v[32:47], v[128:131], v[100:103], v[32:47]
	v_add_f32_e32 v14, v14, v152
	v_add_f32_e32 v14, v14, v153
	v_add_f32_e32 v14, v14, v154
	v_add_f32_e32 v14, v14, v155
	s_setprio 0
	ds_read_b128 v[116:119], v195 offset:27680
	ds_read_b128 v[124:127], v195 offset:32288
	ds_read_b128 v[128:131], v195 offset:27712
	ds_read_b128 v[132:135], v195 offset:27744
	ds_read_b128 v[136:139], v195 offset:32320
	ds_read_b128 v[140:143], v195 offset:32352
	s_cmp_lg_u32 s27, 4
	s_cselect_b32 s27, s34, 0
	s_waitcnt lgkmcnt(6)
	v_mfma_f32_32x32x16_bf16 v[152:167], v[240:243], v[180:183], v[48:63]
	v_exp_f32_e32 v15, v80
	v_exp_f32_e32 v144, v81
	v_exp_f32_e32 v145, v82
	v_exp_f32_e32 v146, v83
	s_waitcnt lgkmcnt(5)
	v_mfma_f32_32x32x16_bf16 v[96:111], v[244:247], v[180:183], v[48:63]
	v_exp_f32_e32 v147, v84
	v_exp_f32_e32 v148, v85
	v_exp_f32_e32 v149, v86
	v_exp_f32_e32 v150, v87
	v_mfma_f32_32x32x16_bf16 v[152:167], v[116:119], v[176:179], v[152:167]
	v_exp_f32_e32 v120, v88
	v_exp_f32_e32 v121, v89
	v_exp_f32_e32 v122, v90
	v_exp_f32_e32 v123, v91
	s_waitcnt lgkmcnt(4)
	v_mfma_f32_32x32x16_bf16 v[96:111], v[124:127], v[176:179], v[96:111]
	v_exp_f32_e32 v151, v92
	v_exp_f32_e32 v184, v93
	v_exp_f32_e32 v185, v94
	v_exp_f32_e32 v186, v95
	s_waitcnt lgkmcnt(3)
	v_mfma_f32_32x32x16_bf16 v[152:167], v[128:131], v[172:175], v[152:167]
	v_exp_f32_e32 v124, v64
	v_exp_f32_e32 v125, v65
	v_exp_f32_e32 v126, v66
	v_exp_f32_e32 v127, v67
	s_waitcnt lgkmcnt(1)
	v_mfma_f32_32x32x16_bf16 v[96:111], v[136:139], v[172:175], v[96:111]
	v_exp_f32_e32 v128, v68
	v_exp_f32_e32 v129, v69
	v_exp_f32_e32 v130, v70
	v_exp_f32_e32 v131, v71
	v_mfma_f32_32x32x16_bf16 v[152:167], v[132:135], v[168:171], v[152:167]
	v_exp_f32_e32 v136, v72
	v_exp_f32_e32 v137, v73
	v_exp_f32_e32 v138, v74
	v_exp_f32_e32 v139, v75
	s_waitcnt lgkmcnt(0)
	v_mfma_f32_32x32x16_bf16 v[96:111], v[140:143], v[168:171], v[96:111]
	v_exp_f32_e32 v132, v76
	v_exp_f32_e32 v133, v77
	v_exp_f32_e32 v134, v78
	v_exp_f32_e32 v135, v79
	s_cmp_gt_i32 s27, 2
	s_cselect_b32 s28, -3, 2
	s_add_i32 s28, s28, s27
	s_mulk_i32 s28, 0x2400
	s_waitcnt vmcnt(3)
	ds_write_b128 v208, v[6:9] offset:9216
	v_add_u32_e32 v6, s28, v208
	s_add_i32 s28, s27, 1
	s_cmp_lg_u32 s27, 4
	s_cselect_b32 s27, s28, 0
	s_add_i32 s28, s13, -1
	s_min_u32 s28, s28, s12
	s_lshl_b32 s92, s28, 13
	s_waitcnt vmcnt(2)
	ds_write_b128 v6, v[2:5] offset:36864
	s_add_u32 vcc_lo, s100, s92
	s_addc_u32 vcc_hi, s101, 0
	global_load_dwordx4 v[6:9], v248, vcc
	s_lshl_b32 s92, s29, 7
	s_add_u32 vcc_lo, s98, s92
	s_addc_u32 vcc_hi, s99, 0
	global_load_dwordx4 v[2:5], v249, vcc
	s_nop 0
	s_mul_i32 s29, s27, 0x2400
	s_add_i32 s34, s29, 0xffffdc00
	s_cmp_lg_u32 s27, 0
	s_cselect_b32 s34, s34, 0x9000
	v_add_u32_e32 v92, s34, v195
	ds_read_b128 v[64:67], v92 offset:36864
	ds_read_b128 v[68:71], v92 offset:36896
	ds_read_b128 v[72:75], v92 offset:41472
	ds_read_b128 v[76:79], v92 offset:41504
	ds_read_b128 v[80:83], v92 offset:36928
	ds_read_b128 v[84:87], v92 offset:36960
	ds_read_b128 v[88:91], v92 offset:41536
	ds_read_b128 v[92:95], v92 offset:41568
	s_setprio 3
	v_cvt_pk_bf16_f32 v116, v15, v144
	v_cvt_pk_bf16_f32 v117, v145, v146
	v_cvt_pk_bf16_f32 v118, v147, v148
	v_cvt_pk_bf16_f32 v119, v149, v150
	s_waitcnt lgkmcnt(7)
	s_nop 0
	v_mfma_f32_32x32x16_bf16 v[16:31], v[64:67], v[116:119], v[16:31]
	v_add_f32_e32 v187, v15, v144
	v_add_f32_e32 v187, v187, v145
	v_add_f32_e32 v187, v187, v146
	s_waitcnt lgkmcnt(5)
	v_mfma_f32_32x32x16_bf16 v[32:47], v[72:75], v[116:119], v[32:47]
	v_cvt_pk_bf16_f32 v64, v120, v121
	v_cvt_pk_bf16_f32 v65, v122, v123
	v_cvt_pk_bf16_f32 v66, v151, v184
	v_cvt_pk_bf16_f32 v67, v185, v186
	v_add_f32_e32 v187, v187, v147
	v_add_f32_e32 v187, v187, v148
	v_add_f32_e32 v187, v187, v149
	v_add_f32_e32 v187, v187, v150
	s_nop 0
	v_mfma_f32_32x32x16_bf16 v[16:31], v[68:71], v[64:67], v[16:31]
	v_add_f32_e32 v187, v187, v120
	v_add_f32_e32 v187, v187, v121
	v_add_f32_e32 v187, v187, v122
	v_add_f32_e32 v187, v187, v123
	s_waitcnt lgkmcnt(4)
	v_mfma_f32_32x32x16_bf16 v[32:47], v[76:79], v[64:67], v[32:47]
	v_cvt_pk_bf16_f32 v68, v124, v125
	v_cvt_pk_bf16_f32 v69, v126, v127
	v_cvt_pk_bf16_f32 v70, v128, v129
	v_cvt_pk_bf16_f32 v71, v130, v131
	v_add_f32_e32 v187, v187, v151
	v_add_f32_e32 v187, v187, v184
	v_add_f32_e32 v187, v187, v185
	v_add_f32_e32 v187, v187, v186
	s_waitcnt lgkmcnt(3)
	v_mfma_f32_32x32x16_bf16 v[16:31], v[80:83], v[68:71], v[16:31]
	v_add_f32_e32 v187, v187, v124
	v_add_f32_e32 v187, v187, v125
	v_add_f32_e32 v187, v187, v126
	v_add_f32_e32 v187, v187, v127
	s_waitcnt lgkmcnt(1)
	v_mfma_f32_32x32x16_bf16 v[32:47], v[88:91], v[68:71], v[32:47]
	v_cvt_pk_bf16_f32 v64, v136, v137
	v_cvt_pk_bf16_f32 v65, v138, v139
	v_cvt_pk_bf16_f32 v66, v132, v133
	v_cvt_pk_bf16_f32 v67, v134, v135
	v_add_f32_e32 v187, v187, v128
	v_add_f32_e32 v187, v187, v129
	v_add_f32_e32 v187, v187, v130
	v_add_f32_e32 v187, v187, v131
	s_nop 0
	v_mfma_f32_32x32x16_bf16 v[16:31], v[84:87], v[64:67], v[16:31]
	v_add_f32_e32 v187, v187, v136
	v_add_f32_e32 v187, v187, v137
	v_add_f32_e32 v187, v187, v138
	v_add_f32_e32 v187, v187, v139
	s_waitcnt lgkmcnt(0)
	v_mfma_f32_32x32x16_bf16 v[32:47], v[92:95], v[64:67], v[32:47]
	v_add_f32_e32 v187, v187, v132
	v_add_f32_e32 v187, v187, v133
	v_add_f32_e32 v187, v187, v134
	v_add_f32_e32 v187, v187, v135
	s_setprio 2
	s_waitcnt lgkmcnt(0)
	s_barrier
	ds_read_b128 v[240:243], v195
	ds_read_b128 v[244:247], v195 offset:4608
	ds_read_b128 v[72:75], v195 offset:32
	ds_read_b128 v[76:79], v195 offset:4640
	ds_read_b128 v[80:83], v195 offset:64
	ds_read_b128 v[84:87], v195 offset:4672
	ds_read_b128 v[88:91], v195 offset:96
	ds_read_b128 v[92:95], v195 offset:4704
	v_add_f32_e32 v1, v1, v14
	s_waitcnt lgkmcnt(6)
	v_mfma_f32_32x32x16_bf16 v[136:151], v[240:243], v[180:183], v[48:63]
	v_exp_f32_e32 v14, v152
	v_exp_f32_e32 v15, v153
	v_exp_f32_e32 v116, v154
	v_exp_f32_e32 v117, v155
	v_mfma_f32_32x32x16_bf16 v[120:135], v[244:247], v[180:183], v[48:63]
	v_exp_f32_e32 v118, v156
	v_exp_f32_e32 v119, v157
	v_exp_f32_e32 v184, v158
	v_exp_f32_e32 v185, v159
	s_waitcnt lgkmcnt(5)
	v_mfma_f32_32x32x16_bf16 v[136:151], v[72:75], v[176:179], v[136:151]
	v_exp_f32_e32 v186, v160
	v_exp_f32_e32 v210, v161
	v_exp_f32_e32 v211, v162
	v_exp_f32_e32 v212, v163
	s_waitcnt lgkmcnt(4)
	v_mfma_f32_32x32x16_bf16 v[120:135], v[76:79], v[176:179], v[120:135]
	v_exp_f32_e32 v160, v164
	v_exp_f32_e32 v161, v165
	v_exp_f32_e32 v162, v166
	v_exp_f32_e32 v163, v167
	s_waitcnt lgkmcnt(3)
	v_mfma_f32_32x32x16_bf16 v[136:151], v[80:83], v[172:175], v[136:151]
	v_exp_f32_e32 v164, v96
	v_exp_f32_e32 v165, v97
	v_exp_f32_e32 v166, v98
	v_exp_f32_e32 v167, v99
	s_waitcnt lgkmcnt(2)
	v_mfma_f32_32x32x16_bf16 v[120:135], v[84:87], v[172:175], v[120:135]
	v_exp_f32_e32 v96, v100
	v_exp_f32_e32 v97, v101
	v_exp_f32_e32 v98, v102
	v_exp_f32_e32 v99, v103
	s_waitcnt lgkmcnt(1)
	v_mfma_f32_32x32x16_bf16 v[136:151], v[88:91], v[168:171], v[136:151]
	v_exp_f32_e32 v100, v104
	v_exp_f32_e32 v101, v105
	v_exp_f32_e32 v102, v106
	v_exp_f32_e32 v103, v107
	s_waitcnt lgkmcnt(0)
	v_mfma_f32_32x32x16_bf16 v[120:135], v[92:95], v[168:171], v[120:135]
	v_exp_f32_e32 v104, v108
	v_exp_f32_e32 v105, v109
	v_exp_f32_e32 v106, v110
	v_exp_f32_e32 v107, v111
	s_cmp_gt_i32 s27, 2
	s_cselect_b32 s34, -3, 2
	s_add_i32 s34, s34, s27
	s_mulk_i32 s34, 0x2400
	v_add_u32_e32 v88, s29, v195
	s_min_u32 s29, s13, s12
	s_waitcnt vmcnt(3)
	ds_write_b128 v208, v[10:13] offset:18432
	v_add_u32_e32 v10, s34, v208
	s_lshl_b32 s92, s29, 13
	s_waitcnt vmcnt(2)
	ds_write_b128 v10, v[112:115] offset:36864
	s_add_u32 vcc_lo, s100, s92
	s_addc_u32 vcc_hi, s101, 0
	global_load_dwordx4 v[152:155], v248, vcc
	s_lshl_b32 s92, s28, 7
	s_add_u32 vcc_lo, s98, s92
	s_addc_u32 vcc_hi, s99, 0
	global_load_dwordx4 v[156:159], v249, vcc
	ds_read_b128 v[240:243], v195 offset:9216
	ds_read_b128 v[244:247], v195 offset:13824
	ds_read_b128 v[10:13], v88 offset:41472
	ds_read_b128 v[64:67], v88 offset:36864
	ds_read_b128 v[68:71], v88 offset:36896
	ds_read_b128 v[72:75], v88 offset:41504
	ds_read_b128 v[76:79], v88 offset:36928
	ds_read_b128 v[80:83], v88 offset:41536
	ds_read_b128 v[84:87], v88 offset:36960
	ds_read_b128 v[88:91], v88 offset:41568
	v_add_f32_e32 v1, v1, v187
	s_setprio 1
	v_mov_b32_e32 v109, v136
	v_cvt_pk_bf16_f32 v92, v14, v15
	v_cvt_pk_bf16_f32 v93, v116, v117
	v_cvt_pk_bf16_f32 v94, v118, v119
	v_cvt_pk_bf16_f32 v95, v184, v185
	s_waitcnt lgkmcnt(6)
	s_nop 0
	v_mfma_f32_32x32x16_bf16 v[16:31], v[64:67], v[92:95], v[16:31]
	v_max3_f32 v109, v109, v137, v138
	v_max3_f32 v109, v109, v139, v140
	v_add_f32_e32 v108, v14, v15
	v_add_f32_e32 v108, v108, v116
	v_add_f32_e32 v108, v108, v117
	s_nop 0
	v_mfma_f32_32x32x16_bf16 v[32:47], v[10:13], v[92:95], v[32:47]
	v_cvt_pk_bf16_f32 v64, v186, v210
	v_cvt_pk_bf16_f32 v65, v211, v212
	v_cvt_pk_bf16_f32 v66, v160, v161
	v_cvt_pk_bf16_f32 v67, v162, v163
	v_max3_f32 v109, v109, v141, v142
	v_max3_f32 v109, v109, v143, v144
	v_add_f32_e32 v108, v108, v118
	v_add_f32_e32 v108, v108, v119
	v_add_f32_e32 v108, v108, v184
	v_add_f32_e32 v108, v108, v185
	s_waitcnt lgkmcnt(5)
	v_mfma_f32_32x32x16_bf16 v[16:31], v[68:71], v[64:67], v[16:31]
	v_max3_f32 v109, v109, v145, v146
	v_max3_f32 v109, v109, v147, v148
	v_add_f32_e32 v108, v108, v186
	v_add_f32_e32 v108, v108, v210
	v_add_f32_e32 v108, v108, v211
	v_add_f32_e32 v108, v108, v212
	s_waitcnt lgkmcnt(4)
	v_mfma_f32_32x32x16_bf16 v[32:47], v[72:75], v[64:67], v[32:47]
	v_cvt_pk_bf16_f32 v10, v164, v165
	v_cvt_pk_bf16_f32 v11, v166, v167
	v_cvt_pk_bf16_f32 v12, v96, v97
	v_cvt_pk_bf16_f32 v13, v98, v99
	v_max3_f32 v109, v109, v149, v150
	v_max3_f32 v109, v109, v151, v120
	v_add_f32_e32 v108, v108, v160
	v_add_f32_e32 v108, v108, v161
	v_add_f32_e32 v108, v108, v162
	v_add_f32_e32 v108, v108, v163
	s_waitcnt lgkmcnt(3)
	v_mfma_f32_32x32x16_bf16 v[16:31], v[76:79], v[10:13], v[16:31]
	v_max3_f32 v109, v109, v121, v122
	v_max3_f32 v109, v109, v123, v124
	v_add_f32_e32 v108, v108, v164
	v_add_f32_e32 v108, v108, v165
	v_add_f32_e32 v108, v108, v166
	v_add_f32_e32 v108, v108, v167
	s_waitcnt lgkmcnt(2)
	v_mfma_f32_32x32x16_bf16 v[32:47], v[80:83], v[10:13], v[32:47]
	v_cvt_pk_bf16_f32 v64, v100, v101
	v_cvt_pk_bf16_f32 v65, v102, v103
	v_cvt_pk_bf16_f32 v66, v104, v105
	v_cvt_pk_bf16_f32 v67, v106, v107
	v_max3_f32 v109, v109, v125, v126
	v_max3_f32 v109, v109, v127, v128
	v_add_f32_e32 v108, v108, v96
	v_add_f32_e32 v108, v108, v97
	v_add_f32_e32 v108, v108, v98
	v_add_f32_e32 v108, v108, v99
	s_waitcnt lgkmcnt(1)
	v_mfma_f32_32x32x16_bf16 v[16:31], v[84:87], v[64:67], v[16:31]
	v_max3_f32 v109, v109, v129, v130
	v_max3_f32 v109, v109, v131, v132
	v_add_f32_e32 v108, v108, v100
	v_add_f32_e32 v108, v108, v101
	v_add_f32_e32 v108, v108, v102
	v_add_f32_e32 v108, v108, v103
	s_waitcnt lgkmcnt(0)
	v_mfma_f32_32x32x16_bf16 v[32:47], v[88:91], v[64:67], v[32:47]
	v_max3_f32 v109, v109, v133, v134
	v_max3_f32 v109, v109, v135, v135
	v_add_f32_e32 v108, v108, v104
	v_add_f32_e32 v108, v108, v105
	v_add_f32_e32 v108, v108, v106
	v_add_f32_e32 v108, v108, v107
	s_setprio 0
	ds_read_b128 v[164:167], v195 offset:9248
	ds_read_b128 v[160:163], v195 offset:13856
	ds_read_b128 v[74:77], v195 offset:9280
	ds_read_b128 v[66:69], v195 offset:9312
	ds_read_b128 v[70:73], v195 offset:13888
	ds_read_b128 v[10:13], v195 offset:13920
	v_add_f32_e32 v64, v1, v108
	v_mov_b32_e32 v1, v109
	s_nop 1
	v_permlane32_swap_b32_e32 v109, v1
	v_max_f32_e32 v1, v1, v1
	v_max_f32_e32 v14, v109, v109
	v_max_f32_e32 v1, v14, v1
	v_cmp_lt_f32_e32 vcc, s52, v1
	s_cbranch_vccz .LBB0_663
	v_max_f32_e32 v1, v1, v1
	v_max_f32_e32 v14, 0, v1
	v_add_f32_e32 v209, v209, v14
	v_xor_b32_e32 v48, 0x80000000, v209
	v_pk_add_f32 v[136:137], v[136:137], v[14:15] op_sel_hi:[1,0] neg_lo:[0,1] neg_hi:[0,1]
	v_pk_add_f32 v[120:121], v[120:121], v[14:15] op_sel_hi:[1,0] neg_lo:[0,1] neg_hi:[0,1]
	v_pk_add_f32 v[138:139], v[138:139], v[14:15] op_sel_hi:[1,0] neg_lo:[0,1] neg_hi:[0,1]
	v_pk_add_f32 v[122:123], v[122:123], v[14:15] op_sel_hi:[1,0] neg_lo:[0,1] neg_hi:[0,1]
	v_pk_add_f32 v[140:141], v[140:141], v[14:15] op_sel_hi:[1,0] neg_lo:[0,1] neg_hi:[0,1]
	v_pk_add_f32 v[124:125], v[124:125], v[14:15] op_sel_hi:[1,0] neg_lo:[0,1] neg_hi:[0,1]
	v_pk_add_f32 v[142:143], v[142:143], v[14:15] op_sel_hi:[1,0] neg_lo:[0,1] neg_hi:[0,1]
	v_pk_add_f32 v[126:127], v[126:127], v[14:15] op_sel_hi:[1,0] neg_lo:[0,1] neg_hi:[0,1]
	v_pk_add_f32 v[144:145], v[144:145], v[14:15] op_sel_hi:[1,0] neg_lo:[0,1] neg_hi:[0,1]
	v_pk_add_f32 v[128:129], v[128:129], v[14:15] op_sel_hi:[1,0] neg_lo:[0,1] neg_hi:[0,1]
	v_pk_add_f32 v[146:147], v[146:147], v[14:15] op_sel_hi:[1,0] neg_lo:[0,1] neg_hi:[0,1]
	v_pk_add_f32 v[130:131], v[130:131], v[14:15] op_sel_hi:[1,0] neg_lo:[0,1] neg_hi:[0,1]
	v_pk_add_f32 v[148:149], v[148:149], v[14:15] op_sel_hi:[1,0] neg_lo:[0,1] neg_hi:[0,1]
	v_pk_add_f32 v[132:133], v[132:133], v[14:15] op_sel_hi:[1,0] neg_lo:[0,1] neg_hi:[0,1]
	v_pk_add_f32 v[150:151], v[150:151], v[14:15] op_sel_hi:[1,0] neg_lo:[0,1] neg_hi:[0,1]
	v_pk_add_f32 v[134:135], v[134:135], v[14:15] op_sel_hi:[1,0] neg_lo:[0,1] neg_hi:[0,1]
	v_exp_f32_e64 v14, -v14
	v_mov_b32_e32 v49, v48
	v_mov_b32_e32 v50, v48
	v_mov_b32_e32 v51, v48
	v_mov_b32_e32 v52, v48
	v_mov_b32_e32 v53, v48
	v_mov_b32_e32 v54, v48
	v_mov_b32_e32 v55, v48
	v_mov_b32_e32 v56, v48
	v_mov_b32_e32 v57, v48
	v_mov_b32_e32 v58, v48
	v_mov_b32_e32 v59, v48
	v_mov_b32_e32 v60, v48
	v_mov_b32_e32 v61, v48
	v_mov_b32_e32 v62, v48
	v_mov_b32_e32 v63, v48
	s_nop 11
	v_pk_mul_f32 v[30:31], v[30:31], v[14:15] op_sel_hi:[1,0]
	v_pk_mul_f32 v[28:29], v[28:29], v[14:15] op_sel_hi:[1,0]
	v_pk_mul_f32 v[26:27], v[26:27], v[14:15] op_sel_hi:[1,0]
	v_pk_mul_f32 v[24:25], v[24:25], v[14:15] op_sel_hi:[1,0]
	v_pk_mul_f32 v[22:23], v[22:23], v[14:15] op_sel_hi:[1,0]
	v_pk_mul_f32 v[20:21], v[20:21], v[14:15] op_sel_hi:[1,0]
	v_pk_mul_f32 v[18:19], v[18:19], v[14:15] op_sel_hi:[1,0]
	v_pk_mul_f32 v[16:17], v[16:17], v[14:15] op_sel_hi:[1,0]
	v_pk_mul_f32 v[46:47], v[46:47], v[14:15] op_sel_hi:[1,0]
	v_pk_mul_f32 v[44:45], v[44:45], v[14:15] op_sel_hi:[1,0]
	v_pk_mul_f32 v[42:43], v[42:43], v[14:15] op_sel_hi:[1,0]
	v_pk_mul_f32 v[40:41], v[40:41], v[14:15] op_sel_hi:[1,0]
	v_pk_mul_f32 v[38:39], v[38:39], v[14:15] op_sel_hi:[1,0]
	v_pk_mul_f32 v[36:37], v[36:37], v[14:15] op_sel_hi:[1,0]
	v_pk_mul_f32 v[34:35], v[34:35], v[14:15] op_sel_hi:[1,0]
	v_pk_mul_f32 v[32:33], v[32:33], v[14:15] op_sel_hi:[1,0]
	v_mul_f32_e32 v64, v64, v14

.LBB0_697:
	s_add_i32 s22, s45, s18
	s_ashr_i32 s23, s22, 31
	s_lshl_b64 s[24:25], s[22:23], 13
	s_lshl_b32 s22, s22, 6
	v_lshl_add_u64 v[2:3], v[198:199], 0, s[24:25]
	s_sub_i32 s24, s22, 64
	s_ashr_i32 s25, s24, 31
	v_lshl_add_u64 v[4:5], s[24:25], 1, v[196:197]
	global_load_dwordx4 v[6:9], v[2:3], off
	s_nop 0
	global_load_dwordx4 v[2:5], v[4:5], off
	s_mul_i32 s2, s34, 0x2400
	s_add_i32 s23, s2, 0xffffdc00
	s_cmp_lg_u32 s34, 0
	s_cselect_b32 s23, s23, 0x9000
	v_add_u32_e32 v1, s23, v201
	ds_read_b128 v[10:13], v1 offset:36864
	ds_read_b128 v[66:69], v1 offset:36896
	ds_read_b128 v[70:73], v1 offset:41472
	ds_read_b128 v[74:77], v1 offset:41504
	ds_read_b128 v[128:131], v1 offset:36928
	ds_read_b128 v[132:135], v1 offset:36960
	ds_read_b128 v[136:139], v1 offset:41536
	ds_read_b128 v[142:145], v1 offset:41568
	s_setprio 3
	v_cvt_pk_bf16_f32 v178, v116, v117
	v_cvt_pk_bf16_f32 v179, v118, v119
	v_cvt_pk_bf16_f32 v180, v112, v113
	v_cvt_pk_bf16_f32 v181, v114, v115
	s_waitcnt lgkmcnt(7)
	s_nop 0
	v_mfma_f32_32x32x16_bf16 v[16:31], v[10:13], v[178:181], v[16:31]
	v_add_f32_e32 v1, v116, v117
	v_add_f32_e32 v1, v1, v118
	v_add_f32_e32 v1, v1, v119
	s_waitcnt lgkmcnt(5)
	v_mfma_f32_32x32x16_bf16 v[32:47], v[70:73], v[178:181], v[32:47]
	v_cvt_pk_bf16_f32 v10, v208, v207
	v_cvt_pk_bf16_f32 v11, v206, v205
	v_cvt_pk_bf16_f32 v12, v204, v187
	v_cvt_pk_bf16_f32 v13, v186, v185
	v_add_f32_e32 v1, v1, v112
	v_add_f32_e32 v1, v1, v113
	v_add_f32_e32 v1, v1, v114
	v_add_f32_e32 v1, v1, v115
	s_nop 0
	v_mfma_f32_32x32x16_bf16 v[16:31], v[66:69], v[10:13], v[16:31]
	v_add_f32_e32 v1, v1, v208
	v_add_f32_e32 v1, v1, v207
	v_add_f32_e32 v1, v1, v206
	v_add_f32_e32 v1, v1, v205
	s_waitcnt lgkmcnt(4)
	v_mfma_f32_32x32x16_bf16 v[32:47], v[74:77], v[10:13], v[32:47]
	v_cvt_pk_bf16_f32 v66, v177, v176
	v_cvt_pk_bf16_f32 v67, v149, v148
	v_cvt_pk_bf16_f32 v68, v147, v146
	v_cvt_pk_bf16_f32 v69, v141, v140
	v_add_f32_e32 v1, v1, v204
	v_add_f32_e32 v1, v1, v187
	v_add_f32_e32 v1, v1, v186
	v_add_f32_e32 v1, v1, v185
	s_waitcnt lgkmcnt(3)
	v_mfma_f32_32x32x16_bf16 v[16:31], v[128:131], v[66:69], v[16:31]
	v_add_f32_e32 v1, v1, v177
	v_add_f32_e32 v1, v1, v176
	v_add_f32_e32 v1, v1, v149
	v_add_f32_e32 v1, v1, v148
	s_waitcnt lgkmcnt(1)
	v_mfma_f32_32x32x16_bf16 v[32:47], v[136:139], v[66:69], v[32:47]
	v_cvt_pk_bf16_f32 v10, v123, v122
	v_cvt_pk_bf16_f32 v11, v121, v120
	v_cvt_pk_bf16_f32 v12, v127, v126
	v_cvt_pk_bf16_f32 v13, v125, v124
	v_add_f32_e32 v1, v1, v147
	v_add_f32_e32 v1, v1, v146
	v_add_f32_e32 v1, v1, v141
	v_add_f32_e32 v1, v1, v140
	s_nop 0
	v_mfma_f32_32x32x16_bf16 v[16:31], v[132:135], v[10:13], v[16:31]
	v_add_f32_e32 v1, v1, v123
	v_add_f32_e32 v1, v1, v122
	v_add_f32_e32 v1, v1, v121
	v_add_f32_e32 v1, v1, v120
	s_waitcnt lgkmcnt(0)
	v_mfma_f32_32x32x16_bf16 v[32:47], v[142:145], v[10:13], v[32:47]
	v_add_f32_e32 v1, v1, v127
	v_add_f32_e32 v1, v1, v126
	v_add_f32_e32 v1, v1, v125
	v_add_f32_e32 v1, v1, v124
	s_setprio 2
	s_waitcnt lgkmcnt(0)
	s_barrier
	ds_read_b128 v[240:243], v201 offset:18432
	ds_read_b128 v[244:247], v201 offset:23040
	ds_read_b128 v[66:69], v201 offset:18464
	ds_read_b128 v[76:79], v201 offset:23072
	ds_read_b128 v[144:147], v201 offset:18496
	ds_read_b128 v[176:179], v201 offset:18528
	ds_read_b128 v[204:207], v201 offset:23104
	ds_read_b128 v[208:211], v201 offset:23136
	s_waitcnt lgkmcnt(6)
	v_mfma_f32_32x32x16_bf16 v[128:143], v[240:243], v[164:167], v[48:63]
	v_exp_f32_e32 v148, v96
	v_exp_f32_e32 v149, v97
	v_exp_f32_e32 v150, v98
	v_exp_f32_e32 v151, v99
	s_waitcnt lgkmcnt(5)
	v_mfma_f32_32x32x16_bf16 v[112:127], v[244:247], v[164:167], v[48:63]
	v_exp_f32_e32 v96, v100
	v_exp_f32_e32 v97, v101
	v_exp_f32_e32 v98, v102
	v_exp_f32_e32 v99, v103
	v_mfma_f32_32x32x16_bf16 v[128:143], v[66:69], v[160:163], v[128:143]
	v_exp_f32_e32 v100, v104
	v_exp_f32_e32 v101, v105
	v_exp_f32_e32 v102, v106
	v_exp_f32_e32 v103, v107
	s_waitcnt lgkmcnt(4)
	v_mfma_f32_32x32x16_bf16 v[112:127], v[76:79], v[160:163], v[112:127]
	v_exp_f32_e32 v71, v108
	v_exp_f32_e32 v72, v109
	v_exp_f32_e32 v73, v110
	v_exp_f32_e32 v74, v111
	s_waitcnt lgkmcnt(3)
	v_mfma_f32_32x32x16_bf16 v[128:143], v[144:147], v[156:159], v[128:143]
	v_exp_f32_e32 v75, v80
	v_exp_f32_e32 v76, v81
	v_exp_f32_e32 v77, v82
	v_exp_f32_e32 v78, v83
	s_waitcnt lgkmcnt(1)
	v_mfma_f32_32x32x16_bf16 v[112:127], v[204:207], v[156:159], v[112:127]
	v_exp_f32_e32 v14, v84
	v_exp_f32_e32 v15, v85
	v_exp_f32_e32 v65, v86
	v_exp_f32_e32 v66, v87
	v_mfma_f32_32x32x16_bf16 v[128:143], v[176:179], v[152:155], v[128:143]
	v_exp_f32_e32 v67, v88
	v_exp_f32_e32 v68, v89
	v_exp_f32_e32 v69, v90
	v_exp_f32_e32 v70, v91
	s_waitcnt lgkmcnt(0)
	v_mfma_f32_32x32x16_bf16 v[112:127], v[208:211], v[152:155], v[112:127]
	v_exp_f32_e32 v79, v92
	v_exp_f32_e32 v80, v93
	v_exp_f32_e32 v81, v94
	v_exp_f32_e32 v82, v95
	s_cmp_lt_u32 s45, 3
	s_cbranch_scc1 .LBB0_699
	s_add_i32 s23, s19, s45
	v_lshl_add_u32 v10, s23, 6, v184
	v_add_u32_e32 v11, 0xffffff7f, v10
	v_cmp_lt_u32_e32 vcc, s53, v11
	v_add_u32_e32 v11, 0xffffff9f, v10
	s_nop 7
	s_nop 3
	s_nop 0
	v_cndmask_b32_e32 v128, v233, v128, vcc
	v_cmp_lt_u32_e32 vcc, s53, v11
	v_add_u32_e32 v11, 0xffffff80, v10
	s_nop 0
	v_cndmask_b32_e32 v112, v233, v112, vcc
	v_cmp_lt_u32_e32 vcc, s53, v11
	v_add_u32_e32 v11, 0xffffffa0, v10
	s_nop 0
	v_cndmask_b32_e32 v129, v233, v129, vcc
	v_cmp_lt_u32_e32 vcc, s53, v11
	v_add_u32_e32 v11, 0xffffff81, v10
	s_nop 0
	v_cndmask_b32_e32 v113, v233, v113, vcc
	v_cmp_lt_u32_e32 vcc, s53, v11
	v_add_u32_e32 v11, 0xffffffa1, v10
	s_nop 0
	v_cndmask_b32_e32 v130, v233, v130, vcc
	v_cmp_lt_u32_e32 vcc, s53, v11
	v_add_u32_e32 v11, 0xffffff82, v10
	s_nop 0
	v_cndmask_b32_e32 v114, v233, v114, vcc
	v_cmp_lt_u32_e32 vcc, s53, v11
	v_add_u32_e32 v11, 0xffffffa2, v10
	s_nop 0
	v_cndmask_b32_e32 v131, v233, v131, vcc
	v_cmp_lt_u32_e32 vcc, s53, v11
	v_add_u32_e32 v11, 0xffffff87, v10
	s_nop 0
	v_cndmask_b32_e32 v115, v233, v115, vcc
	v_cmp_lt_u32_e32 vcc, s53, v11
	v_add_u32_e32 v11, 0xffffffa7, v10
	s_nop 0
	v_cndmask_b32_e32 v132, v233, v132, vcc
	v_cmp_lt_u32_e32 vcc, s53, v11
	v_add_u32_e32 v11, 0xffffff88, v10
	s_nop 0
	v_cndmask_b32_e32 v116, v233, v116, vcc
	v_cmp_lt_u32_e32 vcc, s53, v11
	v_add_u32_e32 v11, 0xffffffa8, v10
	s_nop 0
	v_cndmask_b32_e32 v133, v233, v133, vcc
	v_cmp_lt_u32_e32 vcc, s53, v11
	v_add_u32_e32 v11, 0xffffff89, v10
	s_nop 0
	v_cndmask_b32_e32 v117, v233, v117, vcc
	v_cmp_lt_u32_e32 vcc, s53, v11
	v_add_u32_e32 v11, 0xffffffa9, v10
	s_nop 0
	v_cndmask_b32_e32 v134, v233, v134, vcc
	v_cmp_lt_u32_e32 vcc, s53, v11
	v_add_u32_e32 v11, 0xffffff8a, v10
	s_nop 0
	v_cndmask_b32_e32 v118, v233, v118, vcc
	v_cmp_lt_u32_e32 vcc, s53, v11
	v_add_u32_e32 v11, 0xffffffaa, v10
	s_nop 0
	v_cndmask_b32_e32 v135, v233, v135, vcc
	v_cmp_lt_u32_e32 vcc, s53, v11
	v_add_u32_e32 v11, 0xffffff8f, v10
	s_nop 0
	v_cndmask_b32_e32 v119, v233, v119, vcc
	v_cmp_lt_u32_e32 vcc, s53, v11
	v_add_u32_e32 v11, 0xffffffaf, v10
	s_nop 0
	v_cndmask_b32_e32 v136, v233, v136, vcc
	v_cmp_lt_u32_e32 vcc, s53, v11
	v_add_u32_e32 v11, 0xffffff90, v10
	s_nop 0
	v_cndmask_b32_e32 v120, v233, v120, vcc
	v_cmp_lt_u32_e32 vcc, s53, v11
	v_add_u32_e32 v11, 0xffffffb0, v10
	s_nop 0
	v_cndmask_b32_e32 v137, v233, v137, vcc
	v_cmp_lt_u32_e32 vcc, s53, v11
	v_add_u32_e32 v11, 0xffffff91, v10
	s_nop 0
	v_cndmask_b32_e32 v121, v233, v121, vcc
	v_cmp_lt_u32_e32 vcc, s53, v11
	v_add_u32_e32 v11, 0xffffffb1, v10
	s_nop 0
	v_cndmask_b32_e32 v138, v233, v138, vcc
	v_cmp_lt_u32_e32 vcc, s53, v11
	v_add_u32_e32 v11, 0xffffff92, v10
	s_nop 0
	v_cndmask_b32_e32 v122, v233, v122, vcc
	v_cmp_lt_u32_e32 vcc, s53, v11
	v_add_u32_e32 v11, 0xffffffb2, v10
	s_nop 0
	v_cndmask_b32_e32 v139, v233, v139, vcc
	v_cmp_lt_u32_e32 vcc, s53, v11
	v_add_u32_e32 v11, 0xffffff97, v10
	s_nop 0
	v_cndmask_b32_e32 v123, v233, v123, vcc
	v_cmp_lt_u32_e32 vcc, s53, v11
	v_add_u32_e32 v11, 0xffffffb7, v10
	s_nop 0
	v_cndmask_b32_e32 v140, v233, v140, vcc
	v_cmp_lt_u32_e32 vcc, s53, v11
	v_add_u32_e32 v11, 0xffffff98, v10
	s_nop 0
	v_cndmask_b32_e32 v124, v233, v124, vcc
	v_cmp_lt_u32_e32 vcc, s53, v11
	v_add_u32_e32 v11, 0xffffffb8, v10
	s_nop 0
	v_cndmask_b32_e32 v141, v233, v141, vcc
	v_cmp_lt_u32_e32 vcc, s53, v11
	v_add_u32_e32 v11, 0xffffff99, v10
	s_nop 0
	v_cndmask_b32_e32 v125, v233, v125, vcc
	v_cmp_lt_u32_e32 vcc, s53, v11
	v_add_u32_e32 v11, 0xffffffb9, v10
	s_nop 0
	v_cndmask_b32_e32 v142, v233, v142, vcc
	v_cmp_lt_u32_e32 vcc, s53, v11
	v_add_u32_e32 v11, 0xffffff9a, v10
	v_add_u32_e32 v10, 0xffffffba, v10
	v_cndmask_b32_e32 v126, v233, v126, vcc
	v_cmp_lt_u32_e32 vcc, s53, v11
	s_nop 1
	v_cndmask_b32_e32 v143, v233, v143, vcc
	v_cmp_lt_u32_e32 vcc, s53, v10
	s_nop 1
	v_cndmask_b32_e32 v127, v233, v127, vcc
.LBB0_699:
	s_cmp_gt_i32 s34, 2
	s_cselect_b32 s23, -3, 2
	s_add_i32 s87, s45, 5
	s_add_i32 s23, s23, s34
	s_add_i32 s26, s87, s13
	s_mulk_i32 s23, 0x2400
	s_ashr_i32 s27, s26, 31
	v_add_u32_e32 v10, s23, v203
	s_lshl_b64 vcc, s[26:27], 13
	s_waitcnt vmcnt(3)
	ds_write_b128 v203, v[168:171]
	s_waitcnt vmcnt(2)
	ds_write_b128 v10, v[172:175] offset:36864
	v_lshl_add_u64 v[10:11], v[198:199], 0, vcc
	s_ashr_i32 s23, s22, 31
	global_load_dwordx4 v[144:147], v[10:11], off
	v_lshl_add_u64 v[10:11], s[22:23], 1, v[196:197]
	global_load_dwordx4 v[10:13], v[10:11], off
	v_add_u32_e32 v83, s2, v201
	ds_read_b128 v[240:243], v201 offset:27648
	ds_read_b128 v[244:247], v201 offset:32256
	ds_read_b128 v[84:87], v83 offset:41472
	ds_read_b128 v[88:91], v83 offset:36864
	ds_read_b128 v[92:95], v83 offset:36896
	ds_read_b128 v[104:107], v83 offset:41504
	ds_read_b128 v[108:111], v83 offset:36928
	ds_read_b128 v[170:173], v83 offset:41536
	ds_read_b128 v[174:177], v83 offset:36960
	ds_read_b128 v[178:181], v83 offset:41568
	s_setprio 1
	v_cvt_pk_bf16_f32 v204, v148, v149
	v_cvt_pk_bf16_f32 v205, v150, v151
	v_cvt_pk_bf16_f32 v206, v96, v97
	v_cvt_pk_bf16_f32 v207, v98, v99
	s_waitcnt lgkmcnt(6)
	s_nop 0
	v_mfma_f32_32x32x16_bf16 v[16:31], v[88:91], v[204:207], v[16:31]
	v_add_f32_e32 v168, v148, v149
	v_add_f32_e32 v168, v168, v150
	v_add_f32_e32 v168, v168, v151
	s_nop 0
	v_mfma_f32_32x32x16_bf16 v[32:47], v[84:87], v[204:207], v[32:47]
	v_cvt_pk_bf16_f32 v88, v100, v101
	v_cvt_pk_bf16_f32 v89, v102, v103
	v_cvt_pk_bf16_f32 v90, v71, v72
	v_cvt_pk_bf16_f32 v91, v73, v74
	v_add_f32_e32 v168, v168, v96
	v_add_f32_e32 v168, v168, v97
	v_add_f32_e32 v168, v168, v98
	v_add_f32_e32 v168, v168, v99
	s_waitcnt lgkmcnt(5)
	v_mfma_f32_32x32x16_bf16 v[16:31], v[92:95], v[88:91], v[16:31]
	v_add_f32_e32 v168, v168, v100
	v_add_f32_e32 v168, v168, v101
	v_add_f32_e32 v168, v168, v102
	v_add_f32_e32 v168, v168, v103
	s_waitcnt lgkmcnt(4)
	v_mfma_f32_32x32x16_bf16 v[32:47], v[104:107], v[88:91], v[32:47]
	v_cvt_pk_bf16_f32 v84, v75, v76
	v_cvt_pk_bf16_f32 v85, v77, v78
	v_cvt_pk_bf16_f32 v86, v14, v15
	v_cvt_pk_bf16_f32 v87, v65, v66
	v_add_f32_e32 v168, v168, v71
	v_add_f32_e32 v168, v168, v72
	v_add_f32_e32 v168, v168, v73
	v_add_f32_e32 v168, v168, v74
	s_waitcnt lgkmcnt(3)
	v_mfma_f32_32x32x16_bf16 v[16:31], v[108:111], v[84:87], v[16:31]
	v_add_f32_e32 v168, v168, v75
	v_add_f32_e32 v168, v168, v76
	v_add_f32_e32 v168, v168, v77
	v_add_f32_e32 v168, v168, v78
	s_waitcnt lgkmcnt(2)
	v_mfma_f32_32x32x16_bf16 v[32:47], v[170:173], v[84:87], v[32:47]
	v_cvt_pk_bf16_f32 v72, v67, v68
	v_cvt_pk_bf16_f32 v73, v69, v70
	v_cvt_pk_bf16_f32 v74, v79, v80
	v_cvt_pk_bf16_f32 v75, v81, v82
	v_add_f32_e32 v168, v168, v14
	v_add_f32_e32 v168, v168, v15
	v_add_f32_e32 v168, v168, v65
	v_add_f32_e32 v168, v168, v66
	s_waitcnt lgkmcnt(1)
	v_mfma_f32_32x32x16_bf16 v[16:31], v[174:177], v[72:75], v[16:31]
	v_add_f32_e32 v168, v168, v67
	v_add_f32_e32 v168, v168, v68
	v_add_f32_e32 v168, v168, v69
	v_add_f32_e32 v168, v168, v70
	s_waitcnt lgkmcnt(0)
	v_mfma_f32_32x32x16_bf16 v[32:47], v[178:181], v[72:75], v[32:47]
	v_add_f32_e32 v168, v168, v79
	v_add_f32_e32 v168, v168, v80
	v_add_f32_e32 v168, v168, v81
	v_add_f32_e32 v168, v168, v82
	s_setprio 0
	ds_read_b128 v[70:73], v201 offset:27680
	ds_read_b128 v[170:173], v201 offset:32288
	ds_read_b128 v[174:177], v201 offset:27712
	ds_read_b128 v[178:181], v201 offset:27744
	ds_read_b128 v[204:207], v201 offset:32320
	ds_read_b128 v[208:211], v201 offset:32352
	s_waitcnt lgkmcnt(6)
	v_mfma_f32_32x32x16_bf16 v[96:111], v[240:243], v[164:167], v[48:63]
	v_exp_f32_e32 v148, v128
	v_exp_f32_e32 v149, v129
	v_exp_f32_e32 v150, v130
	v_exp_f32_e32 v151, v131
	s_waitcnt lgkmcnt(5)
	v_mfma_f32_32x32x16_bf16 v[80:95], v[244:247], v[164:167], v[48:63]
	v_exp_f32_e32 v128, v132
	v_exp_f32_e32 v129, v133
	v_exp_f32_e32 v130, v134
	v_exp_f32_e32 v131, v135
	v_mfma_f32_32x32x16_bf16 v[96:111], v[70:73], v[160:163], v[96:111]
	v_exp_f32_e32 v132, v136
	v_exp_f32_e32 v133, v137
	v_exp_f32_e32 v134, v138
	v_exp_f32_e32 v135, v139
	s_waitcnt lgkmcnt(4)
	v_mfma_f32_32x32x16_bf16 v[80:95], v[170:173], v[160:163], v[80:95]
	v_exp_f32_e32 v71, v140
	v_exp_f32_e32 v72, v141
	v_exp_f32_e32 v73, v142
	v_exp_f32_e32 v74, v143
	s_waitcnt lgkmcnt(3)
	v_mfma_f32_32x32x16_bf16 v[96:111], v[174:177], v[156:159], v[96:111]
	v_exp_f32_e32 v75, v112
	v_exp_f32_e32 v76, v113
	v_exp_f32_e32 v77, v114
	v_exp_f32_e32 v78, v115
	s_waitcnt lgkmcnt(1)
	v_mfma_f32_32x32x16_bf16 v[80:95], v[204:207], v[156:159], v[80:95]
	v_exp_f32_e32 v14, v116
	v_exp_f32_e32 v15, v117
	v_exp_f32_e32 v65, v118
	v_exp_f32_e32 v66, v119
	v_mfma_f32_32x32x16_bf16 v[96:111], v[178:181], v[152:155], v[96:111]
	v_exp_f32_e32 v67, v120
	v_exp_f32_e32 v68, v121
	v_exp_f32_e32 v69, v122
	v_exp_f32_e32 v70, v123
	s_waitcnt lgkmcnt(0)
	v_mfma_f32_32x32x16_bf16 v[80:95], v[208:211], v[152:155], v[80:95]
	v_exp_f32_e32 v79, v124
	v_exp_f32_e32 v112, v125
	v_exp_f32_e32 v113, v126
	v_exp_f32_e32 v114, v127
	s_cmp_lt_u32 s45, 2
	s_cbranch_scc1 .LBB0_701
	s_add_i32 s2, s22, 0x80
	v_add_u32_e32 v115, s2, v184
	v_add_u32_e32 v116, 0xffffff7f, v115
	v_cmp_lt_u32_e32 vcc, s53, v116
	v_add_u32_e32 v116, 0xffffff9f, v115
	s_nop 7
	s_nop 3
	s_nop 0
	v_cndmask_b32_e32 v96, v233, v96, vcc
	v_cmp_lt_u32_e32 vcc, s53, v116
	v_add_u32_e32 v116, 0xffffff80, v115
	s_nop 0
	v_cndmask_b32_e32 v80, v233, v80, vcc
	v_cmp_lt_u32_e32 vcc, s53, v116
	v_add_u32_e32 v116, 0xffffffa0, v115
	s_nop 0
	v_cndmask_b32_e32 v97, v233, v97, vcc
	v_cmp_lt_u32_e32 vcc, s53, v116
	v_add_u32_e32 v116, 0xffffff81, v115
	s_nop 0
	v_cndmask_b32_e32 v81, v233, v81, vcc
	v_cmp_lt_u32_e32 vcc, s53, v116
	v_add_u32_e32 v116, 0xffffffa1, v115
	s_nop 0
	v_cndmask_b32_e32 v98, v233, v98, vcc
	v_cmp_lt_u32_e32 vcc, s53, v116
	v_add_u32_e32 v116, 0xffffff82, v115
	s_nop 0
	v_cndmask_b32_e32 v82, v233, v82, vcc
	v_cmp_lt_u32_e32 vcc, s53, v116
	v_add_u32_e32 v116, 0xffffffa2, v115
	s_nop 0
	v_cndmask_b32_e32 v99, v233, v99, vcc
	v_cmp_lt_u32_e32 vcc, s53, v116
	v_add_u32_e32 v116, 0xffffff87, v115
	s_nop 0
	v_cndmask_b32_e32 v83, v233, v83, vcc
	v_cmp_lt_u32_e32 vcc, s53, v116
	v_add_u32_e32 v116, 0xffffffa7, v115
	s_nop 0
	v_cndmask_b32_e32 v100, v233, v100, vcc
	v_cmp_lt_u32_e32 vcc, s53, v116
	v_add_u32_e32 v116, 0xffffff88, v115
	s_nop 0
	v_cndmask_b32_e32 v84, v233, v84, vcc
	v_cmp_lt_u32_e32 vcc, s53, v116
	v_add_u32_e32 v116, 0xffffffa8, v115
	s_nop 0
	v_cndmask_b32_e32 v101, v233, v101, vcc
	v_cmp_lt_u32_e32 vcc, s53, v116
	v_add_u32_e32 v116, 0xffffff89, v115
	s_nop 0
	v_cndmask_b32_e32 v85, v233, v85, vcc
	v_cmp_lt_u32_e32 vcc, s53, v116
	v_add_u32_e32 v116, 0xffffffa9, v115
	s_nop 0
	v_cndmask_b32_e32 v102, v233, v102, vcc
	v_cmp_lt_u32_e32 vcc, s53, v116
	v_add_u32_e32 v116, 0xffffff8a, v115
	s_nop 0
	v_cndmask_b32_e32 v86, v233, v86, vcc
	v_cmp_lt_u32_e32 vcc, s53, v116
	v_add_u32_e32 v116, 0xffffffaa, v115
	s_nop 0
	v_cndmask_b32_e32 v103, v233, v103, vcc
	v_cmp_lt_u32_e32 vcc, s53, v116
	v_add_u32_e32 v116, 0xffffff8f, v115
	s_nop 0
	v_cndmask_b32_e32 v87, v233, v87, vcc
	v_cmp_lt_u32_e32 vcc, s53, v116
	v_add_u32_e32 v116, 0xffffffaf, v115
	s_nop 0
	v_cndmask_b32_e32 v104, v233, v104, vcc
	v_cmp_lt_u32_e32 vcc, s53, v116
	v_add_u32_e32 v116, 0xffffff90, v115
	s_nop 0
	v_cndmask_b32_e32 v88, v233, v88, vcc
	v_cmp_lt_u32_e32 vcc, s53, v116
	v_add_u32_e32 v116, 0xffffffb0, v115
	s_nop 0
	v_cndmask_b32_e32 v105, v233, v105, vcc
	v_cmp_lt_u32_e32 vcc, s53, v116
	v_add_u32_e32 v116, 0xffffff91, v115
	s_nop 0
	v_cndmask_b32_e32 v89, v233, v89, vcc
	v_cmp_lt_u32_e32 vcc, s53, v116
	v_add_u32_e32 v116, 0xffffffb1, v115
	s_nop 0
	v_cndmask_b32_e32 v106, v233, v106, vcc
	v_cmp_lt_u32_e32 vcc, s53, v116
	v_add_u32_e32 v116, 0xffffff92, v115
	s_nop 0
	v_cndmask_b32_e32 v90, v233, v90, vcc
	v_cmp_lt_u32_e32 vcc, s53, v116
	v_add_u32_e32 v116, 0xffffffb2, v115
	s_nop 0
	v_cndmask_b32_e32 v107, v233, v107, vcc
	v_cmp_lt_u32_e32 vcc, s53, v116
	v_add_u32_e32 v116, 0xffffff97, v115
	s_nop 0
	v_cndmask_b32_e32 v91, v233, v91, vcc
	v_cmp_lt_u32_e32 vcc, s53, v116
	v_add_u32_e32 v116, 0xffffffb7, v115
	s_nop 0
	v_cndmask_b32_e32 v108, v233, v108, vcc
	v_cmp_lt_u32_e32 vcc, s53, v116
	v_add_u32_e32 v116, 0xffffff98, v115
	s_nop 0
	v_cndmask_b32_e32 v92, v233, v92, vcc
	v_cmp_lt_u32_e32 vcc, s53, v116
	v_add_u32_e32 v116, 0xffffffb8, v115
	s_nop 0
	v_cndmask_b32_e32 v109, v233, v109, vcc
	v_cmp_lt_u32_e32 vcc, s53, v116
	v_add_u32_e32 v116, 0xffffff99, v115
	s_nop 0
	v_cndmask_b32_e32 v93, v233, v93, vcc
	v_cmp_lt_u32_e32 vcc, s53, v116
	v_add_u32_e32 v116, 0xffffffb9, v115
	s_nop 0
	v_cndmask_b32_e32 v110, v233, v110, vcc
	v_cmp_lt_u32_e32 vcc, s53, v116
	v_add_u32_e32 v116, 0xffffff9a, v115
	v_add_u32_e32 v115, 0xffffffba, v115
	v_cndmask_b32_e32 v94, v233, v94, vcc
	v_cmp_lt_u32_e32 vcc, s53, v116
	s_nop 1
	v_cndmask_b32_e32 v111, v233, v111, vcc
	v_cmp_lt_u32_e32 vcc, s53, v115
	s_nop 1
	v_cndmask_b32_e32 v95, v233, v95, vcc
.LBB0_701:
	s_add_i32 s2, s34, 1
	s_cmp_lg_u32 s34, 4
	s_cselect_b32 s2, s2, 0
	s_cmp_gt_i32 s2, 2
	s_cselect_b32 s23, -3, 2
	s_add_i32 s23, s23, s2
	s_mulk_i32 s23, 0x2400
	s_waitcnt vmcnt(3)
	ds_write_b128 v203, v[6:9] offset:9216
	v_add_u32_e32 v6, s23, v203
	s_add_i32 s23, s2, 1
	s_cmp_lg_u32 s2, 4
	s_cselect_b32 s23, s23, 0
	s_add_i32 s2, s45, 6
	s_add_i32 s34, s2, s13
	s_ashr_i32 s35, s34, 31
	s_lshl_b32 s26, s26, 6
	s_lshl_b64 vcc, s[34:35], 13
	s_ashr_i32 s27, s26, 31
	s_waitcnt vmcnt(2)
	ds_write_b128 v6, v[2:5] offset:36864
	v_lshl_add_u64 v[2:3], v[198:199], 0, vcc
	v_lshl_add_u64 v[6:7], s[26:27], 1, v[196:197]
	global_load_dwordx4 v[2:5], v[2:3], off
	s_mul_i32 s25, s23, 0x2400
	global_load_dwordx4 v[6:9], v[6:7], off
	s_add_i32 s26, s25, 0xffffdc00
	s_cmp_lg_u32 s23, 0
	s_cselect_b32 s26, s26, 0x9000
	v_add_f32_e32 v1, v64, v1
	v_add_u32_e32 v64, s26, v201
	v_add_f32_e32 v1, v1, v168
	ds_read_b128 v[116:119], v64 offset:41472
	ds_read_b128 v[120:123], v64 offset:36864
	ds_read_b128 v[124:127], v64 offset:36896
	ds_read_b128 v[136:139], v64 offset:41504
	ds_read_b128 v[140:143], v64 offset:36928
	ds_read_b128 v[168:171], v64 offset:41536
	ds_read_b128 v[172:175], v64 offset:36960
	ds_read_b128 v[176:179], v64 offset:41568
	s_setprio 3
	v_cvt_pk_bf16_f32 v204, v148, v149
	v_cvt_pk_bf16_f32 v205, v150, v151
	v_cvt_pk_bf16_f32 v206, v128, v129
	v_cvt_pk_bf16_f32 v207, v130, v131
	s_waitcnt lgkmcnt(6)
	s_nop 0
	v_mfma_f32_32x32x16_bf16 v[16:31], v[120:123], v[204:207], v[16:31]
	v_add_f32_e32 v180, v148, v149
	v_add_f32_e32 v180, v180, v150
	v_add_f32_e32 v180, v180, v151
	s_nop 0
	v_mfma_f32_32x32x16_bf16 v[32:47], v[116:119], v[204:207], v[32:47]
	v_cvt_pk_bf16_f32 v120, v132, v133
	v_cvt_pk_bf16_f32 v121, v134, v135
	v_cvt_pk_bf16_f32 v122, v71, v72
	v_cvt_pk_bf16_f32 v123, v73, v74
	v_add_f32_e32 v180, v180, v128
	v_add_f32_e32 v180, v180, v129
	v_add_f32_e32 v180, v180, v130
	v_add_f32_e32 v180, v180, v131
	s_waitcnt lgkmcnt(5)
	v_mfma_f32_32x32x16_bf16 v[16:31], v[124:127], v[120:123], v[16:31]
	v_add_f32_e32 v180, v180, v132
	v_add_f32_e32 v180, v180, v133
	v_add_f32_e32 v180, v180, v134
	v_add_f32_e32 v180, v180, v135
	s_waitcnt lgkmcnt(4)
	v_mfma_f32_32x32x16_bf16 v[32:47], v[136:139], v[120:123], v[32:47]
	v_cvt_pk_bf16_f32 v116, v75, v76
	v_cvt_pk_bf16_f32 v117, v77, v78
	v_cvt_pk_bf16_f32 v118, v14, v15
	v_cvt_pk_bf16_f32 v119, v65, v66
	v_add_f32_e32 v180, v180, v71
	v_add_f32_e32 v180, v180, v72
	v_add_f32_e32 v180, v180, v73
	v_add_f32_e32 v180, v180, v74
	s_waitcnt lgkmcnt(3)
	v_mfma_f32_32x32x16_bf16 v[16:31], v[140:143], v[116:119], v[16:31]
	v_add_f32_e32 v180, v180, v75
	v_add_f32_e32 v180, v180, v76
	v_add_f32_e32 v180, v180, v77
	v_add_f32_e32 v180, v180, v78
	s_waitcnt lgkmcnt(2)
	v_mfma_f32_32x32x16_bf16 v[32:47], v[168:171], v[116:119], v[32:47]
	v_cvt_pk_bf16_f32 v72, v67, v68
	v_cvt_pk_bf16_f32 v73, v69, v70
	v_cvt_pk_bf16_f32 v74, v79, v112
	v_cvt_pk_bf16_f32 v75, v113, v114
	v_add_f32_e32 v180, v180, v14
	v_add_f32_e32 v180, v180, v15
	v_add_f32_e32 v180, v180, v65
	v_add_f32_e32 v180, v180, v66
	s_waitcnt lgkmcnt(1)
	v_mfma_f32_32x32x16_bf16 v[16:31], v[172:175], v[72:75], v[16:31]
	v_add_f32_e32 v180, v180, v67
	v_add_f32_e32 v180, v180, v68
	v_add_f32_e32 v180, v180, v69
	v_add_f32_e32 v180, v180, v70
	s_waitcnt lgkmcnt(0)
	v_mfma_f32_32x32x16_bf16 v[32:47], v[176:179], v[72:75], v[32:47]
	v_add_f32_e32 v180, v180, v79
	v_add_f32_e32 v180, v180, v112
	v_add_f32_e32 v180, v180, v113
	v_add_f32_e32 v180, v180, v114
	s_setprio 2
	s_waitcnt lgkmcnt(0)
	s_barrier
	ds_read_b128 v[240:243], v201
	ds_read_b128 v[244:247], v201 offset:4608
	ds_read_b128 v[128:131], v201 offset:32
	ds_read_b128 v[136:139], v201 offset:4640
	ds_read_b128 v[172:175], v201 offset:64
	ds_read_b128 v[176:179], v201 offset:96
	ds_read_b128 v[204:207], v201 offset:4672
	ds_read_b128 v[208:211], v201 offset:4704
	s_waitcnt lgkmcnt(6)
	v_mfma_f32_32x32x16_bf16 v[64:79], v[240:243], v[164:167], v[48:63]
	v_exp_f32_e32 v168, v96
	v_exp_f32_e32 v169, v97
	v_exp_f32_e32 v170, v98
	v_exp_f32_e32 v171, v99
	s_waitcnt lgkmcnt(5)
	v_mfma_f32_32x32x16_bf16 v[112:127], v[244:247], v[164:167], v[48:63]
	v_exp_f32_e32 v140, v100
	v_exp_f32_e32 v141, v101
	v_exp_f32_e32 v142, v102
	v_exp_f32_e32 v143, v103
	v_mfma_f32_32x32x16_bf16 v[64:79], v[128:131], v[160:163], v[64:79]
	v_exp_f32_e32 v148, v104
	v_exp_f32_e32 v149, v105
	v_exp_f32_e32 v150, v106
	v_exp_f32_e32 v151, v107
	s_waitcnt lgkmcnt(4)
	v_mfma_f32_32x32x16_bf16 v[112:127], v[136:139], v[160:163], v[112:127]
	v_exp_f32_e32 v132, v108
	v_exp_f32_e32 v133, v109
	v_exp_f32_e32 v134, v110
	v_exp_f32_e32 v135, v111
	s_waitcnt lgkmcnt(3)
	v_mfma_f32_32x32x16_bf16 v[64:79], v[172:175], v[156:159], v[64:79]
	v_exp_f32_e32 v136, v80
	v_exp_f32_e32 v137, v81
	v_exp_f32_e32 v138, v82
	v_exp_f32_e32 v139, v83
	s_waitcnt lgkmcnt(1)
	v_mfma_f32_32x32x16_bf16 v[112:127], v[204:207], v[156:159], v[112:127]
	v_exp_f32_e32 v128, v84
	v_exp_f32_e32 v129, v85
	v_exp_f32_e32 v130, v86
	v_exp_f32_e32 v131, v87
	v_mfma_f32_32x32x16_bf16 v[64:79], v[176:179], v[152:155], v[64:79]
	v_exp_f32_e32 v84, v88
	v_exp_f32_e32 v85, v89
	v_exp_f32_e32 v86, v90
	v_exp_f32_e32 v87, v91
	s_waitcnt lgkmcnt(0)
	v_mfma_f32_32x32x16_bf16 v[112:127], v[208:211], v[152:155], v[112:127]
	v_exp_f32_e32 v88, v92
	v_exp_f32_e32 v89, v93
	v_exp_f32_e32 v90, v94
	v_exp_f32_e32 v91, v95
	v_sub_u32_e32 v14, s24, v202
	v_add_u32_e32 v14, v14, v183
	v_add_u32_e32 v15, 0xffffff7f, v14
	v_cmp_lt_u32_e32 vcc, s53, v15
	v_add_u32_e32 v15, 0xffffff9f, v14
	s_cmp_gt_i32 s23, 2
	v_cndmask_b32_e32 v80, v233, v64, vcc
	v_cmp_lt_u32_e32 vcc, s53, v15
	v_add_u32_e32 v64, 0xffffff80, v14
	s_cselect_b32 s24, -3, 2
	v_cndmask_b32_e32 v15, v233, v112, vcc
	v_cmp_lt_u32_e32 vcc, s53, v64
	v_add_u32_e32 v64, 0xffffffa0, v14
	s_add_i32 s24, s24, s23
	v_cndmask_b32_e32 v81, v233, v65, vcc
	v_cmp_lt_u32_e32 vcc, s53, v64
	v_add_u32_e32 v64, 0xffffff81, v14
	s_mulk_i32 s24, 0x2400
	v_cndmask_b32_e32 v100, v233, v113, vcc
	v_cmp_lt_u32_e32 vcc, s53, v64
	v_add_u32_e32 v64, 0xffffffa1, v14
	s_add_i32 s27, s77, s18
	v_cndmask_b32_e32 v82, v233, v66, vcc
	v_cmp_lt_u32_e32 vcc, s53, v64
	v_add_u32_e32 v64, 0xffffff82, v14
	s_nop 7
	s_nop 3
	s_waitcnt vmcnt(3)
	ds_write_b128 v203, v[144:147] offset:18432
	v_cndmask_b32_e32 v101, v233, v114, vcc
	v_cmp_lt_u32_e32 vcc, s53, v64
	v_add_u32_e32 v64, 0xffffffa2, v14
	s_lshl_b32 s34, s34, 6
	v_cndmask_b32_e32 v83, v233, v67, vcc
	v_cmp_lt_u32_e32 vcc, s53, v64
	v_add_u32_e32 v64, 0xffffff87, v14
	s_ashr_i32 s35, s34, 31
	v_cndmask_b32_e32 v102, v233, v115, vcc
	v_cmp_lt_u32_e32 vcc, s53, v64
	v_add_u32_e32 v64, 0xffffffa7, v14
	v_add_f32_e32 v1, v1, v180
	v_cndmask_b32_e32 v105, v233, v68, vcc
	v_cmp_lt_u32_e32 vcc, s53, v64
	v_add_u32_e32 v64, 0xffffff88, v14
	v_add_u32_e32 v68, 0xffffff9a, v14
	v_cndmask_b32_e32 v103, v233, v116, vcc
	v_cmp_lt_u32_e32 vcc, s53, v64
	v_add_u32_e32 v64, 0xffffffa8, v14
	s_add_i32 s26, s23, 1
	v_cndmask_b32_e32 v107, v233, v69, vcc
	v_cmp_lt_u32_e32 vcc, s53, v64
	v_add_u32_e32 v64, 0xffffff89, v14
	s_nop 0
	v_cndmask_b32_e32 v104, v233, v117, vcc
	v_cmp_lt_u32_e32 vcc, s53, v64
	v_add_u32_e32 v64, 0xffffffa9, v14
	s_nop 0
	v_cndmask_b32_e32 v109, v233, v70, vcc
	v_cmp_lt_u32_e32 vcc, s53, v64
	v_add_u32_e32 v64, 0xffffff8a, v14
	s_nop 0
	v_cndmask_b32_e32 v106, v233, v118, vcc
	v_cmp_lt_u32_e32 vcc, s53, v64
	v_add_u32_e32 v64, 0xffffffaa, v14
	s_nop 0
	v_cndmask_b32_e32 v111, v233, v71, vcc
	v_cmp_lt_u32_e32 vcc, s53, v64
	v_add_u32_e32 v64, 0xffffff8f, v14
	s_nop 0
	v_cndmask_b32_e32 v108, v233, v119, vcc
	v_cmp_lt_u32_e32 vcc, s53, v64
	v_add_u32_e32 v64, 0xffffffaf, v14
	s_nop 0
	v_cndmask_b32_e32 v113, v233, v72, vcc
	v_cmp_lt_u32_e32 vcc, s53, v64
	v_add_u32_e32 v64, 0xffffff90, v14
	s_nop 0
	v_cndmask_b32_e32 v110, v233, v120, vcc
	v_cmp_lt_u32_e32 vcc, s53, v64
	v_add_u32_e32 v64, 0xffffffb0, v14
	s_nop 0
	v_cndmask_b32_e32 v115, v233, v73, vcc
	v_cmp_lt_u32_e32 vcc, s53, v64
	v_add_u32_e32 v64, 0xffffff91, v14
	s_nop 0
	v_cndmask_b32_e32 v112, v233, v121, vcc
	v_cmp_lt_u32_e32 vcc, s53, v64
	v_add_u32_e32 v64, 0xffffffb1, v14
	s_nop 0
	v_cndmask_b32_e32 v117, v233, v74, vcc
	v_cmp_lt_u32_e32 vcc, s53, v64
	v_add_u32_e32 v64, 0xffffff92, v14
	s_nop 0
	v_cndmask_b32_e32 v114, v233, v122, vcc
	v_cmp_lt_u32_e32 vcc, s53, v64
	v_add_u32_e32 v64, 0xffffffb2, v14
	s_nop 0
	v_cndmask_b32_e32 v119, v233, v75, vcc
	v_cmp_lt_u32_e32 vcc, s53, v64
	v_add_u32_e32 v64, 0xffffff97, v14
	s_nop 0
	v_cndmask_b32_e32 v116, v233, v123, vcc
	v_cmp_lt_u32_e32 vcc, s53, v64
	v_add_u32_e32 v64, 0xffffffb7, v14
	s_nop 0
	v_cndmask_b32_e32 v121, v233, v76, vcc
	v_cmp_lt_u32_e32 vcc, s53, v64
	v_add_u32_e32 v64, 0xffffff98, v14
	s_nop 0
	v_cndmask_b32_e32 v118, v233, v124, vcc
	v_cmp_lt_u32_e32 vcc, s53, v64
	v_add_u32_e32 v64, 0xffffffb8, v14
	s_nop 0
	v_cndmask_b32_e32 v123, v233, v77, vcc
	v_cmp_lt_u32_e32 vcc, s53, v64
	v_add_u32_e32 v64, 0xffffff99, v14
	s_nop 0
	v_cndmask_b32_e32 v120, v233, v125, vcc
	v_cmp_lt_u32_e32 vcc, s53, v64
	v_add_u32_e32 v64, 0xffffffb9, v14
	v_add_u32_e32 v14, 0xffffffba, v14
	v_cndmask_b32_e32 v125, v233, v78, vcc
	v_cmp_lt_u32_e32 vcc, s53, v64
	s_nop 1
	v_cndmask_b32_e32 v122, v233, v126, vcc
	v_cmp_lt_u32_e32 vcc, s53, v14
	v_add_u32_e32 v14, s24, v203
	s_add_i32 s24, s27, -4
	s_waitcnt vmcnt(2)
	ds_write_b128 v14, v[10:13] offset:36864
	v_add_u32_e32 v14, s25, v201
	s_ashr_i32 s25, s24, 31
	v_cndmask_b32_e32 v124, v233, v127, vcc
	s_lshl_b64 vcc, s[24:25], 13
	v_lshl_add_u64 v[10:11], v[198:199], 0, vcc
	global_load_dwordx4 v[96:99], v[10:11], off
	v_lshl_add_u64 v[10:11], s[34:35], 1, v[196:197]
	global_load_dwordx4 v[10:13], v[10:11], off
	ds_read_b128 v[240:243], v201 offset:9216
	ds_read_b128 v[244:247], v201 offset:13824
	ds_read_b128 v[64:67], v14 offset:41472
	ds_read_b128 v[70:73], v14 offset:36864
	ds_read_b128 v[74:77], v14 offset:36896
	ds_read_b128 v[92:95], v14 offset:41504
	ds_read_b128 v[144:147], v14 offset:36928
	ds_read_b128 v[172:175], v14 offset:41536
	ds_read_b128 v[176:179], v14 offset:36960
	ds_read_b128 v[204:207], v14 offset:41568
	s_setprio 1
	v_cvt_pk_bf16_f32 v208, v168, v169
	v_cvt_pk_bf16_f32 v209, v170, v171
	v_cvt_pk_bf16_f32 v210, v140, v141
	v_cvt_pk_bf16_f32 v211, v142, v143
	s_waitcnt lgkmcnt(6)
	s_nop 0
	v_mfma_f32_32x32x16_bf16 v[16:31], v[70:73], v[208:211], v[16:31]
	v_add_f32_e32 v14, v168, v169
	v_add_f32_e32 v14, v14, v170
	v_add_f32_e32 v14, v14, v171
	s_nop 0
	v_mfma_f32_32x32x16_bf16 v[32:47], v[64:67], v[208:211], v[32:47]
	v_cvt_pk_bf16_f32 v70, v148, v149
	v_cvt_pk_bf16_f32 v71, v150, v151
	v_cvt_pk_bf16_f32 v72, v132, v133
	v_cvt_pk_bf16_f32 v73, v134, v135
	v_add_f32_e32 v14, v14, v140
	v_add_f32_e32 v14, v14, v141
	v_add_f32_e32 v14, v14, v142
	v_add_f32_e32 v14, v14, v143
	s_waitcnt lgkmcnt(5)
	v_mfma_f32_32x32x16_bf16 v[16:31], v[74:77], v[70:73], v[16:31]
	v_add_f32_e32 v14, v14, v148
	v_add_f32_e32 v14, v14, v149
	v_add_f32_e32 v14, v14, v150
	v_add_f32_e32 v14, v14, v151
	s_waitcnt lgkmcnt(4)
	v_mfma_f32_32x32x16_bf16 v[32:47], v[92:95], v[70:73], v[32:47]
	v_cvt_pk_bf16_f32 v64, v136, v137
	v_cvt_pk_bf16_f32 v65, v138, v139
	v_cvt_pk_bf16_f32 v66, v128, v129
	v_cvt_pk_bf16_f32 v67, v130, v131
	v_add_f32_e32 v14, v14, v132
	v_add_f32_e32 v14, v14, v133
	v_add_f32_e32 v14, v14, v134
	v_add_f32_e32 v14, v14, v135
	s_waitcnt lgkmcnt(3)
	v_mfma_f32_32x32x16_bf16 v[16:31], v[144:147], v[64:67], v[16:31]
	v_add_f32_e32 v14, v14, v136
	v_add_f32_e32 v14, v14, v137
	v_add_f32_e32 v14, v14, v138
	v_add_f32_e32 v14, v14, v139
	s_waitcnt lgkmcnt(2)
	v_mfma_f32_32x32x16_bf16 v[32:47], v[172:175], v[64:67], v[32:47]
	v_cvt_pk_bf16_f32 v70, v84, v85
	v_cvt_pk_bf16_f32 v71, v86, v87
	v_cvt_pk_bf16_f32 v72, v88, v89
	v_cvt_pk_bf16_f32 v73, v90, v91
	v_add_f32_e32 v14, v14, v128
	v_add_f32_e32 v14, v14, v129
	v_add_f32_e32 v14, v14, v130
	v_add_f32_e32 v14, v14, v131
	s_waitcnt lgkmcnt(1)
	v_mfma_f32_32x32x16_bf16 v[16:31], v[176:179], v[70:73], v[16:31]
	v_add_f32_e32 v14, v14, v84
	v_add_f32_e32 v14, v14, v85
	v_add_f32_e32 v14, v14, v86
	v_add_f32_e32 v14, v14, v87
	s_waitcnt lgkmcnt(0)
	v_mfma_f32_32x32x16_bf16 v[32:47], v[204:207], v[70:73], v[32:47]
	v_add_f32_e32 v14, v14, v88
	v_add_f32_e32 v14, v14, v89
	v_add_f32_e32 v14, v14, v90
	v_add_f32_e32 v14, v14, v91
	s_setprio 0
	ds_read_b128 v[130:133], v201 offset:9248
	ds_read_b128 v[168:171], v201 offset:13856
	ds_read_b128 v[172:175], v201 offset:9280
	ds_read_b128 v[176:179], v201 offset:13888
	ds_read_b128 v[204:207], v201 offset:9312
	ds_read_b128 v[208:211], v201 offset:13920
	v_cmp_lt_u32_e32 vcc, s53, v68
	s_cmp_lg_u32 s23, 4
	s_cselect_b32 s23, s26, 0
	v_cndmask_b32_e32 v135, v233, v79, vcc
	s_waitcnt lgkmcnt(6)
	v_mfma_f32_32x32x16_bf16 v[64:79], v[240:243], v[164:167], v[48:63]
	v_exp_f32_e32 v148, v80
	v_exp_f32_e32 v149, v81
	v_exp_f32_e32 v150, v82
	v_exp_f32_e32 v151, v83
	v_mfma_f32_32x32x16_bf16 v[80:95], v[244:247], v[164:167], v[48:63]
	v_exp_f32_e32 v142, v105
	v_exp_f32_e32 v143, v107
	v_exp_f32_e32 v144, v109
	v_exp_f32_e32 v147, v111
	s_waitcnt lgkmcnt(5)
	v_mfma_f32_32x32x16_bf16 v[64:79], v[130:133], v[160:163], v[64:79]
	v_exp_f32_e32 v136, v113
	v_exp_f32_e32 v137, v115
	v_exp_f32_e32 v138, v117
	v_exp_f32_e32 v140, v119
	s_waitcnt lgkmcnt(4)
	v_mfma_f32_32x32x16_bf16 v[80:95], v[168:171], v[160:163], v[80:95]
	v_exp_f32_e32 v130, v121
	v_exp_f32_e32 v131, v123
	v_exp_f32_e32 v133, v125
	v_exp_f32_e32 v134, v135
	s_waitcnt lgkmcnt(3)
	v_mfma_f32_32x32x16_bf16 v[64:79], v[172:175], v[156:159], v[64:79]
	v_exp_f32_e32 v125, v15
	v_exp_f32_e32 v126, v100
	v_exp_f32_e32 v127, v101
	v_exp_f32_e32 v128, v102
	s_waitcnt lgkmcnt(2)
	v_mfma_f32_32x32x16_bf16 v[80:95], v[176:179], v[156:159], v[80:95]
	v_exp_f32_e32 v117, v103
	v_exp_f32_e32 v119, v104
	v_exp_f32_e32 v121, v106
	v_exp_f32_e32 v123, v108
	s_waitcnt lgkmcnt(1)
	v_mfma_f32_32x32x16_bf16 v[64:79], v[204:207], v[152:155], v[64:79]
	v_exp_f32_e32 v108, v110
	v_exp_f32_e32 v109, v112
	v_exp_f32_e32 v111, v114
	v_exp_f32_e32 v113, v116
	s_waitcnt lgkmcnt(0)
	v_mfma_f32_32x32x16_bf16 v[80:95], v[208:211], v[152:155], v[80:95]
	v_exp_f32_e32 v110, v118
	v_exp_f32_e32 v112, v120
	v_exp_f32_e32 v114, v122
	v_exp_f32_e32 v115, v124
	s_cmp_gt_i32 s23, 2
	v_sub_u32_e32 v15, s22, v202
	s_cselect_b32 s22, -3, 2
	s_add_i32 s22, s22, s23
	s_mulk_i32 s22, 0x2400
	s_nop 7
	s_nop 3
	s_waitcnt vmcnt(3)
	ds_write_b128 v203, v[2:5] offset:27648
	v_add_u32_e32 v2, s22, v203
	s_add_i32 s22, s23, 1
	s_cmp_lg_u32 s23, 4
	s_cselect_b32 s25, s22, 0
	s_add_i32 s26, s45, 8
	s_min_i32 s22, s26, s92
	s_cmp_gt_i32 s22, 3
	s_cselect_b32 s23, s13, 0
	s_add_i32 s34, s23, s22
	s_ashr_i32 s35, s34, 31
	s_lshl_b64 s[22:23], s[34:35], 13
	s_waitcnt vmcnt(2)
	ds_write_b128 v2, v[6:9] offset:36864
	v_lshl_add_u64 v[2:3], v[198:199], 0, s[22:23]
	s_lshl_b32 s22, s24, 6
	s_ashr_i32 s23, s22, 31
	v_lshl_add_u64 v[6:7], s[22:23], 1, v[196:197]
	global_load_dwordx4 v[2:5], v[2:3], off
	v_add_u32_e32 v168, v15, v183
	global_load_dwordx4 v[6:9], v[6:7], off
	v_add_u32_e32 v15, 0xffffff7f, v168
	v_cmp_lt_u32_e32 vcc, s53, v15
	v_add_u32_e32 v15, 0xffffff9f, v168
	s_mul_i32 s22, s25, 0x2400
	v_cndmask_b32_e32 v101, v233, v64, vcc
	v_cmp_lt_u32_e32 vcc, s53, v15
	v_add_u32_e32 v64, 0xffffff80, v168
	s_add_i32 s23, s22, 0xffffdc00
	v_cndmask_b32_e32 v15, v233, v80, vcc
	v_cmp_lt_u32_e32 vcc, s53, v64
	v_add_u32_e32 v64, 0xffffffa0, v168
	s_cmp_lg_u32 s25, 0
	v_cndmask_b32_e32 v80, v233, v65, vcc
	v_cmp_lt_u32_e32 vcc, s53, v64
	v_add_u32_e32 v64, 0xffffff81, v168
	v_add_u32_e32 v65, 0xffffffba, v168
	v_cndmask_b32_e32 v100, v233, v81, vcc
	v_cmp_lt_u32_e32 vcc, s53, v64
	v_add_u32_e32 v64, 0xffffffa1, v168
	s_cselect_b32 s23, s23, 0x9000
	v_cndmask_b32_e32 v81, v233, v66, vcc
	v_cmp_lt_u32_e32 vcc, s53, v64
	v_add_u32_e32 v64, 0xffffff82, v168
	s_nop 0
	v_cndmask_b32_e32 v102, v233, v82, vcc
	v_cmp_lt_u32_e32 vcc, s53, v64
	v_add_u32_e32 v64, 0xffffffa2, v168
	s_nop 0
	v_cndmask_b32_e32 v82, v233, v67, vcc
	v_cmp_lt_u32_e32 vcc, s53, v64
	v_add_u32_e32 v64, 0xffffff87, v168
	s_nop 0
	v_cndmask_b32_e32 v103, v233, v83, vcc
	v_cmp_lt_u32_e32 vcc, s53, v64
	v_add_u32_e32 v64, 0xffffffa7, v168
	v_add_u32_e32 v83, s23, v201
	v_cndmask_b32_e32 v106, v233, v68, vcc
	v_cmp_lt_u32_e32 vcc, s53, v64
	v_add_u32_e32 v64, 0xffffff88, v168
	s_nop 0
	v_cndmask_b32_e32 v104, v233, v84, vcc
	v_cmp_lt_u32_e32 vcc, s53, v64
	v_add_u32_e32 v64, 0xffffffa8, v168
	s_nop 0
	v_cndmask_b32_e32 v116, v233, v69, vcc
	v_cmp_lt_u32_e32 vcc, s53, v64
	v_add_u32_e32 v64, 0xffffff89, v168
	s_nop 0
	v_cndmask_b32_e32 v105, v233, v85, vcc
	v_cmp_lt_u32_e32 vcc, s53, v64
	v_add_u32_e32 v64, 0xffffffa9, v168
	s_nop 0
	v_cndmask_b32_e32 v120, v233, v70, vcc
	v_cmp_lt_u32_e32 vcc, s53, v64
	v_add_u32_e32 v64, 0xffffff8a, v168
	s_nop 0
	v_cndmask_b32_e32 v107, v233, v86, vcc
	v_cmp_lt_u32_e32 vcc, s53, v64
	v_add_u32_e32 v64, 0xffffffaa, v168
	s_nop 0
	v_cndmask_b32_e32 v124, v233, v71, vcc
	v_cmp_lt_u32_e32 vcc, s53, v64
	v_add_u32_e32 v64, 0xffffff8f, v168
	s_nop 0
	v_cndmask_b32_e32 v118, v233, v87, vcc
	v_cmp_lt_u32_e32 vcc, s53, v64
	v_add_u32_e32 v64, 0xffffffaf, v168
	s_nop 0
	v_cndmask_b32_e32 v129, v233, v72, vcc
	v_cmp_lt_u32_e32 vcc, s53, v64
	v_add_u32_e32 v64, 0xffffff90, v168
	s_nop 0
	v_cndmask_b32_e32 v122, v233, v88, vcc
	v_cmp_lt_u32_e32 vcc, s53, v64
	v_add_u32_e32 v64, 0xffffffb0, v168
	s_nop 0
	v_cndmask_b32_e32 v135, v233, v73, vcc
	v_cmp_lt_u32_e32 vcc, s53, v64
	v_add_u32_e32 v64, 0xffffff91, v168
	s_nop 0
	v_cndmask_b32_e32 v132, v233, v89, vcc
	v_cmp_lt_u32_e32 vcc, s53, v64
	v_add_u32_e32 v64, 0xffffffb1, v168
	s_nop 0
	v_cndmask_b32_e32 v141, v233, v74, vcc
	v_cmp_lt_u32_e32 vcc, s53, v64
	v_add_u32_e32 v64, 0xffffff92, v168
	s_nop 0
	v_cndmask_b32_e32 v139, v233, v90, vcc
	v_cmp_lt_u32_e32 vcc, s53, v64
	v_add_u32_e32 v64, 0xffffffb2, v168
	s_nop 0
	v_cndmask_b32_e32 v175, v233, v75, vcc
	v_cmp_lt_u32_e32 vcc, s53, v64
	v_add_u32_e32 v64, 0xffffff97, v168
	s_nop 0
	v_cndmask_b32_e32 v145, v233, v91, vcc
	v_cmp_lt_u32_e32 vcc, s53, v64
	v_add_u32_e32 v64, 0xffffffb7, v168
	s_nop 0
	v_cndmask_b32_e32 v177, v233, v76, vcc
	v_cmp_lt_u32_e32 vcc, s53, v64
	v_add_u32_e32 v64, 0xffffff98, v168
	s_nop 0
	v_cndmask_b32_e32 v146, v233, v92, vcc
	v_cmp_lt_u32_e32 vcc, s53, v64
	v_add_u32_e32 v64, 0xffffffb8, v168
	s_nop 0
	v_cndmask_b32_e32 v179, v233, v77, vcc
	v_cmp_lt_u32_e32 vcc, s53, v64
	v_add_u32_e32 v64, 0xffffff99, v168
	s_nop 0
	v_cndmask_b32_e32 v176, v233, v93, vcc
	v_cmp_lt_u32_e32 vcc, s53, v64
	v_add_u32_e32 v64, 0xffffffb9, v168
	s_nop 0
	v_cndmask_b32_e32 v181, v233, v78, vcc
	v_cmp_lt_u32_e32 vcc, s53, v64
	v_add_u32_e32 v64, 0xffffff9a, v168
	s_nop 0
	v_cndmask_b32_e32 v178, v233, v94, vcc
	v_cmp_lt_u32_e32 vcc, s53, v65
	s_nop 1
	v_cndmask_b32_e32 v180, v233, v95, vcc
	v_cmp_lt_u32_e32 vcc, s53, v64
	s_nop 1
	v_cndmask_b32_e32 v185, v233, v79, vcc
	ds_read_b128 v[64:67], v83 offset:41472
	ds_read_b128 v[68:71], v83 offset:36864
	ds_read_b128 v[72:75], v83 offset:36896
	ds_read_b128 v[76:79], v83 offset:41504
	ds_read_b128 v[84:87], v83 offset:36928
	ds_read_b128 v[88:91], v83 offset:41536
	ds_read_b128 v[92:95], v83 offset:36960
	ds_read_b128 v[168:171], v83 offset:41568
	s_setprio 3
	v_cvt_pk_bf16_f32 v204, v148, v149
	v_cvt_pk_bf16_f32 v205, v150, v151
	v_cvt_pk_bf16_f32 v206, v142, v143
	v_cvt_pk_bf16_f32 v207, v144, v147
	s_waitcnt lgkmcnt(6)
	s_nop 0
	v_mfma_f32_32x32x16_bf16 v[16:31], v[68:71], v[204:207], v[16:31]
	v_add_f32_e32 v186, v148, v149
	v_add_f32_e32 v186, v186, v150
	v_add_f32_e32 v186, v186, v151
	s_nop 0
	v_mfma_f32_32x32x16_bf16 v[32:47], v[64:67], v[204:207], v[32:47]
	v_cvt_pk_bf16_f32 v68, v136, v137
	v_cvt_pk_bf16_f32 v69, v138, v140
	v_cvt_pk_bf16_f32 v70, v130, v131
	v_cvt_pk_bf16_f32 v71, v133, v134
	v_add_f32_e32 v186, v186, v142
	v_add_f32_e32 v186, v186, v143
	v_add_f32_e32 v186, v186, v144
	v_add_f32_e32 v186, v186, v147
	s_waitcnt lgkmcnt(5)
	v_mfma_f32_32x32x16_bf16 v[16:31], v[72:75], v[68:71], v[16:31]
	v_add_f32_e32 v186, v186, v136
	v_add_f32_e32 v186, v186, v137
	v_add_f32_e32 v186, v186, v138
	v_add_f32_e32 v186, v186, v140
	s_waitcnt lgkmcnt(4)
	v_mfma_f32_32x32x16_bf16 v[32:47], v[76:79], v[68:71], v[32:47]
	v_cvt_pk_bf16_f32 v64, v125, v126
	v_cvt_pk_bf16_f32 v65, v127, v128
	v_cvt_pk_bf16_f32 v66, v117, v119
	v_cvt_pk_bf16_f32 v67, v121, v123
	v_add_f32_e32 v186, v186, v130
	v_add_f32_e32 v186, v186, v131
	v_add_f32_e32 v186, v186, v133
	v_add_f32_e32 v186, v186, v134
	s_waitcnt lgkmcnt(3)
	v_mfma_f32_32x32x16_bf16 v[16:31], v[84:87], v[64:67], v[16:31]
	v_add_f32_e32 v186, v186, v125
	v_add_f32_e32 v186, v186, v126
	v_add_f32_e32 v186, v186, v127
	v_add_f32_e32 v186, v186, v128
	s_waitcnt lgkmcnt(2)
	v_mfma_f32_32x32x16_bf16 v[32:47], v[88:91], v[64:67], v[32:47]
	v_cvt_pk_bf16_f32 v68, v108, v109
	v_cvt_pk_bf16_f32 v69, v111, v113
	v_cvt_pk_bf16_f32 v70, v110, v112
	v_cvt_pk_bf16_f32 v71, v114, v115
	v_add_f32_e32 v186, v186, v117
	v_add_f32_e32 v186, v186, v119
	v_add_f32_e32 v186, v186, v121
	v_add_f32_e32 v186, v186, v123
	s_waitcnt lgkmcnt(1)
	v_mfma_f32_32x32x16_bf16 v[16:31], v[92:95], v[68:71], v[16:31]
	v_add_f32_e32 v186, v186, v108
	v_add_f32_e32 v186, v186, v109
	v_add_f32_e32 v186, v186, v111
	v_add_f32_e32 v186, v186, v113
	s_waitcnt lgkmcnt(0)
	v_mfma_f32_32x32x16_bf16 v[32:47], v[168:171], v[68:71], v[32:47]
	v_add_f32_e32 v186, v186, v110
	v_add_f32_e32 v186, v186, v112
	v_add_f32_e32 v186, v186, v114
	v_add_f32_e32 v186, v186, v115
	s_setprio 2
	s_waitcnt lgkmcnt(0)
	s_barrier
	ds_read_b128 v[240:243], v201 offset:18432
	ds_read_b128 v[244:247], v201 offset:23040
	ds_read_b128 v[112:115], v201 offset:18464
	ds_read_b128 v[204:207], v201 offset:23072
	ds_read_b128 v[208:211], v201 offset:18496
	ds_read_b128 v[212:215], v201 offset:23104
	ds_read_b128 v[216:219], v201 offset:18528
	ds_read_b128 v[236:239], v201 offset:23136
	v_add_f32_e32 v1, v1, v14
	s_waitcnt lgkmcnt(6)
	v_mfma_f32_32x32x16_bf16 v[64:79], v[240:243], v[164:167], v[48:63]
	v_exp_f32_e32 v171, v101
	v_exp_f32_e32 v172, v80
	v_exp_f32_e32 v173, v81
	v_exp_f32_e32 v174, v82
	v_mfma_f32_32x32x16_bf16 v[80:95], v[244:247], v[164:167], v[48:63]
	v_exp_f32_e32 v151, v106
	v_exp_f32_e32 v168, v116
	v_exp_f32_e32 v169, v120
	v_exp_f32_e32 v170, v124
	s_waitcnt lgkmcnt(5)
	v_mfma_f32_32x32x16_bf16 v[64:79], v[112:115], v[160:163], v[64:79]
	v_exp_f32_e32 v147, v129
	v_exp_f32_e32 v148, v135
	v_exp_f32_e32 v149, v141
	v_exp_f32_e32 v150, v175
	s_waitcnt lgkmcnt(4)
	v_mfma_f32_32x32x16_bf16 v[80:95], v[204:207], v[160:163], v[80:95]
	v_exp_f32_e32 v141, v177
	v_exp_f32_e32 v142, v179
	v_exp_f32_e32 v143, v181
	v_exp_f32_e32 v144, v185
	s_waitcnt lgkmcnt(3)
	v_mfma_f32_32x32x16_bf16 v[64:79], v[208:211], v[156:159], v[64:79]
	v_exp_f32_e32 v135, v15
	v_exp_f32_e32 v136, v100
	v_exp_f32_e32 v137, v102
	v_exp_f32_e32 v138, v103
	s_waitcnt lgkmcnt(2)
	v_mfma_f32_32x32x16_bf16 v[80:95], v[212:215], v[156:159], v[80:95]
	v_exp_f32_e32 v128, v104
	v_exp_f32_e32 v129, v105
	v_exp_f32_e32 v130, v107
	v_exp_f32_e32 v131, v118
	s_waitcnt lgkmcnt(1)
	v_mfma_f32_32x32x16_bf16 v[64:79], v[216:219], v[152:155], v[64:79]
	v_exp_f32_e32 v118, v122
	v_exp_f32_e32 v119, v132
	v_exp_f32_e32 v120, v139
	v_exp_f32_e32 v121, v145
	s_waitcnt lgkmcnt(0)
	v_mfma_f32_32x32x16_bf16 v[80:95], v[236:239], v[152:155], v[80:95]
	v_exp_f32_e32 v122, v146
	v_exp_f32_e32 v123, v176
	v_exp_f32_e32 v124, v178
	v_exp_f32_e32 v125, v180
	s_add_i32 s87, s87, s18
	v_lshl_add_u32 v14, s87, 6, v184
	v_add_u32_e32 v15, 0xffffff7f, v14
	v_cmp_lt_u32_e32 vcc, s53, v15
	v_add_u32_e32 v15, 0xffffff9f, v14
	s_cmp_gt_i32 s25, 2
	v_cndmask_b32_e32 v101, v233, v64, vcc
	v_cmp_lt_u32_e32 vcc, s53, v15
	v_add_u32_e32 v64, 0xffffff80, v14
	s_cselect_b32 s23, -3, 2
	v_cndmask_b32_e32 v15, v233, v80, vcc
	v_cmp_lt_u32_e32 vcc, s53, v64
	v_add_u32_e32 v64, 0xffffffa0, v14
	s_add_i32 s23, s23, s25
	v_cndmask_b32_e32 v80, v233, v65, vcc
	v_cmp_lt_u32_e32 vcc, s53, v64
	v_add_u32_e32 v64, 0xffffff81, v14
	s_mulk_i32 s23, 0x2400
	v_cndmask_b32_e32 v100, v233, v81, vcc
	v_cmp_lt_u32_e32 vcc, s53, v64
	v_add_u32_e32 v64, 0xffffffa1, v14
	s_nop 7
	s_nop 3
	s_waitcnt vmcnt(3)
	ds_write_b128 v203, v[96:99]
	v_cndmask_b32_e32 v81, v233, v66, vcc
	v_cmp_lt_u32_e32 vcc, s53, v64
	v_add_u32_e32 v64, 0xffffff82, v14
	s_add_i32 s24, s25, 1
	v_cndmask_b32_e32 v102, v233, v82, vcc
	v_cmp_lt_u32_e32 vcc, s53, v64
	v_add_u32_e32 v64, 0xffffffa2, v14
	v_add_f32_e32 v1, v1, v186
	v_cndmask_b32_e32 v82, v233, v67, vcc
	v_cmp_lt_u32_e32 vcc, s53, v64
	v_add_u32_e32 v64, 0xffffff87, v14
	s_nop 0
	v_cndmask_b32_e32 v103, v233, v83, vcc
	v_cmp_lt_u32_e32 vcc, s53, v64
	v_add_u32_e32 v64, 0xffffffa7, v14
	s_nop 0
	v_cndmask_b32_e32 v106, v233, v68, vcc
	v_cmp_lt_u32_e32 vcc, s53, v64
	v_add_u32_e32 v64, 0xffffff88, v14
	v_add_u32_e32 v68, 0xffffff9a, v14
	v_cndmask_b32_e32 v104, v233, v84, vcc
	v_cmp_lt_u32_e32 vcc, s53, v64
	v_add_u32_e32 v64, 0xffffffa8, v14
	s_nop 0
	v_cndmask_b32_e32 v108, v233, v69, vcc
	v_cmp_lt_u32_e32 vcc, s53, v64
	v_add_u32_e32 v64, 0xffffff89, v14
	s_nop 0
	v_cndmask_b32_e32 v105, v233, v85, vcc
	v_cmp_lt_u32_e32 vcc, s53, v64
	v_add_u32_e32 v64, 0xffffffa9, v14
	s_nop 0
	v_cndmask_b32_e32 v110, v233, v70, vcc
	v_cmp_lt_u32_e32 vcc, s53, v64
	v_add_u32_e32 v64, 0xffffff8a, v14
	s_nop 0
	v_cndmask_b32_e32 v107, v233, v86, vcc
	v_cmp_lt_u32_e32 vcc, s53, v64
	v_add_u32_e32 v64, 0xffffffaa, v14
	s_nop 0
	v_cndmask_b32_e32 v112, v233, v71, vcc
	v_cmp_lt_u32_e32 vcc, s53, v64
	v_add_u32_e32 v64, 0xffffff8f, v14
	s_nop 0
	v_cndmask_b32_e32 v109, v233, v87, vcc
	v_cmp_lt_u32_e32 vcc, s53, v64
	v_add_u32_e32 v64, 0xffffffaf, v14
	s_nop 0
	v_cndmask_b32_e32 v114, v233, v72, vcc
	v_cmp_lt_u32_e32 vcc, s53, v64
	v_add_u32_e32 v64, 0xffffff90, v14
	s_nop 0
	v_cndmask_b32_e32 v111, v233, v88, vcc
	v_cmp_lt_u32_e32 vcc, s53, v64
	v_add_u32_e32 v64, 0xffffffb0, v14
	s_nop 0
	v_cndmask_b32_e32 v116, v233, v73, vcc
	v_cmp_lt_u32_e32 vcc, s53, v64
	v_add_u32_e32 v64, 0xffffff91, v14
	s_nop 0
	v_cndmask_b32_e32 v113, v233, v89, vcc
	v_cmp_lt_u32_e32 vcc, s53, v64
	v_add_u32_e32 v64, 0xffffffb1, v14
	s_nop 0
	v_cndmask_b32_e32 v126, v233, v74, vcc
	v_cmp_lt_u32_e32 vcc, s53, v64
	v_add_u32_e32 v64, 0xffffff92, v14
	s_nop 0
	v_cndmask_b32_e32 v115, v233, v90, vcc
	v_cmp_lt_u32_e32 vcc, s53, v64
	v_add_u32_e32 v64, 0xffffffb2, v14
	s_nop 0
	v_cndmask_b32_e32 v132, v233, v75, vcc
	v_cmp_lt_u32_e32 vcc, s53, v64
	v_add_u32_e32 v64, 0xffffff97, v14
	s_nop 0
	v_cndmask_b32_e32 v117, v233, v91, vcc
	v_cmp_lt_u32_e32 vcc, s53, v64
	v_add_u32_e32 v64, 0xffffffb7, v14
	s_nop 0
	v_cndmask_b32_e32 v134, v233, v76, vcc
	v_cmp_lt_u32_e32 vcc, s53, v64
	v_add_u32_e32 v64, 0xffffff98, v14
	s_nop 0
	v_cndmask_b32_e32 v127, v233, v92, vcc
	v_cmp_lt_u32_e32 vcc, s53, v64
	v_add_u32_e32 v64, 0xffffffb8, v14
	s_nop 0
	v_cndmask_b32_e32 v140, v233, v77, vcc
	v_cmp_lt_u32_e32 vcc, s53, v64
	v_add_u32_e32 v64, 0xffffff99, v14
	s_nop 0
	v_cndmask_b32_e32 v133, v233, v93, vcc
	v_cmp_lt_u32_e32 vcc, s53, v64
	v_add_u32_e32 v64, 0xffffffb9, v14
	v_add_u32_e32 v14, 0xffffffba, v14
	v_cndmask_b32_e32 v146, v233, v78, vcc
	v_cmp_lt_u32_e32 vcc, s53, v64
	s_nop 1
	v_cndmask_b32_e32 v139, v233, v94, vcc
	v_cmp_lt_u32_e32 vcc, s53, v14
	v_add_u32_e32 v14, s23, v203
	s_waitcnt vmcnt(2)
	ds_write_b128 v14, v[10:13] offset:36864
	v_add_u32_e32 v14, s22, v201
	s_add_i32 s22, s45, 9
	s_min_i32 s22, s22, s92
	s_cmp_gt_i32 s22, 3
	s_cselect_b32 s23, s13, 0
	s_add_i32 s22, s23, s22
	s_ashr_i32 s23, s22, 31
	v_cndmask_b32_e32 v145, v233, v95, vcc
	s_lshl_b64 vcc, s[22:23], 13
	s_lshl_b32 s34, s34, 6
	v_lshl_add_u64 v[10:11], v[198:199], 0, vcc
	s_ashr_i32 s35, s34, 31
	global_load_dwordx4 v[96:99], v[10:11], off
	v_lshl_add_u64 v[10:11], s[34:35], 1, v[196:197]
	global_load_dwordx4 v[10:13], v[10:11], off
	ds_read_b128 v[240:243], v201 offset:27648
	ds_read_b128 v[244:247], v201 offset:32256
	ds_read_b128 v[64:67], v14 offset:41472
	ds_read_b128 v[70:73], v14 offset:36864
	ds_read_b128 v[74:77], v14 offset:36896
	ds_read_b128 v[84:87], v14 offset:41504
	ds_read_b128 v[88:91], v14 offset:36928
	ds_read_b128 v[92:95], v14 offset:41536
	ds_read_b128 v[176:179], v14 offset:36960
	ds_read_b128 v[204:207], v14 offset:41568
	s_setprio 1
	v_cvt_pk_bf16_f32 v208, v171, v172
	v_cvt_pk_bf16_f32 v209, v173, v174
	v_cvt_pk_bf16_f32 v210, v151, v168
	v_cvt_pk_bf16_f32 v211, v169, v170
	s_waitcnt lgkmcnt(6)
	s_nop 0
	v_mfma_f32_32x32x16_bf16 v[16:31], v[70:73], v[208:211], v[16:31]
	v_add_f32_e32 v14, v171, v172
	v_add_f32_e32 v14, v14, v173
	v_add_f32_e32 v14, v14, v174
	s_nop 0
	v_mfma_f32_32x32x16_bf16 v[32:47], v[64:67], v[208:211], v[32:47]
	v_cvt_pk_bf16_f32 v70, v147, v148
	v_cvt_pk_bf16_f32 v71, v149, v150
	v_cvt_pk_bf16_f32 v72, v141, v142
	v_cvt_pk_bf16_f32 v73, v143, v144
	v_add_f32_e32 v14, v14, v151
	v_add_f32_e32 v14, v14, v168
	v_add_f32_e32 v14, v14, v169
	v_add_f32_e32 v14, v14, v170
	s_waitcnt lgkmcnt(5)
	v_mfma_f32_32x32x16_bf16 v[16:31], v[74:77], v[70:73], v[16:31]
	v_add_f32_e32 v14, v14, v147
	v_add_f32_e32 v14, v14, v148
	v_add_f32_e32 v14, v14, v149
	v_add_f32_e32 v14, v14, v150
	s_waitcnt lgkmcnt(4)
	v_mfma_f32_32x32x16_bf16 v[32:47], v[84:87], v[70:73], v[32:47]
	v_cvt_pk_bf16_f32 v64, v135, v136
	v_cvt_pk_bf16_f32 v65, v137, v138
	v_cvt_pk_bf16_f32 v66, v128, v129
	v_cvt_pk_bf16_f32 v67, v130, v131
	v_add_f32_e32 v14, v14, v141
	v_add_f32_e32 v14, v14, v142
	v_add_f32_e32 v14, v14, v143
	v_add_f32_e32 v14, v14, v144
	s_waitcnt lgkmcnt(3)
	v_mfma_f32_32x32x16_bf16 v[16:31], v[88:91], v[64:67], v[16:31]
	v_add_f32_e32 v14, v14, v135
	v_add_f32_e32 v14, v14, v136
	v_add_f32_e32 v14, v14, v137
	v_add_f32_e32 v14, v14, v138
	s_waitcnt lgkmcnt(2)
	v_mfma_f32_32x32x16_bf16 v[32:47], v[92:95], v[64:67], v[32:47]
	v_cvt_pk_bf16_f32 v70, v118, v119
	v_cvt_pk_bf16_f32 v71, v120, v121
	v_cvt_pk_bf16_f32 v72, v122, v123
	v_cvt_pk_bf16_f32 v73, v124, v125
	v_add_f32_e32 v14, v14, v128
	v_add_f32_e32 v14, v14, v129
	v_add_f32_e32 v14, v14, v130
	v_add_f32_e32 v14, v14, v131
	s_waitcnt lgkmcnt(1)
	v_mfma_f32_32x32x16_bf16 v[16:31], v[176:179], v[70:73], v[16:31]
	v_add_f32_e32 v14, v14, v118
	v_add_f32_e32 v14, v14, v119
	v_add_f32_e32 v14, v14, v120
	v_add_f32_e32 v14, v14, v121
	s_waitcnt lgkmcnt(0)
	v_mfma_f32_32x32x16_bf16 v[32:47], v[204:207], v[70:73], v[32:47]
	v_add_f32_e32 v14, v14, v122
	v_add_f32_e32 v14, v14, v123
	v_add_f32_e32 v14, v14, v124
	v_add_f32_e32 v14, v14, v125
	s_setprio 0
	ds_read_b128 v[122:125], v201 offset:27680
	ds_read_b128 v[174:177], v201 offset:32288
	ds_read_b128 v[178:181], v201 offset:27712
	ds_read_b128 v[204:207], v201 offset:32320
	ds_read_b128 v[208:211], v201 offset:27744
	ds_read_b128 v[212:215], v201 offset:32352
	v_cmp_lt_u32_e32 vcc, s53, v68
	s_cmp_lg_u32 s25, 4
	s_cselect_b32 s23, s24, 0
	v_cndmask_b32_e32 v131, v233, v79, vcc
	s_waitcnt lgkmcnt(6)
	v_mfma_f32_32x32x16_bf16 v[64:79], v[240:243], v[164:167], v[48:63]
	v_exp_f32_e32 v169, v101
	v_exp_f32_e32 v170, v80
	v_exp_f32_e32 v171, v81
	v_exp_f32_e32 v172, v82
	v_mfma_f32_32x32x16_bf16 v[80:95], v[244:247], v[164:167], v[48:63]
	v_exp_f32_e32 v147, v106
	v_exp_f32_e32 v148, v108
	v_exp_f32_e32 v149, v110
	v_exp_f32_e32 v150, v112
	s_waitcnt lgkmcnt(5)
	v_mfma_f32_32x32x16_bf16 v[64:79], v[122:125], v[160:163], v[64:79]
	v_exp_f32_e32 v138, v114
	v_exp_f32_e32 v141, v116
	v_exp_f32_e32 v142, v126
	v_exp_f32_e32 v143, v132
	s_waitcnt lgkmcnt(4)
	v_mfma_f32_32x32x16_bf16 v[80:95], v[174:177], v[160:163], v[80:95]
	v_exp_f32_e32 v128, v134
	v_exp_f32_e32 v129, v140
	v_exp_f32_e32 v130, v146
	v_exp_f32_e32 v135, v131
	s_waitcnt lgkmcnt(3)
	v_mfma_f32_32x32x16_bf16 v[64:79], v[178:181], v[156:159], v[64:79]
	v_exp_f32_e32 v122, v15
	v_exp_f32_e32 v123, v100
	v_exp_f32_e32 v124, v102
	v_exp_f32_e32 v125, v103
	s_waitcnt lgkmcnt(2)
	v_mfma_f32_32x32x16_bf16 v[80:95], v[204:207], v[156:159], v[80:95]
	v_exp_f32_e32 v118, v104
	v_exp_f32_e32 v119, v105
	v_exp_f32_e32 v120, v107
	v_exp_f32_e32 v121, v109
	s_waitcnt lgkmcnt(1)
	v_mfma_f32_32x32x16_bf16 v[64:79], v[208:211], v[152:155], v[64:79]
	v_exp_f32_e32 v107, v111
	v_exp_f32_e32 v108, v113
	v_exp_f32_e32 v109, v115
	v_exp_f32_e32 v110, v117
	s_waitcnt lgkmcnt(0)
	v_mfma_f32_32x32x16_bf16 v[80:95], v[212:215], v[152:155], v[80:95]
	v_exp_f32_e32 v111, v127
	v_exp_f32_e32 v113, v133
	v_exp_f32_e32 v114, v139
	v_exp_f32_e32 v115, v145
	s_add_i32 s2, s2, s18
	s_cmp_gt_i32 s23, 2
	v_lshl_add_u32 v127, s2, 6, v184
	s_cselect_b32 s2, -3, 2
	s_add_i32 s2, s2, s23
	s_mulk_i32 s2, 0x2400
	s_nop 7
	s_nop 3
	s_waitcnt vmcnt(3)
	ds_write_b128 v203, v[2:5] offset:9216
	v_add_u32_e32 v2, s2, v203
	s_add_i32 s2, s23, 1
	s_cmp_lg_u32 s23, 4
	s_cselect_b32 s2, s2, 0
	s_add_i32 s23, s45, 10
	s_min_i32 s23, s23, s92
	s_cmp_gt_i32 s23, 3
	s_cselect_b32 s24, s13, 0
	s_add_i32 s24, s24, s23
	s_ashr_i32 s25, s24, 31
	s_lshl_b32 s22, s22, 6
	s_lshl_b64 s[34:35], s[24:25], 13
	s_ashr_i32 s23, s22, 31
	s_waitcnt vmcnt(2)
	ds_write_b128 v2, v[6:9] offset:36864
	v_lshl_add_u64 v[2:3], v[198:199], 0, s[34:35]
	v_lshl_add_u64 v[6:7], s[22:23], 1, v[196:197]
	global_load_dwordx4 v[2:5], v[2:3], off
	v_add_u32_e32 v15, 0xffffff7f, v127
	global_load_dwordx4 v[6:9], v[6:7], off
	v_cmp_lt_u32_e32 vcc, s53, v15
	v_add_u32_e32 v15, 0xffffff9f, v127
	s_mul_i32 s22, s2, 0x2400
	v_cndmask_b32_e32 v101, v233, v64, vcc
	v_cmp_lt_u32_e32 vcc, s53, v15
	v_add_u32_e32 v64, 0xffffff80, v127
	s_add_i32 s23, s22, 0xffffdc00
	v_cndmask_b32_e32 v15, v233, v80, vcc
	v_cmp_lt_u32_e32 vcc, s53, v64
	v_add_u32_e32 v64, 0xffffffa0, v127
	s_cmp_lg_u32 s2, 0
	v_cndmask_b32_e32 v80, v233, v65, vcc
	v_cmp_lt_u32_e32 vcc, s53, v64
	v_add_u32_e32 v64, 0xffffff81, v127
	v_add_u32_e32 v65, 0xffffffba, v127
	v_cndmask_b32_e32 v100, v233, v81, vcc
	v_cmp_lt_u32_e32 vcc, s53, v64
	v_add_u32_e32 v64, 0xffffffa1, v127
	s_cselect_b32 s23, s23, 0x9000
	v_cndmask_b32_e32 v81, v233, v66, vcc
	v_cmp_lt_u32_e32 vcc, s53, v64
	v_add_u32_e32 v64, 0xffffff82, v127
	s_nop 0
	v_cndmask_b32_e32 v102, v233, v82, vcc
	v_cmp_lt_u32_e32 vcc, s53, v64
	v_add_u32_e32 v64, 0xffffffa2, v127
	s_nop 0
	v_cndmask_b32_e32 v82, v233, v67, vcc
	v_cmp_lt_u32_e32 vcc, s53, v64
	v_add_u32_e32 v64, 0xffffff87, v127
	s_nop 0
	v_cndmask_b32_e32 v103, v233, v83, vcc
	v_cmp_lt_u32_e32 vcc, s53, v64
	v_add_u32_e32 v64, 0xffffffa7, v127
	v_add_u32_e32 v83, s23, v201
	v_cndmask_b32_e32 v106, v233, v68, vcc
	v_cmp_lt_u32_e32 vcc, s53, v64
	v_add_u32_e32 v64, 0xffffff88, v127
	s_nop 0
	v_cndmask_b32_e32 v104, v233, v84, vcc
	v_cmp_lt_u32_e32 vcc, s53, v64
	v_add_u32_e32 v64, 0xffffffa8, v127
	s_nop 0
	v_cndmask_b32_e32 v116, v233, v69, vcc
	v_cmp_lt_u32_e32 vcc, s53, v64
	v_add_u32_e32 v64, 0xffffff89, v127
	s_nop 0
	v_cndmask_b32_e32 v105, v233, v85, vcc
	v_cmp_lt_u32_e32 vcc, s53, v64
	v_add_u32_e32 v64, 0xffffffa9, v127
	s_nop 0
	v_cndmask_b32_e32 v117, v233, v70, vcc
	v_cmp_lt_u32_e32 vcc, s53, v64
	v_add_u32_e32 v64, 0xffffff8a, v127
	s_nop 0
	v_cndmask_b32_e32 v112, v233, v86, vcc
	v_cmp_lt_u32_e32 vcc, s53, v64
	v_add_u32_e32 v64, 0xffffffaa, v127
	s_nop 0
	v_cndmask_b32_e32 v126, v233, v71, vcc
	v_cmp_lt_u32_e32 vcc, s53, v64
	v_add_u32_e32 v64, 0xffffff8f, v127
	s_nop 0
	v_cndmask_b32_e32 v131, v233, v87, vcc
	v_cmp_lt_u32_e32 vcc, s53, v64
	v_add_u32_e32 v64, 0xffffffaf, v127
	s_nop 0
	v_cndmask_b32_e32 v134, v233, v72, vcc
	v_cmp_lt_u32_e32 vcc, s53, v64
	v_add_u32_e32 v64, 0xffffff90, v127
	s_nop 0
	v_cndmask_b32_e32 v132, v233, v88, vcc
	v_cmp_lt_u32_e32 vcc, s53, v64
	v_add_u32_e32 v64, 0xffffffb0, v127
	s_nop 0
	v_cndmask_b32_e32 v137, v233, v73, vcc
	v_cmp_lt_u32_e32 vcc, s53, v64
	v_add_u32_e32 v64, 0xffffff91, v127
	s_nop 0
	v_cndmask_b32_e32 v133, v233, v89, vcc
	v_cmp_lt_u32_e32 vcc, s53, v64
	v_add_u32_e32 v64, 0xffffffb1, v127
	s_nop 0
	v_cndmask_b32_e32 v140, v233, v74, vcc
	v_cmp_lt_u32_e32 vcc, s53, v64
	v_add_u32_e32 v64, 0xffffff92, v127
	s_nop 0
	v_cndmask_b32_e32 v136, v233, v90, vcc
	v_cmp_lt_u32_e32 vcc, s53, v64
	v_add_u32_e32 v64, 0xffffffb2, v127
	s_nop 0
	v_cndmask_b32_e32 v145, v233, v75, vcc
	v_cmp_lt_u32_e32 vcc, s53, v64
	v_add_u32_e32 v64, 0xffffff97, v127
	s_nop 0
	v_cndmask_b32_e32 v139, v233, v91, vcc
	v_cmp_lt_u32_e32 vcc, s53, v64
	v_add_u32_e32 v64, 0xffffffb7, v127
	s_nop 0
	v_cndmask_b32_e32 v151, v233, v76, vcc
	v_cmp_lt_u32_e32 vcc, s53, v64
	v_add_u32_e32 v64, 0xffffff98, v127
	s_nop 0
	v_cndmask_b32_e32 v144, v233, v92, vcc
	v_cmp_lt_u32_e32 vcc, s53, v64
	v_add_u32_e32 v64, 0xffffffb8, v127
	s_nop 0
	v_cndmask_b32_e32 v173, v233, v77, vcc
	v_cmp_lt_u32_e32 vcc, s53, v64
	v_add_u32_e32 v64, 0xffffff99, v127
	s_nop 0
	v_cndmask_b32_e32 v146, v233, v93, vcc
	v_cmp_lt_u32_e32 vcc, s53, v64
	v_add_u32_e32 v64, 0xffffffb9, v127
	s_nop 0
	v_cndmask_b32_e32 v175, v233, v78, vcc
	v_cmp_lt_u32_e32 vcc, s53, v64
	v_add_u32_e32 v64, 0xffffff9a, v127
	s_nop 0
	v_cndmask_b32_e32 v168, v233, v94, vcc
	v_cmp_lt_u32_e32 vcc, s53, v65
	s_nop 1
	v_cndmask_b32_e32 v174, v233, v95, vcc
	v_cmp_lt_u32_e32 vcc, s53, v64
	s_nop 1
	v_cndmask_b32_e32 v180, v233, v79, vcc
	ds_read_b128 v[64:67], v83 offset:41472
	ds_read_b128 v[68:71], v83 offset:36864
	ds_read_b128 v[72:75], v83 offset:36896
	ds_read_b128 v[76:79], v83 offset:41504
	ds_read_b128 v[84:87], v83 offset:36928
	ds_read_b128 v[88:91], v83 offset:41536
	ds_read_b128 v[92:95], v83 offset:36960
	ds_read_b128 v[176:179], v83 offset:41568
	s_setprio 3
	v_cvt_pk_bf16_f32 v204, v169, v170
	v_cvt_pk_bf16_f32 v205, v171, v172
	v_cvt_pk_bf16_f32 v206, v147, v148
	v_cvt_pk_bf16_f32 v207, v149, v150
	s_waitcnt lgkmcnt(6)
	s_nop 0
	v_mfma_f32_32x32x16_bf16 v[16:31], v[68:71], v[204:207], v[16:31]
	v_add_f32_e32 v230, v169, v170
	v_add_f32_e32 v230, v230, v171
	v_add_f32_e32 v230, v230, v172
	s_nop 0
	v_mfma_f32_32x32x16_bf16 v[32:47], v[64:67], v[204:207], v[32:47]
	v_cvt_pk_bf16_f32 v68, v138, v141
	v_cvt_pk_bf16_f32 v69, v142, v143
	v_cvt_pk_bf16_f32 v70, v128, v129
	v_cvt_pk_bf16_f32 v71, v130, v135
	v_add_f32_e32 v230, v230, v147
	v_add_f32_e32 v230, v230, v148
	v_add_f32_e32 v230, v230, v149
	v_add_f32_e32 v230, v230, v150
	s_waitcnt lgkmcnt(5)
	v_mfma_f32_32x32x16_bf16 v[16:31], v[72:75], v[68:71], v[16:31]
	v_add_f32_e32 v230, v230, v138
	v_add_f32_e32 v230, v230, v141
	v_add_f32_e32 v230, v230, v142
	v_add_f32_e32 v230, v230, v143
	s_waitcnt lgkmcnt(4)
	v_mfma_f32_32x32x16_bf16 v[32:47], v[76:79], v[68:71], v[32:47]
	v_cvt_pk_bf16_f32 v64, v122, v123
	v_cvt_pk_bf16_f32 v65, v124, v125
	v_cvt_pk_bf16_f32 v66, v118, v119
	v_cvt_pk_bf16_f32 v67, v120, v121
	v_add_f32_e32 v230, v230, v128
	v_add_f32_e32 v230, v230, v129
	v_add_f32_e32 v230, v230, v130
	v_add_f32_e32 v230, v230, v135
	s_waitcnt lgkmcnt(3)
	v_mfma_f32_32x32x16_bf16 v[16:31], v[84:87], v[64:67], v[16:31]
	v_add_f32_e32 v230, v230, v122
	v_add_f32_e32 v230, v230, v123
	v_add_f32_e32 v230, v230, v124
	v_add_f32_e32 v230, v230, v125
	s_waitcnt lgkmcnt(2)
	v_mfma_f32_32x32x16_bf16 v[32:47], v[88:91], v[64:67], v[32:47]
	v_cvt_pk_bf16_f32 v68, v107, v108
	v_cvt_pk_bf16_f32 v69, v109, v110
	v_cvt_pk_bf16_f32 v70, v111, v113
	v_cvt_pk_bf16_f32 v71, v114, v115
	v_add_f32_e32 v230, v230, v118
	v_add_f32_e32 v230, v230, v119
	v_add_f32_e32 v230, v230, v120
	v_add_f32_e32 v230, v230, v121
	s_waitcnt lgkmcnt(1)
	v_mfma_f32_32x32x16_bf16 v[16:31], v[92:95], v[68:71], v[16:31]
	v_add_f32_e32 v230, v230, v107
	v_add_f32_e32 v230, v230, v108
	v_add_f32_e32 v230, v230, v109
	v_add_f32_e32 v230, v230, v110
	s_waitcnt lgkmcnt(0)
	v_mfma_f32_32x32x16_bf16 v[32:47], v[176:179], v[68:71], v[32:47]
	v_add_f32_e32 v230, v230, v111
	v_add_f32_e32 v230, v230, v113
	v_add_f32_e32 v230, v230, v114
	v_add_f32_e32 v230, v230, v115
	s_setprio 2
	s_waitcnt lgkmcnt(0)
	s_barrier
	ds_read_b128 v[240:243], v201
	ds_read_b128 v[244:247], v201 offset:4608
	ds_read_b128 v[118:121], v201 offset:32
	ds_read_b128 v[176:179], v201 offset:4640
	ds_read_b128 v[206:209], v201 offset:64
	ds_read_b128 v[210:213], v201 offset:4672
	ds_read_b128 v[214:217], v201 offset:96
	ds_read_b128 v[218:221], v201 offset:4704
	v_add_f32_e32 v169, v1, v14
	s_waitcnt lgkmcnt(6)
	v_mfma_f32_32x32x16_bf16 v[64:79], v[240:243], v[164:167], v[48:63]
	v_exp_f32_e32 v185, v101
	v_exp_f32_e32 v186, v80
	v_exp_f32_e32 v187, v81
	v_exp_f32_e32 v204, v82
	v_mfma_f32_32x32x16_bf16 v[80:95], v[244:247], v[164:167], v[48:63]
	v_exp_f32_e32 v127, v106
	v_exp_f32_e32 v128, v116
	v_exp_f32_e32 v129, v117
	v_exp_f32_e32 v130, v126
	s_waitcnt lgkmcnt(5)
	v_mfma_f32_32x32x16_bf16 v[64:79], v[118:121], v[160:163], v[64:79]
	v_exp_f32_e32 v123, v134
	v_exp_f32_e32 v124, v137
	v_exp_f32_e32 v125, v140
	v_exp_f32_e32 v126, v145
	s_waitcnt lgkmcnt(4)
	v_mfma_f32_32x32x16_bf16 v[80:95], v[176:179], v[160:163], v[80:95]
	v_exp_f32_e32 v119, v151
	v_exp_f32_e32 v120, v173
	v_exp_f32_e32 v121, v175
	v_exp_f32_e32 v122, v180
	s_waitcnt lgkmcnt(3)
	v_mfma_f32_32x32x16_bf16 v[64:79], v[206:209], v[156:159], v[64:79]
	v_exp_f32_e32 v111, v15
	v_exp_f32_e32 v116, v100
	v_exp_f32_e32 v117, v102
	v_exp_f32_e32 v118, v103
	s_waitcnt lgkmcnt(2)
	v_mfma_f32_32x32x16_bf16 v[80:95], v[210:213], v[156:159], v[80:95]
	v_exp_f32_e32 v107, v104
	v_exp_f32_e32 v108, v105
	v_exp_f32_e32 v109, v112
	v_exp_f32_e32 v110, v131
	s_waitcnt lgkmcnt(1)
	v_mfma_f32_32x32x16_bf16 v[64:79], v[214:217], v[152:155], v[64:79]
	v_exp_f32_e32 v103, v132
	v_exp_f32_e32 v104, v133
	v_exp_f32_e32 v105, v136
	v_exp_f32_e32 v106, v139
	s_waitcnt lgkmcnt(0)
	v_mfma_f32_32x32x16_bf16 v[80:95], v[218:221], v[152:155], v[80:95]
	v_exp_f32_e32 v1, v144
	v_exp_f32_e32 v100, v146
	v_exp_f32_e32 v101, v168
	v_exp_f32_e32 v102, v174
	v_lshl_add_u32 v131, s27, 6, v184
	v_add_u32_e32 v14, 0xffffff7f, v131
	v_cmp_lt_u32_e32 vcc, s53, v14
	v_add_u32_e32 v14, 0xffffff9f, v131
	v_add_u32_e32 v15, 0xffffff80, v131
	v_cndmask_b32_e32 v112, v233, v64, vcc
	v_cmp_lt_u32_e32 vcc, s53, v14
	v_add_u32_e32 v64, 0xffffff81, v131
	s_cmp_gt_i32 s2, 2
	v_cndmask_b32_e32 v14, v233, v80, vcc
	v_cmp_lt_u32_e32 vcc, s53, v15
	v_add_u32_e32 v15, 0xffffffa0, v131
	s_cselect_b32 s23, -3, 2
	v_cndmask_b32_e32 v113, v233, v65, vcc
	v_cmp_lt_u32_e32 vcc, s53, v15
	s_add_i32 s23, s23, s2
	v_add_u32_e32 v65, 0xffffffba, v131
	v_cndmask_b32_e32 v15, v233, v81, vcc
	v_cmp_lt_u32_e32 vcc, s53, v64
	v_add_u32_e32 v64, 0xffffffa1, v131
	s_mulk_i32 s23, 0x2400
	v_cndmask_b32_e32 v114, v233, v66, vcc
	v_cmp_lt_u32_e32 vcc, s53, v64
	v_add_u32_e32 v64, 0xffffff82, v131
	s_nop 7
	s_nop 3
	s_waitcnt vmcnt(3)
	ds_write_b128 v203, v[96:99] offset:18432
	v_cndmask_b32_e32 v132, v233, v82, vcc
	v_cmp_lt_u32_e32 vcc, s53, v64
	v_add_u32_e32 v64, 0xffffffa2, v131
	v_add_f32_e32 v96, v169, v230
	v_cndmask_b32_e32 v115, v233, v67, vcc
	v_cmp_lt_u32_e32 vcc, s53, v64
	v_add_u32_e32 v64, 0xffffff87, v131
	s_nop 0
	v_cndmask_b32_e32 v133, v233, v83, vcc
	v_cmp_lt_u32_e32 vcc, s53, v64
	v_add_u32_e32 v64, 0xffffffa7, v131
	s_nop 0
	v_cndmask_b32_e32 v140, v233, v68, vcc
	v_cmp_lt_u32_e32 vcc, s53, v64
	v_add_u32_e32 v64, 0xffffff88, v131
	s_nop 0
	v_cndmask_b32_e32 v134, v233, v84, vcc
	v_cmp_lt_u32_e32 vcc, s53, v64
	v_add_u32_e32 v64, 0xffffffa8, v131
	s_nop 0
	v_cndmask_b32_e32 v141, v233, v69, vcc
	v_cmp_lt_u32_e32 vcc, s53, v64
	v_add_u32_e32 v64, 0xffffff89, v131
	s_nop 0
	v_cndmask_b32_e32 v135, v233, v85, vcc
	v_cmp_lt_u32_e32 vcc, s53, v64
	v_add_u32_e32 v64, 0xffffffa9, v131
	s_nop 0
	v_cndmask_b32_e32 v146, v233, v70, vcc
	v_cmp_lt_u32_e32 vcc, s53, v64
	v_add_u32_e32 v64, 0xffffff8a, v131
	s_nop 0
	v_cndmask_b32_e32 v136, v233, v86, vcc
	v_cmp_lt_u32_e32 vcc, s53, v64
	v_add_u32_e32 v64, 0xffffffaa, v131
	s_nop 0
	v_cndmask_b32_e32 v147, v233, v71, vcc
	v_cmp_lt_u32_e32 vcc, s53, v64
	v_add_u32_e32 v64, 0xffffff8f, v131
	s_nop 0
	v_cndmask_b32_e32 v137, v233, v87, vcc
	v_cmp_lt_u32_e32 vcc, s53, v64
	v_add_u32_e32 v64, 0xffffffaf, v131
	s_nop 0
	v_cndmask_b32_e32 v148, v233, v72, vcc
	v_cmp_lt_u32_e32 vcc, s53, v64
	v_add_u32_e32 v64, 0xffffff90, v131
	s_nop 0
	v_cndmask_b32_e32 v138, v233, v88, vcc
	v_cmp_lt_u32_e32 vcc, s53, v64
	v_add_u32_e32 v64, 0xffffffb0, v131
	v_add_u32_e32 v88, s22, v201
	v_cndmask_b32_e32 v149, v233, v73, vcc
	v_cmp_lt_u32_e32 vcc, s53, v64
	v_add_u32_e32 v64, 0xffffff91, v131
	s_add_i32 s22, s45, 11
	v_cndmask_b32_e32 v139, v233, v89, vcc
	v_cmp_lt_u32_e32 vcc, s53, v64
	v_add_u32_e32 v64, 0xffffffb1, v131
	s_min_i32 s22, s22, s92
	v_cndmask_b32_e32 v176, v233, v74, vcc
	v_cmp_lt_u32_e32 vcc, s53, v64
	v_add_u32_e32 v64, 0xffffff92, v131
	s_cmp_gt_i32 s22, 3
	v_cndmask_b32_e32 v142, v233, v90, vcc
	v_cmp_lt_u32_e32 vcc, s53, v64
	v_add_u32_e32 v64, 0xffffffb2, v131
	s_nop 0
	v_cndmask_b32_e32 v177, v233, v75, vcc
	v_cmp_lt_u32_e32 vcc, s53, v64
	v_add_u32_e32 v64, 0xffffff97, v131
	s_nop 0
	v_cndmask_b32_e32 v143, v233, v91, vcc
	v_cmp_lt_u32_e32 vcc, s53, v64
	v_add_u32_e32 v64, 0xffffffb7, v131
	s_nop 0
	v_cndmask_b32_e32 v178, v233, v76, vcc
	v_cmp_lt_u32_e32 vcc, s53, v64
	v_add_u32_e32 v64, 0xffffff98, v131
	s_nop 0
	v_cndmask_b32_e32 v144, v233, v92, vcc
	v_cmp_lt_u32_e32 vcc, s53, v64
	v_add_u32_e32 v64, 0xffffffb8, v131
	s_nop 0
	v_cndmask_b32_e32 v179, v233, v77, vcc
	v_cmp_lt_u32_e32 vcc, s53, v64
	v_add_u32_e32 v64, 0xffffff99, v131
	s_nop 0
	v_cndmask_b32_e32 v145, v233, v93, vcc
	v_cmp_lt_u32_e32 vcc, s53, v64
	v_add_u32_e32 v64, 0xffffffb9, v131
	s_nop 0
	v_cndmask_b32_e32 v180, v233, v78, vcc
	v_cmp_lt_u32_e32 vcc, s53, v64
	v_add_u32_e32 v64, 0xffffff9a, v131
	s_nop 0
	v_cndmask_b32_e32 v150, v233, v94, vcc
	v_cmp_lt_u32_e32 vcc, s53, v65
	v_add_u32_e32 v65, s23, v203
	s_cselect_b32 s23, s13, 0
	s_add_i32 s22, s23, s22
	s_ashr_i32 s23, s22, 31
	s_lshl_b64 s[22:23], s[22:23], 13
	s_waitcnt vmcnt(2)
	ds_write_b128 v65, v[10:13] offset:36864
	v_lshl_add_u64 v[10:11], v[198:199], 0, s[22:23]
	s_lshl_b32 s22, s24, 6
	s_ashr_i32 s23, s22, 31
	global_load_dwordx4 v[168:171], v[10:11], off
	v_lshl_add_u64 v[10:11], s[22:23], 1, v[196:197]
	global_load_dwordx4 v[172:175], v[10:11], off
	v_cndmask_b32_e32 v151, v233, v95, vcc
	v_cmp_lt_u32_e32 vcc, s53, v64
	s_nop 1
	v_cndmask_b32_e32 v181, v233, v79, vcc
	ds_read_b128 v[240:243], v201 offset:9216
	ds_read_b128 v[244:247], v201 offset:13824
	ds_read_b128 v[10:13], v88 offset:41472
	ds_read_b128 v[64:67], v88 offset:36864
	ds_read_b128 v[68:71], v88 offset:36896
	ds_read_b128 v[72:75], v88 offset:41504
	ds_read_b128 v[76:79], v88 offset:36928
	ds_read_b128 v[80:83], v88 offset:41536
	ds_read_b128 v[84:87], v88 offset:36960
	ds_read_b128 v[88:91], v88 offset:41568
	s_setprio 1
	v_mov_b32_e32 v98, v112
	v_cvt_pk_bf16_f32 v92, v185, v186
	v_cvt_pk_bf16_f32 v93, v187, v204
	v_cvt_pk_bf16_f32 v94, v127, v128
	v_cvt_pk_bf16_f32 v95, v129, v130
	s_waitcnt lgkmcnt(6)
	s_nop 0
	v_mfma_f32_32x32x16_bf16 v[16:31], v[64:67], v[92:95], v[16:31]
	v_max3_f32 v98, v98, v113, v114
	v_max3_f32 v98, v98, v115, v140
	v_add_f32_e32 v97, v185, v186
	v_add_f32_e32 v97, v97, v187
	v_add_f32_e32 v97, v97, v204
	s_nop 0
	v_mfma_f32_32x32x16_bf16 v[32:47], v[10:13], v[92:95], v[32:47]
	v_cvt_pk_bf16_f32 v64, v123, v124
	v_cvt_pk_bf16_f32 v65, v125, v126
	v_cvt_pk_bf16_f32 v66, v119, v120
	v_cvt_pk_bf16_f32 v67, v121, v122
	v_max3_f32 v98, v98, v141, v146
	v_max3_f32 v98, v98, v147, v148
	v_add_f32_e32 v97, v97, v127
	v_add_f32_e32 v97, v97, v128
	v_add_f32_e32 v97, v97, v129
	v_add_f32_e32 v97, v97, v130
	s_waitcnt lgkmcnt(5)
	v_mfma_f32_32x32x16_bf16 v[16:31], v[68:71], v[64:67], v[16:31]
	v_max3_f32 v98, v98, v149, v176
	v_max3_f32 v98, v98, v177, v178
	v_add_f32_e32 v97, v97, v123
	v_add_f32_e32 v97, v97, v124
	v_add_f32_e32 v97, v97, v125
	v_add_f32_e32 v97, v97, v126
	s_waitcnt lgkmcnt(4)
	v_mfma_f32_32x32x16_bf16 v[32:47], v[72:75], v[64:67], v[32:47]
	v_cvt_pk_bf16_f32 v10, v111, v116
	v_cvt_pk_bf16_f32 v11, v117, v118
	v_cvt_pk_bf16_f32 v12, v107, v108
	v_cvt_pk_bf16_f32 v13, v109, v110
	v_max3_f32 v98, v98, v179, v180
	v_max3_f32 v98, v98, v181, v14
	v_add_f32_e32 v97, v97, v119
	v_add_f32_e32 v97, v97, v120
	v_add_f32_e32 v97, v97, v121
	v_add_f32_e32 v97, v97, v122
	s_waitcnt lgkmcnt(3)
	v_mfma_f32_32x32x16_bf16 v[16:31], v[76:79], v[10:13], v[16:31]
	v_max3_f32 v98, v98, v15, v132
	v_max3_f32 v98, v98, v133, v134
	v_add_f32_e32 v97, v97, v111
	v_add_f32_e32 v97, v97, v116
	v_add_f32_e32 v97, v97, v117
	v_add_f32_e32 v97, v97, v118
	s_waitcnt lgkmcnt(2)
	v_mfma_f32_32x32x16_bf16 v[32:47], v[80:83], v[10:13], v[32:47]
	v_cvt_pk_bf16_f32 v64, v103, v104
	v_cvt_pk_bf16_f32 v65, v105, v106
	v_cvt_pk_bf16_f32 v66, v1, v100
	v_cvt_pk_bf16_f32 v67, v101, v102
	v_max3_f32 v98, v98, v135, v136
	v_max3_f32 v98, v98, v137, v138
	v_add_f32_e32 v97, v97, v107
	v_add_f32_e32 v97, v97, v108
	v_add_f32_e32 v97, v97, v109
	v_add_f32_e32 v97, v97, v110
	s_waitcnt lgkmcnt(1)
	v_mfma_f32_32x32x16_bf16 v[16:31], v[84:87], v[64:67], v[16:31]
	v_max3_f32 v98, v98, v139, v142
	v_max3_f32 v98, v98, v143, v144
	v_add_f32_e32 v97, v97, v103
	v_add_f32_e32 v97, v97, v104
	v_add_f32_e32 v97, v97, v105
	v_add_f32_e32 v97, v97, v106
	s_waitcnt lgkmcnt(0)
	v_mfma_f32_32x32x16_bf16 v[32:47], v[88:91], v[64:67], v[32:47]
	v_max3_f32 v98, v98, v145, v150
	v_max3_f32 v98, v98, v151, v151
	v_add_f32_e32 v97, v97, v1
	v_add_f32_e32 v97, v97, v100
	v_add_f32_e32 v97, v97, v101
	v_add_f32_e32 v97, v97, v102
	s_setprio 0
	ds_read_b128 v[124:127], v201 offset:9248
	ds_read_b128 v[120:123], v201 offset:13856
	ds_read_b128 v[74:77], v201 offset:9280
	ds_read_b128 v[66:69], v201 offset:9312
	ds_read_b128 v[70:73], v201 offset:13888
	ds_read_b128 v[10:13], v201 offset:13920
	v_add_f32_e32 v64, v96, v97
	v_mov_b32_e32 v1, v98
	s_nop 1
	v_permlane32_swap_b32_e32 v98, v1
	v_max_f32_e32 v1, v1, v1
	v_max_f32_e32 v65, v98, v98
	v_max_f32_e32 v1, v65, v1
	v_cmp_lt_f32_e32 vcc, s52, v1
	s_cbranch_vccz .LBB0_703
	v_max_f32_e32 v1, v1, v1
	v_max_f32_e32 v82, 0, v1
	v_add_f32_e32 v195, v195, v82
	v_xor_b32_e32 v48, 0x80000000, v195
	v_pk_add_f32 v[112:113], v[112:113], v[82:83] op_sel_hi:[1,0] neg_lo:[0,1] neg_hi:[0,1]
	v_pk_add_f32 v[14:15], v[14:15], v[82:83] op_sel_hi:[1,0] neg_lo:[0,1] neg_hi:[0,1]
	v_pk_add_f32 v[114:115], v[114:115], v[82:83] op_sel_hi:[1,0] neg_lo:[0,1] neg_hi:[0,1]
	v_pk_add_f32 v[132:133], v[132:133], v[82:83] op_sel_hi:[1,0] neg_lo:[0,1] neg_hi:[0,1]
	v_pk_add_f32 v[140:141], v[140:141], v[82:83] op_sel_hi:[1,0] neg_lo:[0,1] neg_hi:[0,1]
	v_pk_add_f32 v[134:135], v[134:135], v[82:83] op_sel_hi:[1,0] neg_lo:[0,1] neg_hi:[0,1]
	v_pk_add_f32 v[146:147], v[146:147], v[82:83] op_sel_hi:[1,0] neg_lo:[0,1] neg_hi:[0,1]
	v_pk_add_f32 v[136:137], v[136:137], v[82:83] op_sel_hi:[1,0] neg_lo:[0,1] neg_hi:[0,1]
	v_pk_add_f32 v[148:149], v[148:149], v[82:83] op_sel_hi:[1,0] neg_lo:[0,1] neg_hi:[0,1]
	v_pk_add_f32 v[138:139], v[138:139], v[82:83] op_sel_hi:[1,0] neg_lo:[0,1] neg_hi:[0,1]
	v_pk_add_f32 v[176:177], v[176:177], v[82:83] op_sel_hi:[1,0] neg_lo:[0,1] neg_hi:[0,1]
	v_pk_add_f32 v[142:143], v[142:143], v[82:83] op_sel_hi:[1,0] neg_lo:[0,1] neg_hi:[0,1]
	v_pk_add_f32 v[178:179], v[178:179], v[82:83] op_sel_hi:[1,0] neg_lo:[0,1] neg_hi:[0,1]
	v_pk_add_f32 v[144:145], v[144:145], v[82:83] op_sel_hi:[1,0] neg_lo:[0,1] neg_hi:[0,1]
	v_pk_add_f32 v[180:181], v[180:181], v[82:83] op_sel_hi:[1,0] neg_lo:[0,1] neg_hi:[0,1]
	v_pk_add_f32 v[150:151], v[150:151], v[82:83] op_sel_hi:[1,0] neg_lo:[0,1] neg_hi:[0,1]
	v_exp_f32_e64 v82, -v82
	v_mov_b32_e32 v49, v48
	v_mov_b32_e32 v50, v48
	v_mov_b32_e32 v51, v48
	v_mov_b32_e32 v52, v48
	v_mov_b32_e32 v53, v48
	v_mov_b32_e32 v54, v48
	v_mov_b32_e32 v55, v48
	v_mov_b32_e32 v56, v48
	v_mov_b32_e32 v57, v48
	v_mov_b32_e32 v58, v48
	v_mov_b32_e32 v59, v48
	v_mov_b32_e32 v60, v48
	v_mov_b32_e32 v61, v48
	v_mov_b32_e32 v62, v48
	v_mov_b32_e32 v63, v48
	s_nop 11
	v_pk_mul_f32 v[30:31], v[30:31], v[82:83] op_sel_hi:[1,0]
	v_pk_mul_f32 v[28:29], v[28:29], v[82:83] op_sel_hi:[1,0]
	v_pk_mul_f32 v[26:27], v[26:27], v[82:83] op_sel_hi:[1,0]
	v_pk_mul_f32 v[24:25], v[24:25], v[82:83] op_sel_hi:[1,0]
	v_pk_mul_f32 v[22:23], v[22:23], v[82:83] op_sel_hi:[1,0]
	v_pk_mul_f32 v[20:21], v[20:21], v[82:83] op_sel_hi:[1,0]
	v_pk_mul_f32 v[18:19], v[18:19], v[82:83] op_sel_hi:[1,0]
	v_pk_mul_f32 v[16:17], v[16:17], v[82:83] op_sel_hi:[1,0]
	v_pk_mul_f32 v[46:47], v[46:47], v[82:83] op_sel_hi:[1,0]
	v_pk_mul_f32 v[44:45], v[44:45], v[82:83] op_sel_hi:[1,0]
	v_pk_mul_f32 v[42:43], v[42:43], v[82:83] op_sel_hi:[1,0]
	v_pk_mul_f32 v[40:41], v[40:41], v[82:83] op_sel_hi:[1,0]
	v_pk_mul_f32 v[38:39], v[38:39], v[82:83] op_sel_hi:[1,0]
	v_pk_mul_f32 v[36:37], v[36:37], v[82:83] op_sel_hi:[1,0]
	v_pk_mul_f32 v[34:35], v[34:35], v[82:83] op_sel_hi:[1,0]
	v_pk_mul_f32 v[32:33], v[32:33], v[82:83] op_sel_hi:[1,0]
	v_mul_f32_e32 v64, v64, v82
